# GEMM loops: MFMA order changed so the two K-halves of each accumulator issue back to back (SrcC forwarding), n outer m inner
# speedup vs baseline: 1.0251x; 1.0007x over previous
; #define PG8_STAGE(bufoff, gbase, voff) do { _Pragma("unroll") for (int _i = 0; _i < 2; ++_i) \
;         __builtin_amdgcn_global_load_lds((const unsigned*)((const char*)(gbase) + (voff)[_i]), (PG8_LAS unsigned*)(lds + (bufoff) + ldsw + _i * 8192), 16, 0, 0); } while (0)
; #define PG8_LDA(dst, b, h) do { _Pragma("unroll") for (int m = 0; m < 4; ++m) _Pragma("unroll") for (int k = 0; k < 2; ++k) dst[m][k] = *(const PG8_LAS bf16x8*)(lds + PG8_SA(b, h) + aoff + m * 2048 + k * 1024); } while (0)
; #define PG8_LDB(dst, b, h) do { _Pragma("unroll") for (int n = 0; n < 2; ++n) _Pragma("unroll") for (int k = 0; k < 2; ++k) dst[n][k] = *(const PG8_LAS bf16x8*)(lds + PG8_SB(b, h) + boff + n * 2048 + k * 1024); } while (0)
; #define PG8_MMA(ai, bj, At, Bt) do { __builtin_amdgcn_s_setprio(1); _Pragma("unroll") for (int m = 0; m < 4; ++m) _Pragma("unroll") for (int n = 0; n < 2; ++n) _Pragma("unroll") for (int k = 0; k < 2; ++k) \
;         acc[ai][bj][m][n] = __builtin_amdgcn_mfma_f32_16x16x32_bf16(Bt[n][k], At[m][k], acc[ai][bj][m][n], 0, 0, 0); __builtin_amdgcn_s_setprio(0); } while (0)
; #define PG8_WAIT_V(n) asm volatile("s_waitcnt vmcnt(" #n ")" ::: "memory")
; #define PG8_WAIT_L(n) asm volatile("s_waitcnt lgkmcnt(" #n ")" ::: "memory")
; #define PG8_BAR __builtin_amdgcn_s_barrier()
; #define PG8_SCHED __builtin_amdgcn_sched_barrier(0)
;     ...
;             const bool last = (t == nt - 2);
;             const char* a1 = PG8_KADV(cA, (size_t)(t + 1) * kstep);
;             const char* a2 = last ? nA : PG8_KADV(cA, (size_t)(t + 2) * kstep); const char* b2 = last ? nB : PG8_KADV(cB, (size_t)(t + 2) * kstep);
;             const char* a3 = PG8_KADV(a2, kstep); const char* b3 = PG8_KADV(b2, kstep);
;             if (last && has_next) S.a_ready(nxt);
;             if constexpr (SP2) {
;             PG8_LDB(B0, 0, 0); PG8_LDB(B1, 0, 1); PG8_SCHED; PG8_LDA(At, 0, 0); PG8_STAGE(PG8_SA(1, 1), a1 + hstep, voffA);
;             PG8_WAIT_V(8); PG8_WAIT_L(0); PG8_BAR; PG8_MMA(0, 0, At, B0); PG8_MMA(0, 1, At, B1); PG8_BAR; PG8_SCHED;
;             PG8_LDA(At, 0, 1); PG8_STAGE(PG8_SB(0, 0), b2, voffB); PG8_STAGE(PG8_SB(0, 1), b2 + hstep, voffB); PG8_STAGE(PG8_SA(0, 0), a2, voffA);
;             PG8_WAIT_V(8); PG8_WAIT_L(0); PG8_BAR; PG8_MMA(1, 0, At, B0); PG8_MMA(1, 1, At, B1); PG8_BAR; PG8_SCHED;
.LBB0_230:
	s_add_u32 s12, s80, 0xfff80080
	s_addc_u32 s13, s81, -1
	s_add_i32 s30, 0, 0x10000
	s_cmp_eq_u32 s28, 28
	s_cselect_b32 s85, s15, s13
	s_cselect_b32 s84, s20, s12
	s_cselect_b32 s83, s21, s25
	s_cselect_b32 s82, s22, s23
	s_add_i32 s12, 0, 0x14000
	v_add_u32_e32 v156, s30, v141
	v_add_u32_e32 v168, s12, v141
	ds_read_b128 v[144:147], v156
	ds_read_b128 v[148:151], v156 offset:1024
	ds_read_b128 v[152:155], v156 offset:2048
	ds_read_b128 v[156:159], v156 offset:3072
	ds_read_b128 v[160:163], v168
	ds_read_b128 v[164:167], v168 offset:1024
	ds_read_b128 v[182:185], v168 offset:2048
	ds_read_b128 v[186:189], v168 offset:3072
	s_add_i32 m0, s1, 0xc000
	ds_read_b128 v[190:193], v143
	ds_read_b128 v[194:197], v143 offset:1024
	ds_read_b128 v[198:201], v143 offset:2048
	ds_read_b128 v[202:205], v143 offset:3072
	ds_read_b128 v[206:209], v143 offset:4096
	ds_read_b128 v[210:213], v143 offset:5120
	ds_read_b128 v[214:217], v143 offset:6144
	ds_read_b128 v[218:221], v143 offset:7168
	global_load_lds_dwordx4 v136, s[80:81]
	s_add_i32 m0, s1, 0xe000
	s_nop 0
	global_load_lds_dwordx4 v138, s[80:81]
	s_waitcnt vmcnt(8)
	s_waitcnt lgkmcnt(0)
	s_barrier
	s_setprio 1
	s_waitcnt lgkmcnt(0)
	v_mfma_f32_16x16x32_bf16 v[124:127], v[144:147], v[190:193], v[124:127]
	v_mfma_f32_16x16x32_bf16 v[124:127], v[148:151], v[194:197], v[124:127]
	v_mfma_f32_16x16x32_bf16 v[108:111], v[144:147], v[198:201], v[108:111]
	v_mfma_f32_16x16x32_bf16 v[108:111], v[148:151], v[202:205], v[108:111]
	v_mfma_f32_16x16x32_bf16 v[92:95], v[144:147], v[206:209], v[92:95]
	v_mfma_f32_16x16x32_bf16 v[92:95], v[148:151], v[210:213], v[92:95]
	v_mfma_f32_16x16x32_bf16 v[76:79], v[144:147], v[214:217], v[76:79]
	v_mfma_f32_16x16x32_bf16 v[76:79], v[148:151], v[218:221], v[76:79]
	v_mfma_f32_16x16x32_bf16 v[120:123], v[152:155], v[190:193], v[120:123]
	v_mfma_f32_16x16x32_bf16 v[120:123], v[156:159], v[194:197], v[120:123]
	v_mfma_f32_16x16x32_bf16 v[104:107], v[152:155], v[198:201], v[104:107]
	v_mfma_f32_16x16x32_bf16 v[104:107], v[156:159], v[202:205], v[104:107]
	v_mfma_f32_16x16x32_bf16 v[88:91], v[152:155], v[206:209], v[88:91]
	v_mfma_f32_16x16x32_bf16 v[88:91], v[156:159], v[210:213], v[88:91]
	v_mfma_f32_16x16x32_bf16 v[72:75], v[152:155], v[214:217], v[72:75]
	v_mfma_f32_16x16x32_bf16 v[72:75], v[156:159], v[218:221], v[72:75]
	s_setprio 0
	s_setprio 1
	v_mfma_f32_16x16x32_bf16 v[116:119], v[160:163], v[190:193], v[116:119]
	v_mfma_f32_16x16x32_bf16 v[116:119], v[164:167], v[194:197], v[116:119]
	v_mfma_f32_16x16x32_bf16 v[100:103], v[160:163], v[198:201], v[100:103]
	v_mfma_f32_16x16x32_bf16 v[100:103], v[164:167], v[202:205], v[100:103]
	v_mfma_f32_16x16x32_bf16 v[84:87], v[160:163], v[206:209], v[84:87]
	v_mfma_f32_16x16x32_bf16 v[84:87], v[164:167], v[210:213], v[84:87]
	v_mfma_f32_16x16x32_bf16 v[68:71], v[160:163], v[214:217], v[68:71]
	v_mfma_f32_16x16x32_bf16 v[68:71], v[164:167], v[218:221], v[68:71]
	v_mfma_f32_16x16x32_bf16 v[112:115], v[182:185], v[190:193], v[112:115]
	v_mfma_f32_16x16x32_bf16 v[112:115], v[186:189], v[194:197], v[112:115]
	v_mfma_f32_16x16x32_bf16 v[96:99], v[182:185], v[198:201], v[96:99]
	v_mfma_f32_16x16x32_bf16 v[96:99], v[186:189], v[202:205], v[96:99]
	v_mfma_f32_16x16x32_bf16 v[80:83], v[182:185], v[206:209], v[80:83]
	v_mfma_f32_16x16x32_bf16 v[80:83], v[186:189], v[210:213], v[80:83]
	v_mfma_f32_16x16x32_bf16 v[64:67], v[182:185], v[214:217], v[64:67]
	v_mfma_f32_16x16x32_bf16 v[64:67], v[186:189], v[218:221], v[64:67]
	s_setprio 0
	s_barrier
	s_add_i32 s13, s30, s0
	s_mov_b32 m0, s13
	ds_read_b128 v[190:193], v143 offset:16384
	ds_read_b128 v[194:197], v143 offset:17408
	ds_read_b128 v[198:201], v143 offset:18432
	ds_read_b128 v[202:205], v143 offset:19456
	ds_read_b128 v[206:209], v143 offset:20480
	ds_read_b128 v[210:213], v143 offset:21504
	ds_read_b128 v[214:217], v143 offset:22528
	ds_read_b128 v[218:221], v143 offset:23552
	global_load_lds_dwordx4 v132, s[82:83]
	s_add_i32 m0, s13, 0x2000
	s_add_u32 s42, s82, 0x80000
	s_addc_u32 s43, s83, 0
	s_add_i32 s12, s12, s0
	global_load_lds_dwordx4 v128, s[82:83]
	s_mov_b32 m0, s12
	s_nop 0
	global_load_lds_dwordx4 v132, s[42:43]
	s_add_i32 m0, s12, 0x2000
	s_nop 0
	global_load_lds_dwordx4 v128, s[42:43]
	s_mov_b32 m0, s1
	s_nop 0
	global_load_lds_dwordx4 v134, s[84:85]
	s_mov_b32 m0, s2
	s_nop 0
	global_load_lds_dwordx4 v130, s[84:85]
	s_waitcnt vmcnt(8)
	s_waitcnt lgkmcnt(0)
	s_barrier
	s_setprio 1
	s_waitcnt lgkmcnt(0)
	v_mfma_f32_16x16x32_bf16 v[60:63], v[144:147], v[190:193], v[60:63]
	v_mfma_f32_16x16x32_bf16 v[60:63], v[148:151], v[194:197], v[60:63]
	v_mfma_f32_16x16x32_bf16 v[44:47], v[144:147], v[198:201], v[44:47]
	v_mfma_f32_16x16x32_bf16 v[44:47], v[148:151], v[202:205], v[44:47]
	v_mfma_f32_16x16x32_bf16 v[28:31], v[144:147], v[206:209], v[28:31]
	v_mfma_f32_16x16x32_bf16 v[28:31], v[148:151], v[210:213], v[28:31]
	v_mfma_f32_16x16x32_bf16 v[12:15], v[144:147], v[214:217], v[12:15]
	v_mfma_f32_16x16x32_bf16 v[12:15], v[148:151], v[218:221], v[12:15]
	v_mfma_f32_16x16x32_bf16 v[56:59], v[152:155], v[190:193], v[56:59]
	v_mfma_f32_16x16x32_bf16 v[56:59], v[156:159], v[194:197], v[56:59]
	v_mfma_f32_16x16x32_bf16 v[40:43], v[152:155], v[198:201], v[40:43]
	v_mfma_f32_16x16x32_bf16 v[40:43], v[156:159], v[202:205], v[40:43]
	v_mfma_f32_16x16x32_bf16 v[24:27], v[152:155], v[206:209], v[24:27]
	v_mfma_f32_16x16x32_bf16 v[24:27], v[156:159], v[210:213], v[24:27]
	v_mfma_f32_16x16x32_bf16 v[8:11], v[152:155], v[214:217], v[8:11]
	v_mfma_f32_16x16x32_bf16 v[8:11], v[156:159], v[218:221], v[8:11]
	s_setprio 0
	s_setprio 1
	v_mfma_f32_16x16x32_bf16 v[52:55], v[160:163], v[190:193], v[52:55]
	v_mfma_f32_16x16x32_bf16 v[52:55], v[164:167], v[194:197], v[52:55]
	v_mfma_f32_16x16x32_bf16 v[36:39], v[160:163], v[198:201], v[36:39]
	v_mfma_f32_16x16x32_bf16 v[36:39], v[164:167], v[202:205], v[36:39]
	v_mfma_f32_16x16x32_bf16 v[20:23], v[160:163], v[206:209], v[20:23]
	v_mfma_f32_16x16x32_bf16 v[20:23], v[164:167], v[210:213], v[20:23]
	v_mfma_f32_16x16x32_bf16 v[4:7], v[160:163], v[214:217], v[4:7]
	v_mfma_f32_16x16x32_bf16 v[4:7], v[164:167], v[218:221], v[4:7]
	v_mfma_f32_16x16x32_bf16 v[48:51], v[182:185], v[190:193], v[48:51]
	v_mfma_f32_16x16x32_bf16 v[48:51], v[186:189], v[194:197], v[48:51]
	v_mfma_f32_16x16x32_bf16 v[32:35], v[182:185], v[198:201], v[32:35]
	v_mfma_f32_16x16x32_bf16 v[32:35], v[186:189], v[202:205], v[32:35]
	v_mfma_f32_16x16x32_bf16 v[16:19], v[182:185], v[206:209], v[16:19]
	v_mfma_f32_16x16x32_bf16 v[16:19], v[186:189], v[210:213], v[16:19]
	v_mfma_f32_16x16x32_bf16 v[0:3], v[182:185], v[214:217], v[0:3]
	v_mfma_f32_16x16x32_bf16 v[0:3], v[186:189], v[218:221], v[0:3]
	s_setprio 0
	s_barrier
; #define PG8_STAGE(bufoff, gbase, voff) do { _Pragma("unroll") for (int _i = 0; _i < 2; ++_i) \
;         __builtin_amdgcn_global_load_lds((const unsigned*)((const char*)(gbase) + (voff)[_i]), (PG8_LAS unsigned*)(lds + (bufoff) + ldsw + _i * 8192), 16, 0, 0); } while (0)
; #define PG8_LDA(dst, b, h) do { _Pragma("unroll") for (int m = 0; m < 4; ++m) _Pragma("unroll") for (int k = 0; k < 2; ++k) dst[m][k] = *(const PG8_LAS bf16x8*)(lds + PG8_SA(b, h) + aoff + m * 2048 + k * 1024); } while (0)
; #define PG8_LDB(dst, b, h) do { _Pragma("unroll") for (int n = 0; n < 2; ++n) _Pragma("unroll") for (int k = 0; k < 2; ++k) dst[n][k] = *(const PG8_LAS bf16x8*)(lds + PG8_SB(b, h) + boff + n * 2048 + k * 1024); } while (0)
; #define PG8_MMA(ai, bj, At, Bt) do { __builtin_amdgcn_s_setprio(1); _Pragma("unroll") for (int m = 0; m < 4; ++m) _Pragma("unroll") for (int n = 0; n < 2; ++n) _Pragma("unroll") for (int k = 0; k < 2; ++k) \
;         acc[ai][bj][m][n] = __builtin_amdgcn_mfma_f32_16x16x32_bf16(Bt[n][k], At[m][k], acc[ai][bj][m][n], 0, 0, 0); __builtin_amdgcn_s_setprio(0); } while (0)
; #define PG8_WAIT_V(n) asm volatile("s_waitcnt vmcnt(" #n ")" ::: "memory")
; #define PG8_WAIT_L(n) asm volatile("s_waitcnt lgkmcnt(" #n ")" ::: "memory")
; #define PG8_BAR __builtin_amdgcn_s_barrier()
; #define PG8_SCHED __builtin_amdgcn_sched_barrier(0)
;     ...
;             PG8_LDB(B0, 1, 0); PG8_LDB(B1, 1, 1); PG8_SCHED; PG8_LDA(At, 1, 0); PG8_STAGE(PG8_SA(0, 1), a2 + hstep, voffA);
;             PG8_WAIT_V(8); PG8_WAIT_L(0); PG8_BAR; PG8_MMA(0, 0, At, B0); PG8_MMA(0, 1, At, B1); PG8_BAR; PG8_SCHED;
;             PG8_LDA(At, 1, 1); PG8_STAGE(PG8_SB(1, 0), b3, voffB); PG8_STAGE(PG8_SB(1, 1), b3 + hstep, voffB); PG8_STAGE(PG8_SA(1, 0), a3, voffA);
;             PG8_WAIT_V(8); PG8_WAIT_L(0); PG8_BAR; PG8_MMA(1, 0, At, B0); PG8_MMA(1, 1, At, B1); PG8_BAR; PG8_SCHED;
	s_add_i32 s12, 0, 0x18000
	s_add_i32 s13, 0, 0x1c000
	v_add_u32_e32 v156, s12, v141
	v_add_u32_e32 v168, s13, v141
	ds_read_b128 v[144:147], v156
	ds_read_b128 v[148:151], v156 offset:1024
	ds_read_b128 v[152:155], v156 offset:2048
	ds_read_b128 v[156:159], v156 offset:3072
	ds_read_b128 v[160:163], v168
	ds_read_b128 v[164:167], v168 offset:1024
	ds_read_b128 v[182:185], v168 offset:2048
	ds_read_b128 v[186:189], v168 offset:3072
	s_add_u32 s42, s84, 0x80000
	s_addc_u32 s43, s85, 0
	s_mov_b32 m0, s3
	ds_read_b128 v[190:193], v143 offset:32768
	ds_read_b128 v[194:197], v143 offset:33792
	ds_read_b128 v[198:201], v143 offset:34816
	ds_read_b128 v[202:205], v143 offset:35840
	ds_read_b128 v[206:209], v143 offset:36864
	ds_read_b128 v[210:213], v143 offset:37888
	ds_read_b128 v[214:217], v143 offset:38912
	ds_read_b128 v[218:221], v143 offset:39936
	global_load_lds_dwordx4 v134, s[42:43]
	s_mov_b32 m0, s8
	s_nop 0
	global_load_lds_dwordx4 v130, s[42:43]
	s_waitcnt vmcnt(8)
	s_waitcnt lgkmcnt(0)
	s_barrier
	s_setprio 1
	s_waitcnt lgkmcnt(0)
	v_mfma_f32_16x16x32_bf16 v[124:127], v[144:147], v[190:193], v[124:127]
	v_mfma_f32_16x16x32_bf16 v[124:127], v[148:151], v[194:197], v[124:127]
	v_mfma_f32_16x16x32_bf16 v[108:111], v[144:147], v[198:201], v[108:111]
	v_mfma_f32_16x16x32_bf16 v[108:111], v[148:151], v[202:205], v[108:111]
	v_mfma_f32_16x16x32_bf16 v[92:95], v[144:147], v[206:209], v[92:95]
	v_mfma_f32_16x16x32_bf16 v[92:95], v[148:151], v[210:213], v[92:95]
	v_mfma_f32_16x16x32_bf16 v[76:79], v[144:147], v[214:217], v[76:79]
	v_mfma_f32_16x16x32_bf16 v[76:79], v[148:151], v[218:221], v[76:79]
	v_mfma_f32_16x16x32_bf16 v[120:123], v[152:155], v[190:193], v[120:123]
	v_mfma_f32_16x16x32_bf16 v[120:123], v[156:159], v[194:197], v[120:123]
	v_mfma_f32_16x16x32_bf16 v[104:107], v[152:155], v[198:201], v[104:107]
	v_mfma_f32_16x16x32_bf16 v[104:107], v[156:159], v[202:205], v[104:107]
	v_mfma_f32_16x16x32_bf16 v[88:91], v[152:155], v[206:209], v[88:91]
	v_mfma_f32_16x16x32_bf16 v[88:91], v[156:159], v[210:213], v[88:91]
	v_mfma_f32_16x16x32_bf16 v[72:75], v[152:155], v[214:217], v[72:75]
	v_mfma_f32_16x16x32_bf16 v[72:75], v[156:159], v[218:221], v[72:75]
	s_setprio 0
	s_setprio 1
	v_mfma_f32_16x16x32_bf16 v[116:119], v[160:163], v[190:193], v[116:119]
	v_mfma_f32_16x16x32_bf16 v[116:119], v[164:167], v[194:197], v[116:119]
	v_mfma_f32_16x16x32_bf16 v[100:103], v[160:163], v[198:201], v[100:103]
	v_mfma_f32_16x16x32_bf16 v[100:103], v[164:167], v[202:205], v[100:103]
	v_mfma_f32_16x16x32_bf16 v[84:87], v[160:163], v[206:209], v[84:87]
	v_mfma_f32_16x16x32_bf16 v[84:87], v[164:167], v[210:213], v[84:87]
	v_mfma_f32_16x16x32_bf16 v[68:71], v[160:163], v[214:217], v[68:71]
	v_mfma_f32_16x16x32_bf16 v[68:71], v[164:167], v[218:221], v[68:71]
	v_mfma_f32_16x16x32_bf16 v[112:115], v[182:185], v[190:193], v[112:115]
	v_mfma_f32_16x16x32_bf16 v[112:115], v[186:189], v[194:197], v[112:115]
	v_mfma_f32_16x16x32_bf16 v[96:99], v[182:185], v[198:201], v[96:99]
	v_mfma_f32_16x16x32_bf16 v[96:99], v[186:189], v[202:205], v[96:99]
	v_mfma_f32_16x16x32_bf16 v[80:83], v[182:185], v[206:209], v[80:83]
	v_mfma_f32_16x16x32_bf16 v[80:83], v[186:189], v[210:213], v[80:83]
	v_mfma_f32_16x16x32_bf16 v[64:67], v[182:185], v[214:217], v[64:67]
	v_mfma_f32_16x16x32_bf16 v[64:67], v[186:189], v[218:221], v[64:67]
	s_setprio 0
	s_barrier
	s_add_i32 s12, s12, s0
	s_mov_b32 m0, s12
	ds_read_b128 v[190:193], v143 offset:49152
	ds_read_b128 v[194:197], v143 offset:50176
	ds_read_b128 v[198:201], v143 offset:51200
	ds_read_b128 v[202:205], v143 offset:52224
	ds_read_b128 v[206:209], v143 offset:53248
	ds_read_b128 v[210:213], v143 offset:54272
	ds_read_b128 v[214:217], v143 offset:55296
	ds_read_b128 v[218:221], v143 offset:56320
	s_add_u32 s100, s82, s16
	s_addc_u32 s101, s83, s17
	global_load_lds_dwordx4 v132, s[100:101]
	s_add_i32 m0, s12, 0x2000
	s_add_u32 s42, s82, 0x80080
	s_addc_u32 s43, s83, 0
	s_add_i32 s12, s13, s0
	global_load_lds_dwordx4 v128, s[100:101]
	s_mov_b32 m0, s12
	s_nop 0
	global_load_lds_dwordx4 v132, s[42:43]
	s_add_i32 m0, s12, 0x2000
	s_nop 0
	global_load_lds_dwordx4 v128, s[42:43]
	s_mov_b32 m0, s9
	s_nop 0
	s_add_u32 s100, s84, s16
	s_addc_u32 s101, s85, s17
	global_load_lds_dwordx4 v134, s[100:101]
	s_mov_b32 m0, s10
	s_nop 0
	global_load_lds_dwordx4 v130, s[100:101]
	s_waitcnt vmcnt(8)
	s_waitcnt lgkmcnt(0)
	s_barrier
	s_setprio 1
	s_waitcnt lgkmcnt(0)
	v_mfma_f32_16x16x32_bf16 v[60:63], v[144:147], v[190:193], v[60:63]
	v_mfma_f32_16x16x32_bf16 v[60:63], v[148:151], v[194:197], v[60:63]
	v_mfma_f32_16x16x32_bf16 v[44:47], v[144:147], v[198:201], v[44:47]
	v_mfma_f32_16x16x32_bf16 v[44:47], v[148:151], v[202:205], v[44:47]
	v_mfma_f32_16x16x32_bf16 v[28:31], v[144:147], v[206:209], v[28:31]
	v_mfma_f32_16x16x32_bf16 v[28:31], v[148:151], v[210:213], v[28:31]
	v_mfma_f32_16x16x32_bf16 v[12:15], v[144:147], v[214:217], v[12:15]
	v_mfma_f32_16x16x32_bf16 v[12:15], v[148:151], v[218:221], v[12:15]
	v_mfma_f32_16x16x32_bf16 v[56:59], v[152:155], v[190:193], v[56:59]
	v_mfma_f32_16x16x32_bf16 v[56:59], v[156:159], v[194:197], v[56:59]
	v_mfma_f32_16x16x32_bf16 v[40:43], v[152:155], v[198:201], v[40:43]
	v_mfma_f32_16x16x32_bf16 v[40:43], v[156:159], v[202:205], v[40:43]
	v_mfma_f32_16x16x32_bf16 v[24:27], v[152:155], v[206:209], v[24:27]
	v_mfma_f32_16x16x32_bf16 v[24:27], v[156:159], v[210:213], v[24:27]
	v_mfma_f32_16x16x32_bf16 v[8:11], v[152:155], v[214:217], v[8:11]
	v_mfma_f32_16x16x32_bf16 v[8:11], v[156:159], v[218:221], v[8:11]
	s_setprio 0
	s_setprio 1
	v_mfma_f32_16x16x32_bf16 v[52:55], v[160:163], v[190:193], v[52:55]
	v_mfma_f32_16x16x32_bf16 v[52:55], v[164:167], v[194:197], v[52:55]
	v_mfma_f32_16x16x32_bf16 v[36:39], v[160:163], v[198:201], v[36:39]
	v_mfma_f32_16x16x32_bf16 v[36:39], v[164:167], v[202:205], v[36:39]
	v_mfma_f32_16x16x32_bf16 v[20:23], v[160:163], v[206:209], v[20:23]
	v_mfma_f32_16x16x32_bf16 v[20:23], v[164:167], v[210:213], v[20:23]
	v_mfma_f32_16x16x32_bf16 v[4:7], v[160:163], v[214:217], v[4:7]
	v_mfma_f32_16x16x32_bf16 v[4:7], v[164:167], v[218:221], v[4:7]
	v_mfma_f32_16x16x32_bf16 v[48:51], v[182:185], v[190:193], v[48:51]
	v_mfma_f32_16x16x32_bf16 v[48:51], v[186:189], v[194:197], v[48:51]
	v_mfma_f32_16x16x32_bf16 v[32:35], v[182:185], v[198:201], v[32:35]
	v_mfma_f32_16x16x32_bf16 v[32:35], v[186:189], v[202:205], v[32:35]
	v_mfma_f32_16x16x32_bf16 v[16:19], v[182:185], v[206:209], v[16:19]
	v_mfma_f32_16x16x32_bf16 v[16:19], v[186:189], v[210:213], v[16:19]
	v_mfma_f32_16x16x32_bf16 v[0:3], v[182:185], v[214:217], v[0:3]
	v_mfma_f32_16x16x32_bf16 v[0:3], v[186:189], v[218:221], v[0:3]
	s_setprio 0
	s_barrier
	s_add_i32 s28, s28, 2
	s_add_u32 s80, s80, 0x100
	s_addc_u32 s81, s81, 0
	s_add_u32 s23, s23, 0x100
	s_addc_u32 s25, s25, 0
	s_cmp_gt_u32 s28, 29
	s_cbranch_scc0 .LBB0_230
	s_and_b64 vcc, exec, s[68:69]
	s_cbranch_vccz .LBB0_233
	s_barrier

; #define PG8_STAGE(bufoff, gbase, voff) do { _Pragma("unroll") for (int _i = 0; _i < 2; ++_i) \
;         __builtin_amdgcn_global_load_lds((const unsigned*)((const char*)(gbase) + (voff)[_i]), (PG8_LAS unsigned*)(lds + (bufoff) + ldsw + _i * 8192), 16, 0, 0); } while (0)
; #define PG8_LDA(dst, b, h) do { _Pragma("unroll") for (int m = 0; m < 4; ++m) _Pragma("unroll") for (int k = 0; k < 2; ++k) dst[m][k] = *(const PG8_LAS bf16x8*)(lds + PG8_SA(b, h) + aoff + m * 2048 + k * 1024); } while (0)
; #define PG8_LDB(dst, b, h) do { _Pragma("unroll") for (int n = 0; n < 2; ++n) _Pragma("unroll") for (int k = 0; k < 2; ++k) dst[n][k] = *(const PG8_LAS bf16x8*)(lds + PG8_SB(b, h) + boff + n * 2048 + k * 1024); } while (0)
; #define PG8_MMA(ai, bj, At, Bt) do { __builtin_amdgcn_s_setprio(1); _Pragma("unroll") for (int m = 0; m < 4; ++m) _Pragma("unroll") for (int n = 0; n < 2; ++n) _Pragma("unroll") for (int k = 0; k < 2; ++k) \
;         acc[ai][bj][m][n] = __builtin_amdgcn_mfma_f32_16x16x32_bf16(Bt[n][k], At[m][k], acc[ai][bj][m][n], 0, 0, 0); __builtin_amdgcn_s_setprio(0); } while (0)
; #define PG8_WAIT_V(n) asm volatile("s_waitcnt vmcnt(" #n ")" ::: "memory")
; #define PG8_WAIT_L(n) asm volatile("s_waitcnt lgkmcnt(" #n ")" ::: "memory")
; #define PG8_BAR __builtin_amdgcn_s_barrier()
; #define PG8_SCHED __builtin_amdgcn_sched_barrier(0)
;     ...
;             const bool last = (t == nt - 2);
;             const char* a1 = PG8_KADV(cA, (size_t)(t + 1) * kstep);
;             const char* a2 = last ? nA : PG8_KADV(cA, (size_t)(t + 2) * kstep); const char* b2 = last ? nB : PG8_KADV(cB, (size_t)(t + 2) * kstep);
;             const char* a3 = PG8_KADV(a2, kstep); const char* b3 = PG8_KADV(b2, kstep);
;             if (last && has_next) S.a_ready(nxt);
;             if constexpr (SP2) {
;             PG8_LDB(B0, 0, 0); PG8_LDB(B1, 0, 1); PG8_SCHED; PG8_LDA(At, 0, 0); PG8_STAGE(PG8_SA(1, 1), a1 + hstep, voffA);
;             PG8_WAIT_V(8); PG8_WAIT_L(0); PG8_BAR; PG8_MMA(0, 0, At, B0); PG8_MMA(0, 1, At, B1); PG8_BAR; PG8_SCHED;
;             PG8_LDA(At, 0, 1); PG8_STAGE(PG8_SB(0, 0), b2, voffB); PG8_STAGE(PG8_SB(0, 1), b2 + hstep, voffB); PG8_STAGE(PG8_SA(0, 0), a2, voffA);
;             PG8_WAIT_V(8); PG8_WAIT_L(0); PG8_BAR; PG8_MMA(1, 0, At, B0); PG8_MMA(1, 1, At, B1); PG8_BAR; PG8_SCHED;
.LBB0_313:
	s_add_u32 s78, s76, 0xffffff00
	s_addc_u32 s79, s77, -1
	s_add_i32 s12, 0, 0x10000
	s_cmpk_eq_i32 s3, 0x54
	s_cselect_b32 s83, s7, s79
	s_cselect_b32 s82, s6, s78
	s_cselect_b32 s81, s75, s30
	s_cselect_b32 s80, s74, s2
	s_add_i32 s13, 0, 0x14000
	v_add_u32_e32 v152, s12, v166
	v_add_u32_e32 v164, s13, v166
	ds_read_b128 v[128:131], v152
	ds_read_b128 v[132:135], v152 offset:1024
	ds_read_b128 v[148:151], v152 offset:2048
	ds_read_b128 v[152:155], v152 offset:3072
	ds_read_b128 v[156:159], v164
	ds_read_b128 v[160:163], v164 offset:1024
	ds_read_b128 v[170:173], v164 offset:2048
	ds_read_b128 v[178:181], v164 offset:3072
	s_add_i32 m0, s9, 0xc000
	ds_read_b128 v[184:187], v183
	ds_read_b128 v[188:191], v183 offset:1024
	ds_read_b128 v[192:195], v183 offset:2048
	ds_read_b128 v[196:199], v183 offset:3072
	ds_read_b128 v[200:203], v183 offset:4096
	ds_read_b128 v[204:207], v183 offset:5120
	ds_read_b128 v[208:211], v183 offset:6144
	ds_read_b128 v[212:215], v183 offset:7168
	global_load_lds_dwordx4 v144, s[76:77]
	s_add_i32 m0, s9, 0xe000
	s_nop 0
	global_load_lds_dwordx4 v146, s[76:77]
	s_waitcnt vmcnt(8)
	s_waitcnt lgkmcnt(0)
	s_barrier
	s_setprio 1
	s_waitcnt lgkmcnt(0)
	v_mfma_f32_16x16x32_bf16 v[124:127], v[128:131], v[184:187], v[124:127]
	v_mfma_f32_16x16x32_bf16 v[124:127], v[132:135], v[188:191], v[124:127]
	v_mfma_f32_16x16x32_bf16 v[112:115], v[128:131], v[192:195], v[112:115]
	v_mfma_f32_16x16x32_bf16 v[112:115], v[132:135], v[196:199], v[112:115]
	v_mfma_f32_16x16x32_bf16 v[92:95], v[128:131], v[200:203], v[92:95]
	v_mfma_f32_16x16x32_bf16 v[92:95], v[132:135], v[204:207], v[92:95]
	v_mfma_f32_16x16x32_bf16 v[80:83], v[128:131], v[208:211], v[80:83]
	v_mfma_f32_16x16x32_bf16 v[80:83], v[132:135], v[212:215], v[80:83]
	v_mfma_f32_16x16x32_bf16 v[120:123], v[148:151], v[184:187], v[120:123]
	v_mfma_f32_16x16x32_bf16 v[120:123], v[152:155], v[188:191], v[120:123]
	v_mfma_f32_16x16x32_bf16 v[104:107], v[148:151], v[192:195], v[104:107]
	v_mfma_f32_16x16x32_bf16 v[104:107], v[152:155], v[196:199], v[104:107]
	v_mfma_f32_16x16x32_bf16 v[88:91], v[148:151], v[200:203], v[88:91]
	v_mfma_f32_16x16x32_bf16 v[88:91], v[152:155], v[204:207], v[88:91]
	v_mfma_f32_16x16x32_bf16 v[72:75], v[148:151], v[208:211], v[72:75]
	v_mfma_f32_16x16x32_bf16 v[72:75], v[152:155], v[212:215], v[72:75]
	s_setprio 0
	s_setprio 1
	v_mfma_f32_16x16x32_bf16 v[116:119], v[156:159], v[184:187], v[116:119]
	v_mfma_f32_16x16x32_bf16 v[116:119], v[160:163], v[188:191], v[116:119]
	v_mfma_f32_16x16x32_bf16 v[100:103], v[156:159], v[192:195], v[100:103]
	v_mfma_f32_16x16x32_bf16 v[100:103], v[160:163], v[196:199], v[100:103]
	v_mfma_f32_16x16x32_bf16 v[84:87], v[156:159], v[200:203], v[84:87]
	v_mfma_f32_16x16x32_bf16 v[84:87], v[160:163], v[204:207], v[84:87]
	v_mfma_f32_16x16x32_bf16 v[68:71], v[156:159], v[208:211], v[68:71]
	v_mfma_f32_16x16x32_bf16 v[68:71], v[160:163], v[212:215], v[68:71]
	v_mfma_f32_16x16x32_bf16 v[108:111], v[170:173], v[184:187], v[108:111]
	v_mfma_f32_16x16x32_bf16 v[108:111], v[178:181], v[188:191], v[108:111]
	v_mfma_f32_16x16x32_bf16 v[96:99], v[170:173], v[192:195], v[96:99]
	v_mfma_f32_16x16x32_bf16 v[96:99], v[178:181], v[196:199], v[96:99]
	v_mfma_f32_16x16x32_bf16 v[76:79], v[170:173], v[200:203], v[76:79]
	v_mfma_f32_16x16x32_bf16 v[76:79], v[178:181], v[204:207], v[76:79]
	v_mfma_f32_16x16x32_bf16 v[64:67], v[170:173], v[208:211], v[64:67]
	v_mfma_f32_16x16x32_bf16 v[64:67], v[178:181], v[212:215], v[64:67]
	s_setprio 0
	s_barrier
	s_add_i32 s12, s12, s8
	s_mov_b32 m0, s12
	ds_read_b128 v[184:187], v183 offset:16384
	ds_read_b128 v[188:191], v183 offset:17408
	ds_read_b128 v[192:195], v183 offset:18432
	ds_read_b128 v[196:199], v183 offset:19456
	ds_read_b128 v[200:203], v183 offset:20480
	ds_read_b128 v[204:207], v183 offset:21504
	ds_read_b128 v[208:211], v183 offset:22528
	ds_read_b128 v[212:215], v183 offset:23552
	global_load_lds_dwordx4 v138, s[80:81]
	s_add_i32 m0, s12, 0x2000
	s_add_u32 s42, s80, 0x160000
	s_addc_u32 s43, s81, 0
	s_add_i32 s12, s13, s8
	global_load_lds_dwordx4 v142, s[80:81]
	s_mov_b32 m0, s12
	s_nop 0
	global_load_lds_dwordx4 v138, s[42:43]
	s_add_i32 m0, s12, 0x2000
	s_nop 0
	global_load_lds_dwordx4 v142, s[42:43]
	s_mov_b32 m0, s9
	s_nop 0
	global_load_lds_dwordx4 v136, s[82:83]
	s_mov_b32 m0, s10
	s_nop 0
	global_load_lds_dwordx4 v140, s[82:83]
	s_waitcnt vmcnt(8)
	s_waitcnt lgkmcnt(0)
	s_barrier
	s_setprio 1
	s_waitcnt lgkmcnt(0)
	v_mfma_f32_16x16x32_bf16 v[60:63], v[128:131], v[184:187], v[60:63]
	v_mfma_f32_16x16x32_bf16 v[60:63], v[132:135], v[188:191], v[60:63]
	v_mfma_f32_16x16x32_bf16 v[48:51], v[128:131], v[192:195], v[48:51]
	v_mfma_f32_16x16x32_bf16 v[48:51], v[132:135], v[196:199], v[48:51]
	v_mfma_f32_16x16x32_bf16 v[28:31], v[128:131], v[200:203], v[28:31]
	v_mfma_f32_16x16x32_bf16 v[28:31], v[132:135], v[204:207], v[28:31]
	v_mfma_f32_16x16x32_bf16 v[16:19], v[128:131], v[208:211], v[16:19]
	v_mfma_f32_16x16x32_bf16 v[16:19], v[132:135], v[212:215], v[16:19]
	v_mfma_f32_16x16x32_bf16 v[56:59], v[148:151], v[184:187], v[56:59]
	v_mfma_f32_16x16x32_bf16 v[56:59], v[152:155], v[188:191], v[56:59]
	v_mfma_f32_16x16x32_bf16 v[40:43], v[148:151], v[192:195], v[40:43]
	v_mfma_f32_16x16x32_bf16 v[40:43], v[152:155], v[196:199], v[40:43]
	v_mfma_f32_16x16x32_bf16 v[24:27], v[148:151], v[200:203], v[24:27]
	v_mfma_f32_16x16x32_bf16 v[24:27], v[152:155], v[204:207], v[24:27]
	v_mfma_f32_16x16x32_bf16 v[8:11], v[148:151], v[208:211], v[8:11]
	v_mfma_f32_16x16x32_bf16 v[8:11], v[152:155], v[212:215], v[8:11]
	s_setprio 0
	s_setprio 1
	v_mfma_f32_16x16x32_bf16 v[52:55], v[156:159], v[184:187], v[52:55]
	v_mfma_f32_16x16x32_bf16 v[52:55], v[160:163], v[188:191], v[52:55]
	v_mfma_f32_16x16x32_bf16 v[36:39], v[156:159], v[192:195], v[36:39]
	v_mfma_f32_16x16x32_bf16 v[36:39], v[160:163], v[196:199], v[36:39]
	v_mfma_f32_16x16x32_bf16 v[20:23], v[156:159], v[200:203], v[20:23]
	v_mfma_f32_16x16x32_bf16 v[20:23], v[160:163], v[204:207], v[20:23]
	v_mfma_f32_16x16x32_bf16 v[4:7], v[156:159], v[208:211], v[4:7]
	v_mfma_f32_16x16x32_bf16 v[4:7], v[160:163], v[212:215], v[4:7]
	v_mfma_f32_16x16x32_bf16 v[44:47], v[170:173], v[184:187], v[44:47]
	v_mfma_f32_16x16x32_bf16 v[44:47], v[178:181], v[188:191], v[44:47]
	v_mfma_f32_16x16x32_bf16 v[32:35], v[170:173], v[192:195], v[32:35]
	v_mfma_f32_16x16x32_bf16 v[32:35], v[178:181], v[196:199], v[32:35]
	v_mfma_f32_16x16x32_bf16 v[12:15], v[170:173], v[200:203], v[12:15]
	v_mfma_f32_16x16x32_bf16 v[12:15], v[178:181], v[204:207], v[12:15]
	v_mfma_f32_16x16x32_bf16 v[0:3], v[170:173], v[208:211], v[0:3]
	v_mfma_f32_16x16x32_bf16 v[0:3], v[178:181], v[212:215], v[0:3]
	s_setprio 0
	s_barrier
; #define PG8_STAGE(bufoff, gbase, voff) do { _Pragma("unroll") for (int _i = 0; _i < 2; ++_i) \
;         __builtin_amdgcn_global_load_lds((const unsigned*)((const char*)(gbase) + (voff)[_i]), (PG8_LAS unsigned*)(lds + (bufoff) + ldsw + _i * 8192), 16, 0, 0); } while (0)
; #define PG8_LDA(dst, b, h) do { _Pragma("unroll") for (int m = 0; m < 4; ++m) _Pragma("unroll") for (int k = 0; k < 2; ++k) dst[m][k] = *(const PG8_LAS bf16x8*)(lds + PG8_SA(b, h) + aoff + m * 2048 + k * 1024); } while (0)
; #define PG8_LDB(dst, b, h) do { _Pragma("unroll") for (int n = 0; n < 2; ++n) _Pragma("unroll") for (int k = 0; k < 2; ++k) dst[n][k] = *(const PG8_LAS bf16x8*)(lds + PG8_SB(b, h) + boff + n * 2048 + k * 1024); } while (0)
; #define PG8_MMA(ai, bj, At, Bt) do { __builtin_amdgcn_s_setprio(1); _Pragma("unroll") for (int m = 0; m < 4; ++m) _Pragma("unroll") for (int n = 0; n < 2; ++n) _Pragma("unroll") for (int k = 0; k < 2; ++k) \
;         acc[ai][bj][m][n] = __builtin_amdgcn_mfma_f32_16x16x32_bf16(Bt[n][k], At[m][k], acc[ai][bj][m][n], 0, 0, 0); __builtin_amdgcn_s_setprio(0); } while (0)
; #define PG8_WAIT_V(n) asm volatile("s_waitcnt vmcnt(" #n ")" ::: "memory")
; #define PG8_WAIT_L(n) asm volatile("s_waitcnt lgkmcnt(" #n ")" ::: "memory")
; #define PG8_BAR __builtin_amdgcn_s_barrier()
; #define PG8_SCHED __builtin_amdgcn_sched_barrier(0)
;     ...
;             PG8_LDB(B0, 1, 0); PG8_LDB(B1, 1, 1); PG8_SCHED; PG8_LDA(At, 1, 0); PG8_STAGE(PG8_SA(0, 1), a2 + hstep, voffA);
;             PG8_WAIT_V(8); PG8_WAIT_L(0); PG8_BAR; PG8_MMA(0, 0, At, B0); PG8_MMA(0, 1, At, B1); PG8_BAR; PG8_SCHED;
;             PG8_LDA(At, 1, 1); PG8_STAGE(PG8_SB(1, 0), b3, voffB); PG8_STAGE(PG8_SB(1, 1), b3 + hstep, voffB); PG8_STAGE(PG8_SA(1, 0), a3, voffA);
;             PG8_WAIT_V(8); PG8_WAIT_L(0); PG8_BAR; PG8_MMA(1, 0, At, B0); PG8_MMA(1, 1, At, B1); PG8_BAR; PG8_SCHED;
	s_add_i32 s12, 0, 0x18000
	s_add_i32 s13, 0, 0x1c000
	v_add_u32_e32 v152, s12, v166
	v_add_u32_e32 v168, s13, v166
	ds_read_b128 v[128:131], v152
	ds_read_b128 v[132:135], v152 offset:1024
	ds_read_b128 v[148:151], v152 offset:2048
	ds_read_b128 v[152:155], v152 offset:3072
	ds_read_b128 v[156:159], v168
	ds_read_b128 v[160:163], v168 offset:1024
	ds_read_b128 v[170:173], v168 offset:2048
	ds_read_b128 v[178:181], v168 offset:3072
	s_add_u32 s42, s82, 0x160000
	s_addc_u32 s43, s83, 0
	s_mov_b32 m0, s18
	ds_read_b128 v[184:187], v183 offset:32768
	ds_read_b128 v[188:191], v183 offset:33792
	ds_read_b128 v[192:195], v183 offset:34816
	ds_read_b128 v[196:199], v183 offset:35840
	ds_read_b128 v[200:203], v183 offset:36864
	ds_read_b128 v[204:207], v183 offset:37888
	ds_read_b128 v[208:211], v183 offset:38912
	ds_read_b128 v[212:215], v183 offset:39936
	global_load_lds_dwordx4 v136, s[42:43]
	s_mov_b32 m0, s19
	s_nop 0
	global_load_lds_dwordx4 v140, s[42:43]
	s_waitcnt vmcnt(8)
	s_waitcnt lgkmcnt(0)
	s_barrier
	s_setprio 1
	s_waitcnt lgkmcnt(0)
	v_mfma_f32_16x16x32_bf16 v[124:127], v[128:131], v[184:187], v[124:127]
	v_mfma_f32_16x16x32_bf16 v[124:127], v[132:135], v[188:191], v[124:127]
	v_mfma_f32_16x16x32_bf16 v[112:115], v[128:131], v[192:195], v[112:115]
	v_mfma_f32_16x16x32_bf16 v[112:115], v[132:135], v[196:199], v[112:115]
	v_mfma_f32_16x16x32_bf16 v[92:95], v[128:131], v[200:203], v[92:95]
	v_mfma_f32_16x16x32_bf16 v[92:95], v[132:135], v[204:207], v[92:95]
	v_mfma_f32_16x16x32_bf16 v[80:83], v[128:131], v[208:211], v[80:83]
	v_mfma_f32_16x16x32_bf16 v[80:83], v[132:135], v[212:215], v[80:83]
	v_mfma_f32_16x16x32_bf16 v[120:123], v[148:151], v[184:187], v[120:123]
	v_mfma_f32_16x16x32_bf16 v[120:123], v[152:155], v[188:191], v[120:123]
	v_mfma_f32_16x16x32_bf16 v[104:107], v[148:151], v[192:195], v[104:107]
	v_mfma_f32_16x16x32_bf16 v[104:107], v[152:155], v[196:199], v[104:107]
	v_mfma_f32_16x16x32_bf16 v[88:91], v[148:151], v[200:203], v[88:91]
	v_mfma_f32_16x16x32_bf16 v[88:91], v[152:155], v[204:207], v[88:91]
	v_mfma_f32_16x16x32_bf16 v[72:75], v[148:151], v[208:211], v[72:75]
	v_mfma_f32_16x16x32_bf16 v[72:75], v[152:155], v[212:215], v[72:75]
	s_setprio 0
	s_setprio 1
	v_mfma_f32_16x16x32_bf16 v[116:119], v[156:159], v[184:187], v[116:119]
	v_mfma_f32_16x16x32_bf16 v[116:119], v[160:163], v[188:191], v[116:119]
	v_mfma_f32_16x16x32_bf16 v[100:103], v[156:159], v[192:195], v[100:103]
	v_mfma_f32_16x16x32_bf16 v[100:103], v[160:163], v[196:199], v[100:103]
	v_mfma_f32_16x16x32_bf16 v[84:87], v[156:159], v[200:203], v[84:87]
	v_mfma_f32_16x16x32_bf16 v[84:87], v[160:163], v[204:207], v[84:87]
	v_mfma_f32_16x16x32_bf16 v[68:71], v[156:159], v[208:211], v[68:71]
	v_mfma_f32_16x16x32_bf16 v[68:71], v[160:163], v[212:215], v[68:71]
	v_mfma_f32_16x16x32_bf16 v[108:111], v[170:173], v[184:187], v[108:111]
	v_mfma_f32_16x16x32_bf16 v[108:111], v[178:181], v[188:191], v[108:111]
	v_mfma_f32_16x16x32_bf16 v[96:99], v[170:173], v[192:195], v[96:99]
	v_mfma_f32_16x16x32_bf16 v[96:99], v[178:181], v[196:199], v[96:99]
	v_mfma_f32_16x16x32_bf16 v[76:79], v[170:173], v[200:203], v[76:79]
	v_mfma_f32_16x16x32_bf16 v[76:79], v[178:181], v[204:207], v[76:79]
	v_mfma_f32_16x16x32_bf16 v[64:67], v[170:173], v[208:211], v[64:67]
	v_mfma_f32_16x16x32_bf16 v[64:67], v[178:181], v[212:215], v[64:67]
	s_setprio 0
	s_barrier
	s_add_i32 s12, s12, s8
	s_mov_b32 m0, s12
	ds_read_b128 v[184:187], v183 offset:49152
	ds_read_b128 v[188:191], v183 offset:50176
	ds_read_b128 v[192:195], v183 offset:51200
	ds_read_b128 v[196:199], v183 offset:52224
	ds_read_b128 v[200:203], v183 offset:53248
	ds_read_b128 v[204:207], v183 offset:54272
	ds_read_b128 v[208:211], v183 offset:55296
	ds_read_b128 v[212:215], v183 offset:56320
	s_add_u32 s100, s80, s38
	s_addc_u32 s101, s81, s39
	global_load_lds_dwordx4 v138, s[100:101]
	s_add_i32 m0, s12, 0x2000
	s_add_u32 s42, s80, 0x15ff80
	s_addc_u32 s43, s81, 0
	s_add_i32 s12, s13, s8
	global_load_lds_dwordx4 v142, s[100:101]
	s_mov_b32 m0, s12
	s_nop 0
	global_load_lds_dwordx4 v138, s[42:43]
	s_add_i32 m0, s12, 0x2000
	s_nop 0
	global_load_lds_dwordx4 v142, s[42:43]
	s_mov_b32 m0, s20
	s_nop 0
	s_add_u32 s100, s82, s38
	s_addc_u32 s101, s83, s39
	global_load_lds_dwordx4 v136, s[100:101]
	s_mov_b32 m0, s21
	s_nop 0
	global_load_lds_dwordx4 v140, s[100:101]
	s_waitcnt vmcnt(8)
	s_waitcnt lgkmcnt(0)
	s_barrier
	s_setprio 1
	s_waitcnt lgkmcnt(0)
	v_mfma_f32_16x16x32_bf16 v[60:63], v[128:131], v[184:187], v[60:63]
	v_mfma_f32_16x16x32_bf16 v[60:63], v[132:135], v[188:191], v[60:63]
	v_mfma_f32_16x16x32_bf16 v[48:51], v[128:131], v[192:195], v[48:51]
	v_mfma_f32_16x16x32_bf16 v[48:51], v[132:135], v[196:199], v[48:51]
	v_mfma_f32_16x16x32_bf16 v[28:31], v[128:131], v[200:203], v[28:31]
	v_mfma_f32_16x16x32_bf16 v[28:31], v[132:135], v[204:207], v[28:31]
	v_mfma_f32_16x16x32_bf16 v[16:19], v[128:131], v[208:211], v[16:19]
	v_mfma_f32_16x16x32_bf16 v[16:19], v[132:135], v[212:215], v[16:19]
	v_mfma_f32_16x16x32_bf16 v[56:59], v[148:151], v[184:187], v[56:59]
	v_mfma_f32_16x16x32_bf16 v[56:59], v[152:155], v[188:191], v[56:59]
	v_mfma_f32_16x16x32_bf16 v[40:43], v[148:151], v[192:195], v[40:43]
	v_mfma_f32_16x16x32_bf16 v[40:43], v[152:155], v[196:199], v[40:43]
	v_mfma_f32_16x16x32_bf16 v[24:27], v[148:151], v[200:203], v[24:27]
	v_mfma_f32_16x16x32_bf16 v[24:27], v[152:155], v[204:207], v[24:27]
	v_mfma_f32_16x16x32_bf16 v[8:11], v[148:151], v[208:211], v[8:11]
	v_mfma_f32_16x16x32_bf16 v[8:11], v[152:155], v[212:215], v[8:11]
	s_setprio 0
	s_setprio 1
	v_mfma_f32_16x16x32_bf16 v[52:55], v[156:159], v[184:187], v[52:55]
	v_mfma_f32_16x16x32_bf16 v[52:55], v[160:163], v[188:191], v[52:55]
	v_mfma_f32_16x16x32_bf16 v[36:39], v[156:159], v[192:195], v[36:39]
	v_mfma_f32_16x16x32_bf16 v[36:39], v[160:163], v[196:199], v[36:39]
	v_mfma_f32_16x16x32_bf16 v[20:23], v[156:159], v[200:203], v[20:23]
	v_mfma_f32_16x16x32_bf16 v[20:23], v[160:163], v[204:207], v[20:23]
	v_mfma_f32_16x16x32_bf16 v[4:7], v[156:159], v[208:211], v[4:7]
	v_mfma_f32_16x16x32_bf16 v[4:7], v[160:163], v[212:215], v[4:7]
	v_mfma_f32_16x16x32_bf16 v[44:47], v[170:173], v[184:187], v[44:47]
	v_mfma_f32_16x16x32_bf16 v[44:47], v[178:181], v[188:191], v[44:47]
	v_mfma_f32_16x16x32_bf16 v[32:35], v[170:173], v[192:195], v[32:35]
	v_mfma_f32_16x16x32_bf16 v[32:35], v[178:181], v[196:199], v[32:35]
	v_mfma_f32_16x16x32_bf16 v[12:15], v[170:173], v[200:203], v[12:15]
	v_mfma_f32_16x16x32_bf16 v[12:15], v[178:181], v[204:207], v[12:15]
	v_mfma_f32_16x16x32_bf16 v[0:3], v[170:173], v[208:211], v[0:3]
	v_mfma_f32_16x16x32_bf16 v[0:3], v[178:181], v[212:215], v[0:3]
	s_setprio 0
	s_barrier
	s_add_i32 s3, s3, 2
	s_add_u32 s2, s2, 0xffffff00
	s_addc_u32 s30, s30, -1
	s_cmpk_gt_u32 s3, 0x55
	s_mov_b64 s[76:77], s[78:79]
	s_cbranch_scc0 .LBB0_313
	s_and_b64 vcc, exec, s[72:73]
	s_cbranch_vccz .LBB0_316
	s_barrier

; #define PG8_STAGE(bufoff, gbase, voff) do { _Pragma("unroll") for (int _i = 0; _i < 2; ++_i) \
;         __builtin_amdgcn_global_load_lds((const unsigned*)((const char*)(gbase) + (voff)[_i]), (PG8_LAS unsigned*)(lds + (bufoff) + ldsw + _i * 8192), 16, 0, 0); } while (0)
; #define PG8_LDA(dst, b, h) do { _Pragma("unroll") for (int m = 0; m < 4; ++m) _Pragma("unroll") for (int k = 0; k < 2; ++k) dst[m][k] = *(const PG8_LAS bf16x8*)(lds + PG8_SA(b, h) + aoff + m * 2048 + k * 1024); } while (0)
; #define PG8_LDB(dst, b, h) do { _Pragma("unroll") for (int n = 0; n < 2; ++n) _Pragma("unroll") for (int k = 0; k < 2; ++k) dst[n][k] = *(const PG8_LAS bf16x8*)(lds + PG8_SB(b, h) + boff + n * 2048 + k * 1024); } while (0)
; #define PG8_MMA(ai, bj, At, Bt) do { __builtin_amdgcn_s_setprio(1); _Pragma("unroll") for (int m = 0; m < 4; ++m) _Pragma("unroll") for (int n = 0; n < 2; ++n) _Pragma("unroll") for (int k = 0; k < 2; ++k) \
;         acc[ai][bj][m][n] = __builtin_amdgcn_mfma_f32_16x16x32_bf16(Bt[n][k], At[m][k], acc[ai][bj][m][n], 0, 0, 0); __builtin_amdgcn_s_setprio(0); } while (0)
; #define PG8_WAIT_V(n) asm volatile("s_waitcnt vmcnt(" #n ")" ::: "memory")
; #define PG8_WAIT_L(n) asm volatile("s_waitcnt lgkmcnt(" #n ")" ::: "memory")
; #define PG8_BAR __builtin_amdgcn_s_barrier()
; #define PG8_SCHED __builtin_amdgcn_sched_barrier(0)
;     ...
;             const bool last = (t == nt - 2);
;             const char* a1 = PG8_KADV(cA, (size_t)(t + 1) * kstep);
;             const char* a2 = last ? nA : PG8_KADV(cA, (size_t)(t + 2) * kstep); const char* b2 = last ? nB : PG8_KADV(cB, (size_t)(t + 2) * kstep);
;             const char* a3 = PG8_KADV(a2, kstep); const char* b3 = PG8_KADV(b2, kstep);
;             if (last && has_next) S.a_ready(nxt);
;             if constexpr (SP2) {
;             PG8_LDB(B0, 0, 0); PG8_LDB(B1, 0, 1); PG8_SCHED; PG8_LDA(At, 0, 0); PG8_STAGE(PG8_SA(1, 1), a1 + hstep, voffA);
;             PG8_WAIT_V(8); PG8_WAIT_L(0); PG8_BAR; PG8_MMA(0, 0, At, B0); PG8_MMA(0, 1, At, B1); PG8_BAR; PG8_SCHED;
;             PG8_LDA(At, 0, 1); PG8_STAGE(PG8_SB(0, 0), b2, voffB); PG8_STAGE(PG8_SB(0, 1), b2 + hstep, voffB); PG8_STAGE(PG8_SA(0, 0), a2, voffA);
;             PG8_WAIT_V(8); PG8_WAIT_L(0); PG8_BAR; PG8_MMA(1, 0, At, B0); PG8_MMA(1, 1, At, B1); PG8_BAR; PG8_SCHED;
.LBB0_343:
	s_add_u32 s78, s76, 0xffffff00
	s_addc_u32 s79, s77, -1
	s_add_i32 s12, 0, 0x10000
	s_cmpk_eq_i32 s3, 0x54
	s_cselect_b32 s83, s7, s79
	s_cselect_b32 s82, s6, s78
	s_cselect_b32 s81, s75, s30
	s_cselect_b32 s80, s74, s2
	s_add_i32 s13, 0, 0x14000
	v_add_u32_e32 v140, s12, v233
	v_add_u32_e32 v156, s13, v233
	ds_read_b128 v[128:131], v140
	ds_read_b128 v[132:135], v140 offset:1024
	ds_read_b128 v[136:139], v140 offset:2048
	ds_read_b128 v[140:143], v140 offset:3072
	ds_read_b128 v[144:147], v156
	ds_read_b128 v[148:151], v156 offset:1024
	ds_read_b128 v[152:155], v156 offset:2048
	ds_read_b128 v[156:159], v156 offset:3072
	s_add_i32 m0, s9, 0xc000
	ds_read_b128 v[160:163], v236
	ds_read_b128 v[164:167], v236 offset:1024
	ds_read_b128 v[194:197], v236 offset:2048
	ds_read_b128 v[198:201], v236 offset:3072
	ds_read_b128 v[202:205], v236 offset:4096
	ds_read_b128 v[206:209], v236 offset:5120
	ds_read_b128 v[210:213], v236 offset:6144
	ds_read_b128 v[214:217], v236 offset:7168
	global_load_lds_dwordx4 v190, s[76:77]
	s_add_i32 m0, s9, 0xe000
	s_nop 0
	global_load_lds_dwordx4 v192, s[76:77]
	s_waitcnt vmcnt(8)
	s_waitcnt lgkmcnt(0)
	s_barrier
	s_setprio 1
	s_waitcnt lgkmcnt(0)
	v_mfma_f32_16x16x32_bf16 v[124:127], v[128:131], v[160:163], v[124:127]
	v_mfma_f32_16x16x32_bf16 v[124:127], v[132:135], v[164:167], v[124:127]
	v_mfma_f32_16x16x32_bf16 v[108:111], v[128:131], v[194:197], v[108:111]
	v_mfma_f32_16x16x32_bf16 v[108:111], v[132:135], v[198:201], v[108:111]
	v_mfma_f32_16x16x32_bf16 v[100:103], v[128:131], v[202:205], v[100:103]
	v_mfma_f32_16x16x32_bf16 v[100:103], v[132:135], v[206:209], v[100:103]
	v_mfma_f32_16x16x32_bf16 v[84:87], v[128:131], v[210:213], v[84:87]
	v_mfma_f32_16x16x32_bf16 v[84:87], v[132:135], v[214:217], v[84:87]
	v_mfma_f32_16x16x32_bf16 v[120:123], v[136:139], v[160:163], v[120:123]
	v_mfma_f32_16x16x32_bf16 v[120:123], v[140:143], v[164:167], v[120:123]
	v_mfma_f32_16x16x32_bf16 v[104:107], v[136:139], v[194:197], v[104:107]
	v_mfma_f32_16x16x32_bf16 v[104:107], v[140:143], v[198:201], v[104:107]
	v_mfma_f32_16x16x32_bf16 v[92:95], v[136:139], v[202:205], v[92:95]
	v_mfma_f32_16x16x32_bf16 v[92:95], v[140:143], v[206:209], v[92:95]
	v_mfma_f32_16x16x32_bf16 v[76:79], v[136:139], v[210:213], v[76:79]
	v_mfma_f32_16x16x32_bf16 v[76:79], v[140:143], v[214:217], v[76:79]
	s_setprio 0
	s_setprio 1
	v_mfma_f32_16x16x32_bf16 v[116:119], v[144:147], v[160:163], v[116:119]
	v_mfma_f32_16x16x32_bf16 v[116:119], v[148:151], v[164:167], v[116:119]
	v_mfma_f32_16x16x32_bf16 v[96:99], v[144:147], v[194:197], v[96:99]
	v_mfma_f32_16x16x32_bf16 v[96:99], v[148:151], v[198:201], v[96:99]
	v_mfma_f32_16x16x32_bf16 v[80:83], v[144:147], v[202:205], v[80:83]
	v_mfma_f32_16x16x32_bf16 v[80:83], v[148:151], v[206:209], v[80:83]
	v_mfma_f32_16x16x32_bf16 v[68:71], v[144:147], v[210:213], v[68:71]
	v_mfma_f32_16x16x32_bf16 v[68:71], v[148:151], v[214:217], v[68:71]
	v_mfma_f32_16x16x32_bf16 v[112:115], v[152:155], v[160:163], v[112:115]
	v_mfma_f32_16x16x32_bf16 v[112:115], v[156:159], v[164:167], v[112:115]
	v_mfma_f32_16x16x32_bf16 v[88:91], v[152:155], v[194:197], v[88:91]
	v_mfma_f32_16x16x32_bf16 v[88:91], v[156:159], v[198:201], v[88:91]
	v_mfma_f32_16x16x32_bf16 v[72:75], v[152:155], v[202:205], v[72:75]
	v_mfma_f32_16x16x32_bf16 v[72:75], v[156:159], v[206:209], v[72:75]
	v_mfma_f32_16x16x32_bf16 v[64:67], v[152:155], v[210:213], v[64:67]
	v_mfma_f32_16x16x32_bf16 v[64:67], v[156:159], v[214:217], v[64:67]
	s_setprio 0
	s_barrier
	s_add_i32 s12, s12, s8
	s_mov_b32 m0, s12
	ds_read_b128 v[160:163], v236 offset:16384
	ds_read_b128 v[164:167], v236 offset:17408
	ds_read_b128 v[194:197], v236 offset:18432
	ds_read_b128 v[198:201], v236 offset:19456
	ds_read_b128 v[202:205], v236 offset:20480
	ds_read_b128 v[206:209], v236 offset:21504
	ds_read_b128 v[210:213], v236 offset:22528
	ds_read_b128 v[214:217], v236 offset:23552
	global_load_lds_dwordx4 v184, s[80:81]
	s_add_i32 m0, s12, 0x2000
	s_add_u32 s42, s80, 0x160000
	s_addc_u32 s43, s81, 0
	s_add_i32 s12, s13, s8
	global_load_lds_dwordx4 v188, s[80:81]
	s_mov_b32 m0, s12
	s_nop 0
	global_load_lds_dwordx4 v184, s[42:43]
	s_add_i32 m0, s12, 0x2000
	s_nop 0
	global_load_lds_dwordx4 v188, s[42:43]
	s_mov_b32 m0, s9
	s_nop 0
	global_load_lds_dwordx4 v182, s[82:83]
	s_mov_b32 m0, s10
	s_nop 0
	global_load_lds_dwordx4 v186, s[82:83]
	s_waitcnt vmcnt(8)
	s_waitcnt lgkmcnt(0)
	s_barrier
	s_setprio 1
	s_waitcnt lgkmcnt(0)
	v_mfma_f32_16x16x32_bf16 v[60:63], v[128:131], v[160:163], v[60:63]
	v_mfma_f32_16x16x32_bf16 v[60:63], v[132:135], v[164:167], v[60:63]
	v_mfma_f32_16x16x32_bf16 v[52:55], v[128:131], v[194:197], v[52:55]
	v_mfma_f32_16x16x32_bf16 v[52:55], v[132:135], v[198:201], v[52:55]
	v_mfma_f32_16x16x32_bf16 v[36:39], v[128:131], v[202:205], v[36:39]
	v_mfma_f32_16x16x32_bf16 v[36:39], v[132:135], v[206:209], v[36:39]
	v_mfma_f32_16x16x32_bf16 v[20:23], v[128:131], v[210:213], v[20:23]
	v_mfma_f32_16x16x32_bf16 v[20:23], v[132:135], v[214:217], v[20:23]
	v_mfma_f32_16x16x32_bf16 v[56:59], v[136:139], v[160:163], v[56:59]
	v_mfma_f32_16x16x32_bf16 v[56:59], v[140:143], v[164:167], v[56:59]
	v_mfma_f32_16x16x32_bf16 v[44:47], v[136:139], v[194:197], v[44:47]
	v_mfma_f32_16x16x32_bf16 v[44:47], v[140:143], v[198:201], v[44:47]
	v_mfma_f32_16x16x32_bf16 v[28:31], v[136:139], v[202:205], v[28:31]
	v_mfma_f32_16x16x32_bf16 v[28:31], v[140:143], v[206:209], v[28:31]
	v_mfma_f32_16x16x32_bf16 v[12:15], v[136:139], v[210:213], v[12:15]
	v_mfma_f32_16x16x32_bf16 v[12:15], v[140:143], v[214:217], v[12:15]
	s_setprio 0
	s_setprio 1
	v_mfma_f32_16x16x32_bf16 v[48:51], v[144:147], v[160:163], v[48:51]
	v_mfma_f32_16x16x32_bf16 v[48:51], v[148:151], v[164:167], v[48:51]
	v_mfma_f32_16x16x32_bf16 v[32:35], v[144:147], v[194:197], v[32:35]
	v_mfma_f32_16x16x32_bf16 v[32:35], v[148:151], v[198:201], v[32:35]
	v_mfma_f32_16x16x32_bf16 v[16:19], v[144:147], v[202:205], v[16:19]
	v_mfma_f32_16x16x32_bf16 v[16:19], v[148:151], v[206:209], v[16:19]
	v_mfma_f32_16x16x32_bf16 v[4:7], v[144:147], v[210:213], v[4:7]
	v_mfma_f32_16x16x32_bf16 v[4:7], v[148:151], v[214:217], v[4:7]
	v_mfma_f32_16x16x32_bf16 v[40:43], v[152:155], v[160:163], v[40:43]
	v_mfma_f32_16x16x32_bf16 v[40:43], v[156:159], v[164:167], v[40:43]
	v_mfma_f32_16x16x32_bf16 v[24:27], v[152:155], v[194:197], v[24:27]
	v_mfma_f32_16x16x32_bf16 v[24:27], v[156:159], v[198:201], v[24:27]
	v_mfma_f32_16x16x32_bf16 v[8:11], v[152:155], v[202:205], v[8:11]
	v_mfma_f32_16x16x32_bf16 v[8:11], v[156:159], v[206:209], v[8:11]
	v_mfma_f32_16x16x32_bf16 v[0:3], v[152:155], v[210:213], v[0:3]
	v_mfma_f32_16x16x32_bf16 v[0:3], v[156:159], v[214:217], v[0:3]
	s_setprio 0
	s_barrier
; #define PG8_STAGE(bufoff, gbase, voff) do { _Pragma("unroll") for (int _i = 0; _i < 2; ++_i) \
;         __builtin_amdgcn_global_load_lds((const unsigned*)((const char*)(gbase) + (voff)[_i]), (PG8_LAS unsigned*)(lds + (bufoff) + ldsw + _i * 8192), 16, 0, 0); } while (0)
; #define PG8_LDA(dst, b, h) do { _Pragma("unroll") for (int m = 0; m < 4; ++m) _Pragma("unroll") for (int k = 0; k < 2; ++k) dst[m][k] = *(const PG8_LAS bf16x8*)(lds + PG8_SA(b, h) + aoff + m * 2048 + k * 1024); } while (0)
; #define PG8_LDB(dst, b, h) do { _Pragma("unroll") for (int n = 0; n < 2; ++n) _Pragma("unroll") for (int k = 0; k < 2; ++k) dst[n][k] = *(const PG8_LAS bf16x8*)(lds + PG8_SB(b, h) + boff + n * 2048 + k * 1024); } while (0)
; #define PG8_MMA(ai, bj, At, Bt) do { __builtin_amdgcn_s_setprio(1); _Pragma("unroll") for (int m = 0; m < 4; ++m) _Pragma("unroll") for (int n = 0; n < 2; ++n) _Pragma("unroll") for (int k = 0; k < 2; ++k) \
;         acc[ai][bj][m][n] = __builtin_amdgcn_mfma_f32_16x16x32_bf16(Bt[n][k], At[m][k], acc[ai][bj][m][n], 0, 0, 0); __builtin_amdgcn_s_setprio(0); } while (0)
; #define PG8_WAIT_V(n) asm volatile("s_waitcnt vmcnt(" #n ")" ::: "memory")
; #define PG8_WAIT_L(n) asm volatile("s_waitcnt lgkmcnt(" #n ")" ::: "memory")
; #define PG8_BAR __builtin_amdgcn_s_barrier()
; #define PG8_SCHED __builtin_amdgcn_sched_barrier(0)
;     ...
;             PG8_LDB(B0, 1, 0); PG8_LDB(B1, 1, 1); PG8_SCHED; PG8_LDA(At, 1, 0); PG8_STAGE(PG8_SA(0, 1), a2 + hstep, voffA);
;             PG8_WAIT_V(8); PG8_WAIT_L(0); PG8_BAR; PG8_MMA(0, 0, At, B0); PG8_MMA(0, 1, At, B1); PG8_BAR; PG8_SCHED;
;             PG8_LDA(At, 1, 1); PG8_STAGE(PG8_SB(1, 0), b3, voffB); PG8_STAGE(PG8_SB(1, 1), b3 + hstep, voffB); PG8_STAGE(PG8_SA(1, 0), a3, voffA);
;             PG8_WAIT_V(8); PG8_WAIT_L(0); PG8_BAR; PG8_MMA(1, 0, At, B0); PG8_MMA(1, 1, At, B1); PG8_BAR; PG8_SCHED;
	s_add_i32 s12, 0, 0x18000
	s_add_i32 s13, 0, 0x1c000
	v_add_u32_e32 v140, s12, v233
	v_add_u32_e32 v156, s13, v233
	ds_read_b128 v[128:131], v140
	ds_read_b128 v[132:135], v140 offset:1024
	ds_read_b128 v[136:139], v140 offset:2048
	ds_read_b128 v[140:143], v140 offset:3072
	ds_read_b128 v[144:147], v156
	ds_read_b128 v[148:151], v156 offset:1024
	ds_read_b128 v[152:155], v156 offset:2048
	ds_read_b128 v[156:159], v156 offset:3072
	s_add_u32 s42, s82, 0x160000
	s_addc_u32 s43, s83, 0
	s_mov_b32 m0, s18
	ds_read_b128 v[160:163], v236 offset:32768
	ds_read_b128 v[164:167], v236 offset:33792
	ds_read_b128 v[194:197], v236 offset:34816
	ds_read_b128 v[198:201], v236 offset:35840
	ds_read_b128 v[202:205], v236 offset:36864
	ds_read_b128 v[206:209], v236 offset:37888
	ds_read_b128 v[210:213], v236 offset:38912
	ds_read_b128 v[214:217], v236 offset:39936
	global_load_lds_dwordx4 v182, s[42:43]
	s_mov_b32 m0, s19
	s_nop 0
	global_load_lds_dwordx4 v186, s[42:43]
	s_waitcnt vmcnt(8)
	s_waitcnt lgkmcnt(0)
	s_barrier
	s_setprio 1
	s_waitcnt lgkmcnt(0)
	v_mfma_f32_16x16x32_bf16 v[124:127], v[128:131], v[160:163], v[124:127]
	v_mfma_f32_16x16x32_bf16 v[124:127], v[132:135], v[164:167], v[124:127]
	v_mfma_f32_16x16x32_bf16 v[108:111], v[128:131], v[194:197], v[108:111]
	v_mfma_f32_16x16x32_bf16 v[108:111], v[132:135], v[198:201], v[108:111]
	v_mfma_f32_16x16x32_bf16 v[100:103], v[128:131], v[202:205], v[100:103]
	v_mfma_f32_16x16x32_bf16 v[100:103], v[132:135], v[206:209], v[100:103]
	v_mfma_f32_16x16x32_bf16 v[84:87], v[128:131], v[210:213], v[84:87]
	v_mfma_f32_16x16x32_bf16 v[84:87], v[132:135], v[214:217], v[84:87]
	v_mfma_f32_16x16x32_bf16 v[120:123], v[136:139], v[160:163], v[120:123]
	v_mfma_f32_16x16x32_bf16 v[120:123], v[140:143], v[164:167], v[120:123]
	v_mfma_f32_16x16x32_bf16 v[104:107], v[136:139], v[194:197], v[104:107]
	v_mfma_f32_16x16x32_bf16 v[104:107], v[140:143], v[198:201], v[104:107]
	v_mfma_f32_16x16x32_bf16 v[92:95], v[136:139], v[202:205], v[92:95]
	v_mfma_f32_16x16x32_bf16 v[92:95], v[140:143], v[206:209], v[92:95]
	v_mfma_f32_16x16x32_bf16 v[76:79], v[136:139], v[210:213], v[76:79]
	v_mfma_f32_16x16x32_bf16 v[76:79], v[140:143], v[214:217], v[76:79]
	s_setprio 0
	s_setprio 1
	v_mfma_f32_16x16x32_bf16 v[116:119], v[144:147], v[160:163], v[116:119]
	v_mfma_f32_16x16x32_bf16 v[116:119], v[148:151], v[164:167], v[116:119]
	v_mfma_f32_16x16x32_bf16 v[96:99], v[144:147], v[194:197], v[96:99]
	v_mfma_f32_16x16x32_bf16 v[96:99], v[148:151], v[198:201], v[96:99]
	v_mfma_f32_16x16x32_bf16 v[80:83], v[144:147], v[202:205], v[80:83]
	v_mfma_f32_16x16x32_bf16 v[80:83], v[148:151], v[206:209], v[80:83]
	v_mfma_f32_16x16x32_bf16 v[68:71], v[144:147], v[210:213], v[68:71]
	v_mfma_f32_16x16x32_bf16 v[68:71], v[148:151], v[214:217], v[68:71]
	v_mfma_f32_16x16x32_bf16 v[112:115], v[152:155], v[160:163], v[112:115]
	v_mfma_f32_16x16x32_bf16 v[112:115], v[156:159], v[164:167], v[112:115]
	v_mfma_f32_16x16x32_bf16 v[88:91], v[152:155], v[194:197], v[88:91]
	v_mfma_f32_16x16x32_bf16 v[88:91], v[156:159], v[198:201], v[88:91]
	v_mfma_f32_16x16x32_bf16 v[72:75], v[152:155], v[202:205], v[72:75]
	v_mfma_f32_16x16x32_bf16 v[72:75], v[156:159], v[206:209], v[72:75]
	v_mfma_f32_16x16x32_bf16 v[64:67], v[152:155], v[210:213], v[64:67]
	v_mfma_f32_16x16x32_bf16 v[64:67], v[156:159], v[214:217], v[64:67]
	s_setprio 0
	s_barrier
	s_add_i32 s12, s12, s8
	s_mov_b32 m0, s12
	ds_read_b128 v[160:163], v236 offset:49152
	ds_read_b128 v[164:167], v236 offset:50176
	ds_read_b128 v[194:197], v236 offset:51200
	ds_read_b128 v[198:201], v236 offset:52224
	ds_read_b128 v[202:205], v236 offset:53248
	ds_read_b128 v[206:209], v236 offset:54272
	ds_read_b128 v[210:213], v236 offset:55296
	ds_read_b128 v[214:217], v236 offset:56320
	s_add_u32 s100, s80, s38
	s_addc_u32 s101, s81, s39
	global_load_lds_dwordx4 v184, s[100:101]
	s_add_i32 m0, s12, 0x2000
	s_add_u32 s42, s80, 0x15ff80
	s_addc_u32 s43, s81, 0
	s_add_i32 s12, s13, s8
	global_load_lds_dwordx4 v188, s[100:101]
	s_mov_b32 m0, s12
	s_nop 0
	global_load_lds_dwordx4 v184, s[42:43]
	s_add_i32 m0, s12, 0x2000
	s_nop 0
	global_load_lds_dwordx4 v188, s[42:43]
	s_mov_b32 m0, s20
	s_nop 0
	s_add_u32 s100, s82, s38
	s_addc_u32 s101, s83, s39
	global_load_lds_dwordx4 v182, s[100:101]
	s_mov_b32 m0, s21
	s_nop 0
	global_load_lds_dwordx4 v186, s[100:101]
	s_waitcnt vmcnt(8)
	s_waitcnt lgkmcnt(0)
	s_barrier
	s_setprio 1
	s_waitcnt lgkmcnt(0)
	v_mfma_f32_16x16x32_bf16 v[60:63], v[128:131], v[160:163], v[60:63]
	v_mfma_f32_16x16x32_bf16 v[60:63], v[132:135], v[164:167], v[60:63]
	v_mfma_f32_16x16x32_bf16 v[52:55], v[128:131], v[194:197], v[52:55]
	v_mfma_f32_16x16x32_bf16 v[52:55], v[132:135], v[198:201], v[52:55]
	v_mfma_f32_16x16x32_bf16 v[36:39], v[128:131], v[202:205], v[36:39]
	v_mfma_f32_16x16x32_bf16 v[36:39], v[132:135], v[206:209], v[36:39]
	v_mfma_f32_16x16x32_bf16 v[20:23], v[128:131], v[210:213], v[20:23]
	v_mfma_f32_16x16x32_bf16 v[20:23], v[132:135], v[214:217], v[20:23]
	v_mfma_f32_16x16x32_bf16 v[56:59], v[136:139], v[160:163], v[56:59]
	v_mfma_f32_16x16x32_bf16 v[56:59], v[140:143], v[164:167], v[56:59]
	v_mfma_f32_16x16x32_bf16 v[44:47], v[136:139], v[194:197], v[44:47]
	v_mfma_f32_16x16x32_bf16 v[44:47], v[140:143], v[198:201], v[44:47]
	v_mfma_f32_16x16x32_bf16 v[28:31], v[136:139], v[202:205], v[28:31]
	v_mfma_f32_16x16x32_bf16 v[28:31], v[140:143], v[206:209], v[28:31]
	v_mfma_f32_16x16x32_bf16 v[12:15], v[136:139], v[210:213], v[12:15]
	v_mfma_f32_16x16x32_bf16 v[12:15], v[140:143], v[214:217], v[12:15]
	s_setprio 0
	s_setprio 1
	v_mfma_f32_16x16x32_bf16 v[48:51], v[144:147], v[160:163], v[48:51]
	v_mfma_f32_16x16x32_bf16 v[48:51], v[148:151], v[164:167], v[48:51]
	v_mfma_f32_16x16x32_bf16 v[32:35], v[144:147], v[194:197], v[32:35]
	v_mfma_f32_16x16x32_bf16 v[32:35], v[148:151], v[198:201], v[32:35]
	v_mfma_f32_16x16x32_bf16 v[16:19], v[144:147], v[202:205], v[16:19]
	v_mfma_f32_16x16x32_bf16 v[16:19], v[148:151], v[206:209], v[16:19]
	v_mfma_f32_16x16x32_bf16 v[4:7], v[144:147], v[210:213], v[4:7]
	v_mfma_f32_16x16x32_bf16 v[4:7], v[148:151], v[214:217], v[4:7]
	v_mfma_f32_16x16x32_bf16 v[40:43], v[152:155], v[160:163], v[40:43]
	v_mfma_f32_16x16x32_bf16 v[40:43], v[156:159], v[164:167], v[40:43]
	v_mfma_f32_16x16x32_bf16 v[24:27], v[152:155], v[194:197], v[24:27]
	v_mfma_f32_16x16x32_bf16 v[24:27], v[156:159], v[198:201], v[24:27]
	v_mfma_f32_16x16x32_bf16 v[8:11], v[152:155], v[202:205], v[8:11]
	v_mfma_f32_16x16x32_bf16 v[8:11], v[156:159], v[206:209], v[8:11]
	v_mfma_f32_16x16x32_bf16 v[0:3], v[152:155], v[210:213], v[0:3]
	v_mfma_f32_16x16x32_bf16 v[0:3], v[156:159], v[214:217], v[0:3]
	s_setprio 0
	s_barrier
	s_add_i32 s3, s3, 2
	s_add_u32 s2, s2, 0xffffff00
	s_addc_u32 s30, s30, -1
	s_cmpk_gt_u32 s3, 0x55
	s_mov_b64 s[76:77], s[78:79]
	s_cbranch_scc0 .LBB0_343
	v_mov_b64_e32 v[234:235], 0x7f
	v_mov_b64_e32 v[174:175], 0x80
	v_mov_b64_e32 v[226:227], 0xb00
	s_and_b64 vcc, exec, s[72:73]
	s_cbranch_vccz .LBB0_346
	s_barrier

; #define PG8_STAGE(bufoff, gbase, voff) do { _Pragma("unroll") for (int _i = 0; _i < 2; ++_i) \
;         __builtin_amdgcn_global_load_lds((const unsigned*)((const char*)(gbase) + (voff)[_i]), (PG8_LAS unsigned*)(lds + (bufoff) + ldsw + _i * 8192), 16, 0, 0); } while (0)
; #define PG8_LDA(dst, b, h) do { _Pragma("unroll") for (int m = 0; m < 4; ++m) _Pragma("unroll") for (int k = 0; k < 2; ++k) dst[m][k] = *(const PG8_LAS bf16x8*)(lds + PG8_SA(b, h) + aoff + m * 2048 + k * 1024); } while (0)
; #define PG8_LDB(dst, b, h) do { _Pragma("unroll") for (int n = 0; n < 2; ++n) _Pragma("unroll") for (int k = 0; k < 2; ++k) dst[n][k] = *(const PG8_LAS bf16x8*)(lds + PG8_SB(b, h) + boff + n * 2048 + k * 1024); } while (0)
; #define PG8_MMA(ai, bj, At, Bt) do { __builtin_amdgcn_s_setprio(1); _Pragma("unroll") for (int m = 0; m < 4; ++m) _Pragma("unroll") for (int n = 0; n < 2; ++n) _Pragma("unroll") for (int k = 0; k < 2; ++k) \
;         acc[ai][bj][m][n] = __builtin_amdgcn_mfma_f32_16x16x32_bf16(Bt[n][k], At[m][k], acc[ai][bj][m][n], 0, 0, 0); __builtin_amdgcn_s_setprio(0); } while (0)
; #define PG8_WAIT_V(n) asm volatile("s_waitcnt vmcnt(" #n ")" ::: "memory")
; #define PG8_WAIT_L(n) asm volatile("s_waitcnt lgkmcnt(" #n ")" ::: "memory")
; #define PG8_BAR __builtin_amdgcn_s_barrier()
; #define PG8_SCHED __builtin_amdgcn_sched_barrier(0)
;     ...
;             const bool last = (t == nt - 2);
;             const char* a1 = PG8_KADV(cA, (size_t)(t + 1) * kstep);
;             const char* a2 = last ? nA : PG8_KADV(cA, (size_t)(t + 2) * kstep); const char* b2 = last ? nB : PG8_KADV(cB, (size_t)(t + 2) * kstep);
;             const char* a3 = PG8_KADV(a2, kstep); const char* b3 = PG8_KADV(b2, kstep);
;             if (last && has_next) S.a_ready(nxt);
;             if constexpr (SP2) {
;             PG8_LDB(B0, 0, 0); PG8_LDB(B1, 0, 1); PG8_SCHED; PG8_LDA(At, 0, 0); PG8_STAGE(PG8_SA(1, 1), a1 + hstep, voffA);
;             PG8_WAIT_V(8); PG8_WAIT_L(0); PG8_BAR; PG8_MMA(0, 0, At, B0); PG8_MMA(0, 1, At, B1); PG8_BAR; PG8_SCHED;
;             PG8_LDA(At, 0, 1); PG8_STAGE(PG8_SB(0, 0), b2, voffB); PG8_STAGE(PG8_SB(0, 1), b2 + hstep, voffB); PG8_STAGE(PG8_SA(0, 0), a2, voffA);
;             PG8_WAIT_V(8); PG8_WAIT_L(0); PG8_BAR; PG8_MMA(1, 0, At, B0); PG8_MMA(1, 1, At, B1); PG8_BAR; PG8_SCHED;
.LBB0_490:
	s_add_u32 s3, s86, 0xfff80080
	s_addc_u32 s12, s87, -1
	s_add_i32 s13, 0, 0x10000
	s_cmp_eq_u32 s2, 28
	s_cselect_b32 s91, s23, s12
	s_cselect_b32 s90, s25, s3
	s_cselect_b32 s89, s28, s40
	s_cselect_b32 s88, s30, s33
	s_add_i32 s3, 0, 0x14000
	v_add_u32_e32 v156, s13, v141
	v_add_u32_e32 v168, s3, v141
	ds_read_b128 v[144:147], v156
	ds_read_b128 v[148:151], v156 offset:1024
	ds_read_b128 v[152:155], v156 offset:2048
	ds_read_b128 v[156:159], v156 offset:3072
	ds_read_b128 v[160:163], v168
	ds_read_b128 v[164:167], v168 offset:1024
	ds_read_b128 v[170:173], v168 offset:2048
	ds_read_b128 v[178:181], v168 offset:3072
	s_add_i32 m0, s9, 0xc000
	ds_read_b128 v[182:185], v143
	ds_read_b128 v[186:189], v143 offset:1024
	ds_read_b128 v[190:193], v143 offset:2048
	ds_read_b128 v[194:197], v143 offset:3072
	ds_read_b128 v[198:201], v143 offset:4096
	ds_read_b128 v[202:205], v143 offset:5120
	ds_read_b128 v[206:209], v143 offset:6144
	ds_read_b128 v[210:213], v143 offset:7168
	global_load_lds_dwordx4 v136, s[86:87]
	s_add_i32 m0, s9, 0xe000
	s_nop 0
	global_load_lds_dwordx4 v138, s[86:87]
	s_waitcnt vmcnt(8)
	s_waitcnt lgkmcnt(0)
	s_barrier
	s_setprio 1
	s_waitcnt lgkmcnt(0)
	v_mfma_f32_16x16x32_bf16 v[124:127], v[144:147], v[182:185], v[124:127]
	v_mfma_f32_16x16x32_bf16 v[124:127], v[148:151], v[186:189], v[124:127]
	v_mfma_f32_16x16x32_bf16 v[116:119], v[144:147], v[190:193], v[116:119]
	v_mfma_f32_16x16x32_bf16 v[116:119], v[148:151], v[194:197], v[116:119]
	v_mfma_f32_16x16x32_bf16 v[100:103], v[144:147], v[198:201], v[100:103]
	v_mfma_f32_16x16x32_bf16 v[100:103], v[148:151], v[202:205], v[100:103]
	v_mfma_f32_16x16x32_bf16 v[84:87], v[144:147], v[206:209], v[84:87]
	v_mfma_f32_16x16x32_bf16 v[84:87], v[148:151], v[210:213], v[84:87]
	v_mfma_f32_16x16x32_bf16 v[120:123], v[152:155], v[182:185], v[120:123]
	v_mfma_f32_16x16x32_bf16 v[120:123], v[156:159], v[186:189], v[120:123]
	v_mfma_f32_16x16x32_bf16 v[112:115], v[152:155], v[190:193], v[112:115]
	v_mfma_f32_16x16x32_bf16 v[112:115], v[156:159], v[194:197], v[112:115]
	v_mfma_f32_16x16x32_bf16 v[96:99], v[152:155], v[198:201], v[96:99]
	v_mfma_f32_16x16x32_bf16 v[96:99], v[156:159], v[202:205], v[96:99]
	v_mfma_f32_16x16x32_bf16 v[80:83], v[152:155], v[206:209], v[80:83]
	v_mfma_f32_16x16x32_bf16 v[80:83], v[156:159], v[210:213], v[80:83]
	s_setprio 0
	s_setprio 1
	v_mfma_f32_16x16x32_bf16 v[108:111], v[160:163], v[182:185], v[108:111]
	v_mfma_f32_16x16x32_bf16 v[108:111], v[164:167], v[186:189], v[108:111]
	v_mfma_f32_16x16x32_bf16 v[92:95], v[160:163], v[190:193], v[92:95]
	v_mfma_f32_16x16x32_bf16 v[92:95], v[164:167], v[194:197], v[92:95]
	v_mfma_f32_16x16x32_bf16 v[76:79], v[160:163], v[198:201], v[76:79]
	v_mfma_f32_16x16x32_bf16 v[76:79], v[164:167], v[202:205], v[76:79]
	v_mfma_f32_16x16x32_bf16 v[68:71], v[160:163], v[206:209], v[68:71]
	v_mfma_f32_16x16x32_bf16 v[68:71], v[164:167], v[210:213], v[68:71]
	v_mfma_f32_16x16x32_bf16 v[104:107], v[170:173], v[182:185], v[104:107]
	v_mfma_f32_16x16x32_bf16 v[104:107], v[178:181], v[186:189], v[104:107]
	v_mfma_f32_16x16x32_bf16 v[88:91], v[170:173], v[190:193], v[88:91]
	v_mfma_f32_16x16x32_bf16 v[88:91], v[178:181], v[194:197], v[88:91]
	v_mfma_f32_16x16x32_bf16 v[72:75], v[170:173], v[198:201], v[72:75]
	v_mfma_f32_16x16x32_bf16 v[72:75], v[178:181], v[202:205], v[72:75]
	v_mfma_f32_16x16x32_bf16 v[64:67], v[170:173], v[206:209], v[64:67]
	v_mfma_f32_16x16x32_bf16 v[64:67], v[178:181], v[210:213], v[64:67]
	s_setprio 0
	s_barrier
	s_add_i32 s12, s13, s8
	s_mov_b32 m0, s12
	ds_read_b128 v[182:185], v143 offset:16384
	ds_read_b128 v[186:189], v143 offset:17408
	ds_read_b128 v[190:193], v143 offset:18432
	ds_read_b128 v[194:197], v143 offset:19456
	ds_read_b128 v[198:201], v143 offset:20480
	ds_read_b128 v[202:205], v143 offset:21504
	ds_read_b128 v[206:209], v143 offset:22528
	ds_read_b128 v[210:213], v143 offset:23552
	global_load_lds_dwordx4 v130, s[88:89]
	s_add_i32 m0, s12, 0x2000
	s_add_u32 s42, s88, 0x80000
	s_addc_u32 s43, s89, 0
	s_add_i32 s3, s3, s8
	global_load_lds_dwordx4 v134, s[88:89]
	s_mov_b32 m0, s3
	s_nop 0
	global_load_lds_dwordx4 v130, s[42:43]
	s_add_i32 m0, s3, 0x2000
	s_nop 0
	global_load_lds_dwordx4 v134, s[42:43]
	s_mov_b32 m0, s9
	s_nop 0
	global_load_lds_dwordx4 v128, s[90:91]
	s_mov_b32 m0, s10
	s_nop 0
	global_load_lds_dwordx4 v132, s[90:91]
	s_waitcnt vmcnt(8)
	s_waitcnt lgkmcnt(0)
	s_barrier
	s_setprio 1
	s_waitcnt lgkmcnt(0)
	v_mfma_f32_16x16x32_bf16 v[60:63], v[144:147], v[182:185], v[60:63]
	v_mfma_f32_16x16x32_bf16 v[60:63], v[148:151], v[186:189], v[60:63]
	v_mfma_f32_16x16x32_bf16 v[52:55], v[144:147], v[190:193], v[52:55]
	v_mfma_f32_16x16x32_bf16 v[52:55], v[148:151], v[194:197], v[52:55]
	v_mfma_f32_16x16x32_bf16 v[36:39], v[144:147], v[198:201], v[36:39]
	v_mfma_f32_16x16x32_bf16 v[36:39], v[148:151], v[202:205], v[36:39]
	v_mfma_f32_16x16x32_bf16 v[20:23], v[144:147], v[206:209], v[20:23]
	v_mfma_f32_16x16x32_bf16 v[20:23], v[148:151], v[210:213], v[20:23]
	v_mfma_f32_16x16x32_bf16 v[56:59], v[152:155], v[182:185], v[56:59]
	v_mfma_f32_16x16x32_bf16 v[56:59], v[156:159], v[186:189], v[56:59]
	v_mfma_f32_16x16x32_bf16 v[48:51], v[152:155], v[190:193], v[48:51]
	v_mfma_f32_16x16x32_bf16 v[48:51], v[156:159], v[194:197], v[48:51]
	v_mfma_f32_16x16x32_bf16 v[32:35], v[152:155], v[198:201], v[32:35]
	v_mfma_f32_16x16x32_bf16 v[32:35], v[156:159], v[202:205], v[32:35]
	v_mfma_f32_16x16x32_bf16 v[16:19], v[152:155], v[206:209], v[16:19]
	v_mfma_f32_16x16x32_bf16 v[16:19], v[156:159], v[210:213], v[16:19]
	s_setprio 0
	s_setprio 1
	v_mfma_f32_16x16x32_bf16 v[44:47], v[160:163], v[182:185], v[44:47]
	v_mfma_f32_16x16x32_bf16 v[44:47], v[164:167], v[186:189], v[44:47]
	v_mfma_f32_16x16x32_bf16 v[28:31], v[160:163], v[190:193], v[28:31]
	v_mfma_f32_16x16x32_bf16 v[28:31], v[164:167], v[194:197], v[28:31]
	v_mfma_f32_16x16x32_bf16 v[12:15], v[160:163], v[198:201], v[12:15]
	v_mfma_f32_16x16x32_bf16 v[12:15], v[164:167], v[202:205], v[12:15]
	v_mfma_f32_16x16x32_bf16 v[4:7], v[160:163], v[206:209], v[4:7]
	v_mfma_f32_16x16x32_bf16 v[4:7], v[164:167], v[210:213], v[4:7]
	v_mfma_f32_16x16x32_bf16 v[40:43], v[170:173], v[182:185], v[40:43]
	v_mfma_f32_16x16x32_bf16 v[40:43], v[178:181], v[186:189], v[40:43]
	v_mfma_f32_16x16x32_bf16 v[24:27], v[170:173], v[190:193], v[24:27]
	v_mfma_f32_16x16x32_bf16 v[24:27], v[178:181], v[194:197], v[24:27]
	v_mfma_f32_16x16x32_bf16 v[8:11], v[170:173], v[198:201], v[8:11]
	v_mfma_f32_16x16x32_bf16 v[8:11], v[178:181], v[202:205], v[8:11]
	v_mfma_f32_16x16x32_bf16 v[0:3], v[170:173], v[206:209], v[0:3]
	v_mfma_f32_16x16x32_bf16 v[0:3], v[178:181], v[210:213], v[0:3]
	s_setprio 0
	s_barrier
; #define PG8_STAGE(bufoff, gbase, voff) do { _Pragma("unroll") for (int _i = 0; _i < 2; ++_i) \
;         __builtin_amdgcn_global_load_lds((const unsigned*)((const char*)(gbase) + (voff)[_i]), (PG8_LAS unsigned*)(lds + (bufoff) + ldsw + _i * 8192), 16, 0, 0); } while (0)
; #define PG8_LDA(dst, b, h) do { _Pragma("unroll") for (int m = 0; m < 4; ++m) _Pragma("unroll") for (int k = 0; k < 2; ++k) dst[m][k] = *(const PG8_LAS bf16x8*)(lds + PG8_SA(b, h) + aoff + m * 2048 + k * 1024); } while (0)
; #define PG8_LDB(dst, b, h) do { _Pragma("unroll") for (int n = 0; n < 2; ++n) _Pragma("unroll") for (int k = 0; k < 2; ++k) dst[n][k] = *(const PG8_LAS bf16x8*)(lds + PG8_SB(b, h) + boff + n * 2048 + k * 1024); } while (0)
; #define PG8_MMA(ai, bj, At, Bt) do { __builtin_amdgcn_s_setprio(1); _Pragma("unroll") for (int m = 0; m < 4; ++m) _Pragma("unroll") for (int n = 0; n < 2; ++n) _Pragma("unroll") for (int k = 0; k < 2; ++k) \
;         acc[ai][bj][m][n] = __builtin_amdgcn_mfma_f32_16x16x32_bf16(Bt[n][k], At[m][k], acc[ai][bj][m][n], 0, 0, 0); __builtin_amdgcn_s_setprio(0); } while (0)
; #define PG8_WAIT_V(n) asm volatile("s_waitcnt vmcnt(" #n ")" ::: "memory")
; #define PG8_WAIT_L(n) asm volatile("s_waitcnt lgkmcnt(" #n ")" ::: "memory")
; #define PG8_BAR __builtin_amdgcn_s_barrier()
; #define PG8_SCHED __builtin_amdgcn_sched_barrier(0)
;     ...
;             PG8_LDB(B0, 1, 0); PG8_LDB(B1, 1, 1); PG8_SCHED; PG8_LDA(At, 1, 0); PG8_STAGE(PG8_SA(0, 1), a2 + hstep, voffA);
;             PG8_WAIT_V(8); PG8_WAIT_L(0); PG8_BAR; PG8_MMA(0, 0, At, B0); PG8_MMA(0, 1, At, B1); PG8_BAR; PG8_SCHED;
;             PG8_LDA(At, 1, 1); PG8_STAGE(PG8_SB(1, 0), b3, voffB); PG8_STAGE(PG8_SB(1, 1), b3 + hstep, voffB); PG8_STAGE(PG8_SA(1, 0), a3, voffA);
;             PG8_WAIT_V(8); PG8_WAIT_L(0); PG8_BAR; PG8_MMA(1, 0, At, B0); PG8_MMA(1, 1, At, B1); PG8_BAR; PG8_SCHED;
	s_add_i32 s3, 0, 0x18000
	s_add_i32 s12, 0, 0x1c000
	v_add_u32_e32 v156, s3, v141
	v_add_u32_e32 v168, s12, v141
	ds_read_b128 v[144:147], v156
	ds_read_b128 v[148:151], v156 offset:1024
	ds_read_b128 v[152:155], v156 offset:2048
	ds_read_b128 v[156:159], v156 offset:3072
	ds_read_b128 v[160:163], v168
	ds_read_b128 v[164:167], v168 offset:1024
	ds_read_b128 v[170:173], v168 offset:2048
	ds_read_b128 v[178:181], v168 offset:3072
	s_add_u32 s42, s90, 0x80000
	s_addc_u32 s43, s91, 0
	s_mov_b32 m0, s18
	ds_read_b128 v[182:185], v143 offset:32768
	ds_read_b128 v[186:189], v143 offset:33792
	ds_read_b128 v[190:193], v143 offset:34816
	ds_read_b128 v[194:197], v143 offset:35840
	ds_read_b128 v[198:201], v143 offset:36864
	ds_read_b128 v[202:205], v143 offset:37888
	ds_read_b128 v[206:209], v143 offset:38912
	ds_read_b128 v[210:213], v143 offset:39936
	global_load_lds_dwordx4 v128, s[42:43]
	s_mov_b32 m0, s19
	s_nop 0
	global_load_lds_dwordx4 v132, s[42:43]
	s_waitcnt vmcnt(8)
	s_waitcnt lgkmcnt(0)
	s_barrier
	s_setprio 1
	s_waitcnt lgkmcnt(0)
	v_mfma_f32_16x16x32_bf16 v[124:127], v[144:147], v[182:185], v[124:127]
	v_mfma_f32_16x16x32_bf16 v[124:127], v[148:151], v[186:189], v[124:127]
	v_mfma_f32_16x16x32_bf16 v[116:119], v[144:147], v[190:193], v[116:119]
	v_mfma_f32_16x16x32_bf16 v[116:119], v[148:151], v[194:197], v[116:119]
	v_mfma_f32_16x16x32_bf16 v[100:103], v[144:147], v[198:201], v[100:103]
	v_mfma_f32_16x16x32_bf16 v[100:103], v[148:151], v[202:205], v[100:103]
	v_mfma_f32_16x16x32_bf16 v[84:87], v[144:147], v[206:209], v[84:87]
	v_mfma_f32_16x16x32_bf16 v[84:87], v[148:151], v[210:213], v[84:87]
	v_mfma_f32_16x16x32_bf16 v[120:123], v[152:155], v[182:185], v[120:123]
	v_mfma_f32_16x16x32_bf16 v[120:123], v[156:159], v[186:189], v[120:123]
	v_mfma_f32_16x16x32_bf16 v[112:115], v[152:155], v[190:193], v[112:115]
	v_mfma_f32_16x16x32_bf16 v[112:115], v[156:159], v[194:197], v[112:115]
	v_mfma_f32_16x16x32_bf16 v[96:99], v[152:155], v[198:201], v[96:99]
	v_mfma_f32_16x16x32_bf16 v[96:99], v[156:159], v[202:205], v[96:99]
	v_mfma_f32_16x16x32_bf16 v[80:83], v[152:155], v[206:209], v[80:83]
	v_mfma_f32_16x16x32_bf16 v[80:83], v[156:159], v[210:213], v[80:83]
	s_setprio 0
	s_setprio 1
	v_mfma_f32_16x16x32_bf16 v[108:111], v[160:163], v[182:185], v[108:111]
	v_mfma_f32_16x16x32_bf16 v[108:111], v[164:167], v[186:189], v[108:111]
	v_mfma_f32_16x16x32_bf16 v[92:95], v[160:163], v[190:193], v[92:95]
	v_mfma_f32_16x16x32_bf16 v[92:95], v[164:167], v[194:197], v[92:95]
	v_mfma_f32_16x16x32_bf16 v[76:79], v[160:163], v[198:201], v[76:79]
	v_mfma_f32_16x16x32_bf16 v[76:79], v[164:167], v[202:205], v[76:79]
	v_mfma_f32_16x16x32_bf16 v[68:71], v[160:163], v[206:209], v[68:71]
	v_mfma_f32_16x16x32_bf16 v[68:71], v[164:167], v[210:213], v[68:71]
	v_mfma_f32_16x16x32_bf16 v[104:107], v[170:173], v[182:185], v[104:107]
	v_mfma_f32_16x16x32_bf16 v[104:107], v[178:181], v[186:189], v[104:107]
	v_mfma_f32_16x16x32_bf16 v[88:91], v[170:173], v[190:193], v[88:91]
	v_mfma_f32_16x16x32_bf16 v[88:91], v[178:181], v[194:197], v[88:91]
	v_mfma_f32_16x16x32_bf16 v[72:75], v[170:173], v[198:201], v[72:75]
	v_mfma_f32_16x16x32_bf16 v[72:75], v[178:181], v[202:205], v[72:75]
	v_mfma_f32_16x16x32_bf16 v[64:67], v[170:173], v[206:209], v[64:67]
	v_mfma_f32_16x16x32_bf16 v[64:67], v[178:181], v[210:213], v[64:67]
	s_setprio 0
	s_barrier
	s_add_i32 s3, s3, s8
	s_mov_b32 m0, s3
	ds_read_b128 v[182:185], v143 offset:49152
	ds_read_b128 v[186:189], v143 offset:50176
	ds_read_b128 v[190:193], v143 offset:51200
	ds_read_b128 v[194:197], v143 offset:52224
	ds_read_b128 v[198:201], v143 offset:53248
	ds_read_b128 v[202:205], v143 offset:54272
	ds_read_b128 v[206:209], v143 offset:55296
	ds_read_b128 v[210:213], v143 offset:56320
	s_add_u32 s100, s88, s16
	s_addc_u32 s101, s89, s17
	global_load_lds_dwordx4 v130, s[100:101]
	s_add_i32 m0, s3, 0x2000
	s_add_u32 s42, s88, 0x80080
	s_addc_u32 s43, s89, 0
	s_add_i32 s3, s12, s8
	global_load_lds_dwordx4 v134, s[100:101]
	s_mov_b32 m0, s3
	s_nop 0
	global_load_lds_dwordx4 v130, s[42:43]
	s_add_i32 m0, s3, 0x2000
	s_nop 0
	global_load_lds_dwordx4 v134, s[42:43]
	s_mov_b32 m0, s20
	s_nop 0
	s_add_u32 s100, s90, s16
	s_addc_u32 s101, s91, s17
	global_load_lds_dwordx4 v128, s[100:101]
	s_mov_b32 m0, s21
	s_nop 0
	global_load_lds_dwordx4 v132, s[100:101]
	s_waitcnt vmcnt(8)
	s_waitcnt lgkmcnt(0)
	s_barrier
	s_setprio 1
	s_waitcnt lgkmcnt(0)
	v_mfma_f32_16x16x32_bf16 v[60:63], v[144:147], v[182:185], v[60:63]
	v_mfma_f32_16x16x32_bf16 v[60:63], v[148:151], v[186:189], v[60:63]
	v_mfma_f32_16x16x32_bf16 v[52:55], v[144:147], v[190:193], v[52:55]
	v_mfma_f32_16x16x32_bf16 v[52:55], v[148:151], v[194:197], v[52:55]
	v_mfma_f32_16x16x32_bf16 v[36:39], v[144:147], v[198:201], v[36:39]
	v_mfma_f32_16x16x32_bf16 v[36:39], v[148:151], v[202:205], v[36:39]
	v_mfma_f32_16x16x32_bf16 v[20:23], v[144:147], v[206:209], v[20:23]
	v_mfma_f32_16x16x32_bf16 v[20:23], v[148:151], v[210:213], v[20:23]
	v_mfma_f32_16x16x32_bf16 v[56:59], v[152:155], v[182:185], v[56:59]
	v_mfma_f32_16x16x32_bf16 v[56:59], v[156:159], v[186:189], v[56:59]
	v_mfma_f32_16x16x32_bf16 v[48:51], v[152:155], v[190:193], v[48:51]
	v_mfma_f32_16x16x32_bf16 v[48:51], v[156:159], v[194:197], v[48:51]
	v_mfma_f32_16x16x32_bf16 v[32:35], v[152:155], v[198:201], v[32:35]
	v_mfma_f32_16x16x32_bf16 v[32:35], v[156:159], v[202:205], v[32:35]
	v_mfma_f32_16x16x32_bf16 v[16:19], v[152:155], v[206:209], v[16:19]
	v_mfma_f32_16x16x32_bf16 v[16:19], v[156:159], v[210:213], v[16:19]
	s_setprio 0
	s_setprio 1
	v_mfma_f32_16x16x32_bf16 v[44:47], v[160:163], v[182:185], v[44:47]
	v_mfma_f32_16x16x32_bf16 v[44:47], v[164:167], v[186:189], v[44:47]
	v_mfma_f32_16x16x32_bf16 v[28:31], v[160:163], v[190:193], v[28:31]
	v_mfma_f32_16x16x32_bf16 v[28:31], v[164:167], v[194:197], v[28:31]
	v_mfma_f32_16x16x32_bf16 v[12:15], v[160:163], v[198:201], v[12:15]
	v_mfma_f32_16x16x32_bf16 v[12:15], v[164:167], v[202:205], v[12:15]
	v_mfma_f32_16x16x32_bf16 v[4:7], v[160:163], v[206:209], v[4:7]
	v_mfma_f32_16x16x32_bf16 v[4:7], v[164:167], v[210:213], v[4:7]
	v_mfma_f32_16x16x32_bf16 v[40:43], v[170:173], v[182:185], v[40:43]
	v_mfma_f32_16x16x32_bf16 v[40:43], v[178:181], v[186:189], v[40:43]
	v_mfma_f32_16x16x32_bf16 v[24:27], v[170:173], v[190:193], v[24:27]
	v_mfma_f32_16x16x32_bf16 v[24:27], v[178:181], v[194:197], v[24:27]
	v_mfma_f32_16x16x32_bf16 v[8:11], v[170:173], v[198:201], v[8:11]
	v_mfma_f32_16x16x32_bf16 v[8:11], v[178:181], v[202:205], v[8:11]
	v_mfma_f32_16x16x32_bf16 v[0:3], v[170:173], v[206:209], v[0:3]
	v_mfma_f32_16x16x32_bf16 v[0:3], v[178:181], v[210:213], v[0:3]
	s_setprio 0
	s_barrier
	s_add_i32 s2, s2, 2
	s_add_u32 s86, s86, 0x100
	s_addc_u32 s87, s87, 0
	s_add_u32 s33, s33, 0x100
	s_addc_u32 s40, s40, 0
	s_cmp_gt_u32 s2, 29
	s_cbranch_scc0 .LBB0_490
	s_and_b64 vcc, exec, s[74:75]
	s_cbranch_vccz .LBB0_493
	s_barrier

; #define PG8_STAGE(bufoff, gbase, voff) do { _Pragma("unroll") for (int _i = 0; _i < 2; ++_i) \
;         __builtin_amdgcn_global_load_lds((const unsigned*)((const char*)(gbase) + (voff)[_i]), (PG8_LAS unsigned*)(lds + (bufoff) + ldsw + _i * 8192), 16, 0, 0); } while (0)
; #define PG8_LDA(dst, b, h) do { _Pragma("unroll") for (int m = 0; m < 4; ++m) _Pragma("unroll") for (int k = 0; k < 2; ++k) dst[m][k] = *(const PG8_LAS bf16x8*)(lds + PG8_SA(b, h) + aoff + m * 2048 + k * 1024); } while (0)
; #define PG8_LDB(dst, b, h) do { _Pragma("unroll") for (int n = 0; n < 2; ++n) _Pragma("unroll") for (int k = 0; k < 2; ++k) dst[n][k] = *(const PG8_LAS bf16x8*)(lds + PG8_SB(b, h) + boff + n * 2048 + k * 1024); } while (0)
; #define PG8_MMA(ai, bj, At, Bt) do { __builtin_amdgcn_s_setprio(1); _Pragma("unroll") for (int m = 0; m < 4; ++m) _Pragma("unroll") for (int n = 0; n < 2; ++n) _Pragma("unroll") for (int k = 0; k < 2; ++k) \
;         acc[ai][bj][m][n] = __builtin_amdgcn_mfma_f32_16x16x32_bf16(Bt[n][k], At[m][k], acc[ai][bj][m][n], 0, 0, 0); __builtin_amdgcn_s_setprio(0); } while (0)
; #define PG8_WAIT_V(n) asm volatile("s_waitcnt vmcnt(" #n ")" ::: "memory")
; #define PG8_WAIT_L(n) asm volatile("s_waitcnt lgkmcnt(" #n ")" ::: "memory")
; #define PG8_BAR __builtin_amdgcn_s_barrier()
; #define PG8_SCHED __builtin_amdgcn_sched_barrier(0)
;     ...
;             const bool last = (t == nt - 2);
;             const char* a1 = PG8_KADV(cA, (size_t)(t + 1) * kstep);
;             const char* a2 = last ? nA : PG8_KADV(cA, (size_t)(t + 2) * kstep); const char* b2 = last ? nB : PG8_KADV(cB, (size_t)(t + 2) * kstep);
;             const char* a3 = PG8_KADV(a2, kstep); const char* b3 = PG8_KADV(b2, kstep);
;             if (last && has_next) S.a_ready(nxt);
;             if constexpr (SP2) {
;             PG8_LDB(B0, 0, 0); PG8_LDB(B1, 0, 1); PG8_SCHED; PG8_LDA(At, 0, 0); PG8_STAGE(PG8_SA(1, 1), a1 + hstep, voffA);
;             PG8_WAIT_V(8); PG8_WAIT_L(0); PG8_BAR; PG8_MMA(0, 0, At, B0); PG8_MMA(0, 1, At, B1); PG8_BAR; PG8_SCHED;
;             PG8_LDA(At, 0, 1); PG8_STAGE(PG8_SB(0, 0), b2, voffB); PG8_STAGE(PG8_SB(0, 1), b2 + hstep, voffB); PG8_STAGE(PG8_SA(0, 0), a2, voffA);
;             PG8_WAIT_V(8); PG8_WAIT_L(0); PG8_BAR; PG8_MMA(1, 0, At, B0); PG8_MMA(1, 1, At, B1); PG8_BAR; PG8_SCHED;
.LBB0_514:
	s_add_u32 s3, s86, 0xfff80080
	s_addc_u32 s12, s87, -1
	s_add_i32 s13, 0, 0x10000
	s_cmp_eq_u32 s2, 28
	s_cselect_b32 s91, s28, s12
	s_cselect_b32 s90, s30, s3
	s_cselect_b32 s89, s33, s43
	s_cselect_b32 s88, s40, s42
	s_add_i32 s3, 0, 0x14000
	v_add_u32_e32 v156, s13, v141
	v_add_u32_e32 v168, s3, v141
	ds_read_b128 v[144:147], v156
	ds_read_b128 v[148:151], v156 offset:1024
	ds_read_b128 v[152:155], v156 offset:2048
	ds_read_b128 v[156:159], v156 offset:3072
	ds_read_b128 v[160:163], v168
	ds_read_b128 v[164:167], v168 offset:1024
	ds_read_b128 v[170:173], v168 offset:2048
	ds_read_b128 v[178:181], v168 offset:3072
	s_add_i32 m0, s18, 0xc000
	ds_read_b128 v[182:185], v143
	ds_read_b128 v[186:189], v143 offset:1024
	ds_read_b128 v[190:193], v143 offset:2048
	ds_read_b128 v[194:197], v143 offset:3072
	ds_read_b128 v[198:201], v143 offset:4096
	ds_read_b128 v[202:205], v143 offset:5120
	ds_read_b128 v[206:209], v143 offset:6144
	ds_read_b128 v[210:213], v143 offset:7168
	global_load_lds_dwordx4 v136, s[86:87]
	s_add_i32 m0, s18, 0xe000
	s_nop 0
	global_load_lds_dwordx4 v138, s[86:87]
	s_waitcnt vmcnt(8)
	s_waitcnt lgkmcnt(0)
	s_barrier
	s_setprio 1
	s_waitcnt lgkmcnt(0)
	v_mfma_f32_16x16x32_bf16 v[124:127], v[144:147], v[182:185], v[124:127]
	v_mfma_f32_16x16x32_bf16 v[124:127], v[148:151], v[186:189], v[124:127]
	v_mfma_f32_16x16x32_bf16 v[116:119], v[144:147], v[190:193], v[116:119]
	v_mfma_f32_16x16x32_bf16 v[116:119], v[148:151], v[194:197], v[116:119]
	v_mfma_f32_16x16x32_bf16 v[100:103], v[144:147], v[198:201], v[100:103]
	v_mfma_f32_16x16x32_bf16 v[100:103], v[148:151], v[202:205], v[100:103]
	v_mfma_f32_16x16x32_bf16 v[84:87], v[144:147], v[206:209], v[84:87]
	v_mfma_f32_16x16x32_bf16 v[84:87], v[148:151], v[210:213], v[84:87]
	v_mfma_f32_16x16x32_bf16 v[120:123], v[152:155], v[182:185], v[120:123]
	v_mfma_f32_16x16x32_bf16 v[120:123], v[156:159], v[186:189], v[120:123]
	v_mfma_f32_16x16x32_bf16 v[112:115], v[152:155], v[190:193], v[112:115]
	v_mfma_f32_16x16x32_bf16 v[112:115], v[156:159], v[194:197], v[112:115]
	v_mfma_f32_16x16x32_bf16 v[96:99], v[152:155], v[198:201], v[96:99]
	v_mfma_f32_16x16x32_bf16 v[96:99], v[156:159], v[202:205], v[96:99]
	v_mfma_f32_16x16x32_bf16 v[80:83], v[152:155], v[206:209], v[80:83]
	v_mfma_f32_16x16x32_bf16 v[80:83], v[156:159], v[210:213], v[80:83]
	s_setprio 0
	s_setprio 1
	v_mfma_f32_16x16x32_bf16 v[108:111], v[160:163], v[182:185], v[108:111]
	v_mfma_f32_16x16x32_bf16 v[108:111], v[164:167], v[186:189], v[108:111]
	v_mfma_f32_16x16x32_bf16 v[92:95], v[160:163], v[190:193], v[92:95]
	v_mfma_f32_16x16x32_bf16 v[92:95], v[164:167], v[194:197], v[92:95]
	v_mfma_f32_16x16x32_bf16 v[76:79], v[160:163], v[198:201], v[76:79]
	v_mfma_f32_16x16x32_bf16 v[76:79], v[164:167], v[202:205], v[76:79]
	v_mfma_f32_16x16x32_bf16 v[68:71], v[160:163], v[206:209], v[68:71]
	v_mfma_f32_16x16x32_bf16 v[68:71], v[164:167], v[210:213], v[68:71]
	v_mfma_f32_16x16x32_bf16 v[104:107], v[170:173], v[182:185], v[104:107]
	v_mfma_f32_16x16x32_bf16 v[104:107], v[178:181], v[186:189], v[104:107]
	v_mfma_f32_16x16x32_bf16 v[88:91], v[170:173], v[190:193], v[88:91]
	v_mfma_f32_16x16x32_bf16 v[88:91], v[178:181], v[194:197], v[88:91]
	v_mfma_f32_16x16x32_bf16 v[72:75], v[170:173], v[198:201], v[72:75]
	v_mfma_f32_16x16x32_bf16 v[72:75], v[178:181], v[202:205], v[72:75]
	v_mfma_f32_16x16x32_bf16 v[64:67], v[170:173], v[206:209], v[64:67]
	v_mfma_f32_16x16x32_bf16 v[64:67], v[178:181], v[210:213], v[64:67]
	s_setprio 0
	s_barrier
	s_add_i32 s12, s13, s10
	s_mov_b32 m0, s12
	ds_read_b128 v[182:185], v143 offset:16384
	ds_read_b128 v[186:189], v143 offset:17408
	ds_read_b128 v[190:193], v143 offset:18432
	ds_read_b128 v[194:197], v143 offset:19456
	ds_read_b128 v[198:201], v143 offset:20480
	ds_read_b128 v[202:205], v143 offset:21504
	ds_read_b128 v[206:209], v143 offset:22528
	ds_read_b128 v[210:213], v143 offset:23552
	global_load_lds_dwordx4 v130, s[88:89]
	s_add_i32 m0, s12, 0x2000
	s_add_u32 vcc_lo, s88, 0x80000
	v_lshl_add_u64 v[216:217], s[88:89], 0, v[134:135]
	s_addc_u32 vcc_hi, s89, 0
	s_add_i32 s3, s3, s10
	global_load_lds_dwordx4 v134, s[88:89]
	s_mov_b32 m0, s3
	v_lshl_add_u64 v[220:221], s[90:91], 0, v[132:133]
	global_load_lds_dwordx4 v130, vcc
	s_add_i32 m0, s3, 0x2000
	s_nop 0
	global_load_lds_dwordx4 v134, vcc
	v_lshl_add_u64 v[218:219], s[90:91], 0, v[128:129]
	s_mov_b32 m0, s18
	s_nop 0
	global_load_lds_dwordx4 v128, s[90:91]
	s_mov_b32 m0, s19
	s_nop 0
	global_load_lds_dwordx4 v132, s[90:91]
	s_waitcnt vmcnt(8)
	s_waitcnt lgkmcnt(0)
	s_barrier
; #define PG8_STAGE(bufoff, gbase, voff) do { _Pragma("unroll") for (int _i = 0; _i < 2; ++_i) \
;         __builtin_amdgcn_global_load_lds((const unsigned*)((const char*)(gbase) + (voff)[_i]), (PG8_LAS unsigned*)(lds + (bufoff) + ldsw + _i * 8192), 16, 0, 0); } while (0)
; #define PG8_LDA(dst, b, h) do { _Pragma("unroll") for (int m = 0; m < 4; ++m) _Pragma("unroll") for (int k = 0; k < 2; ++k) dst[m][k] = *(const PG8_LAS bf16x8*)(lds + PG8_SA(b, h) + aoff + m * 2048 + k * 1024); } while (0)
; #define PG8_LDB(dst, b, h) do { _Pragma("unroll") for (int n = 0; n < 2; ++n) _Pragma("unroll") for (int k = 0; k < 2; ++k) dst[n][k] = *(const PG8_LAS bf16x8*)(lds + PG8_SB(b, h) + boff + n * 2048 + k * 1024); } while (0)
; #define PG8_MMA(ai, bj, At, Bt) do { __builtin_amdgcn_s_setprio(1); _Pragma("unroll") for (int m = 0; m < 4; ++m) _Pragma("unroll") for (int n = 0; n < 2; ++n) _Pragma("unroll") for (int k = 0; k < 2; ++k) \
;         acc[ai][bj][m][n] = __builtin_amdgcn_mfma_f32_16x16x32_bf16(Bt[n][k], At[m][k], acc[ai][bj][m][n], 0, 0, 0); __builtin_amdgcn_s_setprio(0); } while (0)
; #define PG8_WAIT_V(n) asm volatile("s_waitcnt vmcnt(" #n ")" ::: "memory")
; #define PG8_WAIT_L(n) asm volatile("s_waitcnt lgkmcnt(" #n ")" ::: "memory")
; #define PG8_BAR __builtin_amdgcn_s_barrier()
; #define PG8_SCHED __builtin_amdgcn_sched_barrier(0)
;     ...
;             PG8_WAIT_V(8); PG8_WAIT_L(0); PG8_BAR; PG8_MMA(1, 0, At, B0); PG8_MMA(1, 1, At, B1); PG8_BAR; PG8_SCHED;
;             PG8_LDB(B0, 1, 0); PG8_LDB(B1, 1, 1); PG8_SCHED; PG8_LDA(At, 1, 0); PG8_STAGE(PG8_SA(0, 1), a2 + hstep, voffA);
;             PG8_WAIT_V(8); PG8_WAIT_L(0); PG8_BAR; PG8_MMA(0, 0, At, B0); PG8_MMA(0, 1, At, B1); PG8_BAR; PG8_SCHED;
	s_setprio 1
	s_waitcnt lgkmcnt(0)
	v_mfma_f32_16x16x32_bf16 v[60:63], v[144:147], v[182:185], v[60:63]
	v_mfma_f32_16x16x32_bf16 v[60:63], v[148:151], v[186:189], v[60:63]
	v_mfma_f32_16x16x32_bf16 v[52:55], v[144:147], v[190:193], v[52:55]
	v_mfma_f32_16x16x32_bf16 v[52:55], v[148:151], v[194:197], v[52:55]
	v_mfma_f32_16x16x32_bf16 v[36:39], v[144:147], v[198:201], v[36:39]
	v_mfma_f32_16x16x32_bf16 v[36:39], v[148:151], v[202:205], v[36:39]
	v_mfma_f32_16x16x32_bf16 v[20:23], v[144:147], v[206:209], v[20:23]
	v_mfma_f32_16x16x32_bf16 v[20:23], v[148:151], v[210:213], v[20:23]
	v_mfma_f32_16x16x32_bf16 v[56:59], v[152:155], v[182:185], v[56:59]
	v_mfma_f32_16x16x32_bf16 v[56:59], v[156:159], v[186:189], v[56:59]
	v_mfma_f32_16x16x32_bf16 v[48:51], v[152:155], v[190:193], v[48:51]
	v_mfma_f32_16x16x32_bf16 v[48:51], v[156:159], v[194:197], v[48:51]
	v_mfma_f32_16x16x32_bf16 v[32:35], v[152:155], v[198:201], v[32:35]
	v_mfma_f32_16x16x32_bf16 v[32:35], v[156:159], v[202:205], v[32:35]
	v_mfma_f32_16x16x32_bf16 v[16:19], v[152:155], v[206:209], v[16:19]
	v_mfma_f32_16x16x32_bf16 v[16:19], v[156:159], v[210:213], v[16:19]
	s_setprio 0
	s_setprio 1
	v_mfma_f32_16x16x32_bf16 v[44:47], v[160:163], v[182:185], v[44:47]
	v_mfma_f32_16x16x32_bf16 v[44:47], v[164:167], v[186:189], v[44:47]
	v_mfma_f32_16x16x32_bf16 v[28:31], v[160:163], v[190:193], v[28:31]
	v_mfma_f32_16x16x32_bf16 v[28:31], v[164:167], v[194:197], v[28:31]
	v_mfma_f32_16x16x32_bf16 v[12:15], v[160:163], v[198:201], v[12:15]
	v_mfma_f32_16x16x32_bf16 v[12:15], v[164:167], v[202:205], v[12:15]
	v_mfma_f32_16x16x32_bf16 v[4:7], v[160:163], v[206:209], v[4:7]
	v_mfma_f32_16x16x32_bf16 v[4:7], v[164:167], v[210:213], v[4:7]
	v_mfma_f32_16x16x32_bf16 v[40:43], v[170:173], v[182:185], v[40:43]
	v_mfma_f32_16x16x32_bf16 v[40:43], v[178:181], v[186:189], v[40:43]
	v_mfma_f32_16x16x32_bf16 v[24:27], v[170:173], v[190:193], v[24:27]
	v_mfma_f32_16x16x32_bf16 v[24:27], v[178:181], v[194:197], v[24:27]
	v_mfma_f32_16x16x32_bf16 v[8:11], v[170:173], v[198:201], v[8:11]
	v_mfma_f32_16x16x32_bf16 v[8:11], v[178:181], v[202:205], v[8:11]
	v_mfma_f32_16x16x32_bf16 v[0:3], v[170:173], v[206:209], v[0:3]
	v_mfma_f32_16x16x32_bf16 v[0:3], v[178:181], v[210:213], v[0:3]
	s_setprio 0
	s_barrier
	s_add_i32 s3, 0, 0x18000
	s_add_i32 s12, 0, 0x1c000
	v_add_u32_e32 v156, s3, v141
	v_add_u32_e32 v168, s12, v141
	ds_read_b128 v[144:147], v156
	ds_read_b128 v[148:151], v156 offset:1024
	ds_read_b128 v[152:155], v156 offset:2048
	ds_read_b128 v[156:159], v156 offset:3072
	ds_read_b128 v[160:163], v168
	ds_read_b128 v[164:167], v168 offset:1024
	ds_read_b128 v[170:173], v168 offset:2048
	ds_read_b128 v[178:181], v168 offset:3072
	s_add_u32 s90, s90, 0x80000
	s_addc_u32 s91, s91, 0
	s_mov_b32 m0, s20
	ds_read_b128 v[182:185], v143 offset:32768
	ds_read_b128 v[186:189], v143 offset:33792
	ds_read_b128 v[190:193], v143 offset:34816
	ds_read_b128 v[194:197], v143 offset:35840
	ds_read_b128 v[198:201], v143 offset:36864
	ds_read_b128 v[202:205], v143 offset:37888
	ds_read_b128 v[206:209], v143 offset:38912
	ds_read_b128 v[210:213], v143 offset:39936
	global_load_lds_dwordx4 v128, s[90:91]
	s_mov_b32 m0, s21
	s_nop 0
	global_load_lds_dwordx4 v132, s[90:91]
	s_waitcnt vmcnt(8)
	s_waitcnt lgkmcnt(0)
	s_barrier
	s_setprio 1
	s_waitcnt lgkmcnt(0)
	v_mfma_f32_16x16x32_bf16 v[124:127], v[144:147], v[182:185], v[124:127]
	v_mfma_f32_16x16x32_bf16 v[124:127], v[148:151], v[186:189], v[124:127]
	v_mfma_f32_16x16x32_bf16 v[116:119], v[144:147], v[190:193], v[116:119]
	v_mfma_f32_16x16x32_bf16 v[116:119], v[148:151], v[194:197], v[116:119]
	v_mfma_f32_16x16x32_bf16 v[100:103], v[144:147], v[198:201], v[100:103]
	v_mfma_f32_16x16x32_bf16 v[100:103], v[148:151], v[202:205], v[100:103]
	v_mfma_f32_16x16x32_bf16 v[84:87], v[144:147], v[206:209], v[84:87]
	v_mfma_f32_16x16x32_bf16 v[84:87], v[148:151], v[210:213], v[84:87]
	v_mfma_f32_16x16x32_bf16 v[120:123], v[152:155], v[182:185], v[120:123]
	v_mfma_f32_16x16x32_bf16 v[120:123], v[156:159], v[186:189], v[120:123]
	v_mfma_f32_16x16x32_bf16 v[112:115], v[152:155], v[190:193], v[112:115]
	v_mfma_f32_16x16x32_bf16 v[112:115], v[156:159], v[194:197], v[112:115]
	v_mfma_f32_16x16x32_bf16 v[96:99], v[152:155], v[198:201], v[96:99]
	v_mfma_f32_16x16x32_bf16 v[96:99], v[156:159], v[202:205], v[96:99]
	v_mfma_f32_16x16x32_bf16 v[80:83], v[152:155], v[206:209], v[80:83]
	v_mfma_f32_16x16x32_bf16 v[80:83], v[156:159], v[210:213], v[80:83]
	s_setprio 0
	s_setprio 1
	v_mfma_f32_16x16x32_bf16 v[108:111], v[160:163], v[182:185], v[108:111]
	v_mfma_f32_16x16x32_bf16 v[108:111], v[164:167], v[186:189], v[108:111]
	v_mfma_f32_16x16x32_bf16 v[92:95], v[160:163], v[190:193], v[92:95]
	v_mfma_f32_16x16x32_bf16 v[92:95], v[164:167], v[194:197], v[92:95]
	v_mfma_f32_16x16x32_bf16 v[76:79], v[160:163], v[198:201], v[76:79]
	v_mfma_f32_16x16x32_bf16 v[76:79], v[164:167], v[202:205], v[76:79]
	v_mfma_f32_16x16x32_bf16 v[68:71], v[160:163], v[206:209], v[68:71]
	v_mfma_f32_16x16x32_bf16 v[68:71], v[164:167], v[210:213], v[68:71]
	v_mfma_f32_16x16x32_bf16 v[104:107], v[170:173], v[182:185], v[104:107]
	v_mfma_f32_16x16x32_bf16 v[104:107], v[178:181], v[186:189], v[104:107]
	v_mfma_f32_16x16x32_bf16 v[88:91], v[170:173], v[190:193], v[88:91]
	v_mfma_f32_16x16x32_bf16 v[88:91], v[178:181], v[194:197], v[88:91]
	v_mfma_f32_16x16x32_bf16 v[72:75], v[170:173], v[198:201], v[72:75]
	v_mfma_f32_16x16x32_bf16 v[72:75], v[178:181], v[202:205], v[72:75]
	v_mfma_f32_16x16x32_bf16 v[64:67], v[170:173], v[206:209], v[64:67]
	v_mfma_f32_16x16x32_bf16 v[64:67], v[178:181], v[210:213], v[64:67]
	s_setprio 0
	s_barrier
; #define PG8_STAGE(bufoff, gbase, voff) do { _Pragma("unroll") for (int _i = 0; _i < 2; ++_i) \
;         __builtin_amdgcn_global_load_lds((const unsigned*)((const char*)(gbase) + (voff)[_i]), (PG8_LAS unsigned*)(lds + (bufoff) + ldsw + _i * 8192), 16, 0, 0); } while (0)
; #define PG8_LDA(dst, b, h) do { _Pragma("unroll") for (int m = 0; m < 4; ++m) _Pragma("unroll") for (int k = 0; k < 2; ++k) dst[m][k] = *(const PG8_LAS bf16x8*)(lds + PG8_SA(b, h) + aoff + m * 2048 + k * 1024); } while (0)
; #define PG8_MMA(ai, bj, At, Bt) do { __builtin_amdgcn_s_setprio(1); _Pragma("unroll") for (int m = 0; m < 4; ++m) _Pragma("unroll") for (int n = 0; n < 2; ++n) _Pragma("unroll") for (int k = 0; k < 2; ++k) \
;         acc[ai][bj][m][n] = __builtin_amdgcn_mfma_f32_16x16x32_bf16(Bt[n][k], At[m][k], acc[ai][bj][m][n], 0, 0, 0); __builtin_amdgcn_s_setprio(0); } while (0)
; #define PG8_WAIT_V(n) asm volatile("s_waitcnt vmcnt(" #n ")" ::: "memory")
; #define PG8_WAIT_L(n) asm volatile("s_waitcnt lgkmcnt(" #n ")" ::: "memory")
; #define PG8_BAR __builtin_amdgcn_s_barrier()
; #define PG8_SCHED __builtin_amdgcn_sched_barrier(0)
;     ...
;             PG8_LDA(At, 1, 1); PG8_STAGE(PG8_SB(1, 0), b3, voffB); PG8_STAGE(PG8_SB(1, 1), b3 + hstep, voffB); PG8_STAGE(PG8_SA(1, 0), a3, voffA);
;             PG8_WAIT_V(8); PG8_WAIT_L(0); PG8_BAR; PG8_MMA(1, 0, At, B0); PG8_MMA(1, 1, At, B1); PG8_BAR; PG8_SCHED;
	s_add_i32 s3, s3, s10
	s_mov_b32 m0, s3
	ds_read_b128 v[182:185], v143 offset:49152
	ds_read_b128 v[186:189], v143 offset:50176
	ds_read_b128 v[190:193], v143 offset:51200
	ds_read_b128 v[194:197], v143 offset:52224
	ds_read_b128 v[198:201], v143 offset:53248
	ds_read_b128 v[202:205], v143 offset:54272
	ds_read_b128 v[206:209], v143 offset:55296
	ds_read_b128 v[210:213], v143 offset:56320
	s_add_u32 s100, s88, s16
	s_addc_u32 s101, s89, s17
	global_load_lds_dwordx4 v130, s[100:101]
	s_add_i32 m0, s3, 0x2000
	s_add_u32 s88, s88, 0x80080
	v_lshl_add_u64 v[214:215], v[216:217], 0, s[16:17]
	s_addc_u32 s89, s89, 0
	s_add_i32 s3, s12, s10
	global_load_lds_dwordx4 v[214:215], off
	s_mov_b32 m0, s3
	s_nop 0
	global_load_lds_dwordx4 v130, s[88:89]
	s_add_i32 m0, s3, 0x2000
	s_nop 0
	global_load_lds_dwordx4 v134, s[88:89]
	v_lshl_add_u64 v[214:215], v[218:219], 0, s[16:17]
	s_mov_b32 m0, s22
	s_nop 0
	global_load_lds_dwordx4 v[214:215], off
	v_lshl_add_u64 v[214:215], v[220:221], 0, s[16:17]
	s_mov_b32 m0, s23
	s_nop 0
	global_load_lds_dwordx4 v[214:215], off
	s_waitcnt vmcnt(8)
	s_waitcnt lgkmcnt(0)
	s_barrier
	s_setprio 1
	s_waitcnt lgkmcnt(0)
	v_mfma_f32_16x16x32_bf16 v[60:63], v[144:147], v[182:185], v[60:63]
	v_mfma_f32_16x16x32_bf16 v[60:63], v[148:151], v[186:189], v[60:63]
	v_mfma_f32_16x16x32_bf16 v[52:55], v[144:147], v[190:193], v[52:55]
	v_mfma_f32_16x16x32_bf16 v[52:55], v[148:151], v[194:197], v[52:55]
	v_mfma_f32_16x16x32_bf16 v[36:39], v[144:147], v[198:201], v[36:39]
	v_mfma_f32_16x16x32_bf16 v[36:39], v[148:151], v[202:205], v[36:39]
	v_mfma_f32_16x16x32_bf16 v[20:23], v[144:147], v[206:209], v[20:23]
	v_mfma_f32_16x16x32_bf16 v[20:23], v[148:151], v[210:213], v[20:23]
	v_mfma_f32_16x16x32_bf16 v[56:59], v[152:155], v[182:185], v[56:59]
	v_mfma_f32_16x16x32_bf16 v[56:59], v[156:159], v[186:189], v[56:59]
	v_mfma_f32_16x16x32_bf16 v[48:51], v[152:155], v[190:193], v[48:51]
	v_mfma_f32_16x16x32_bf16 v[48:51], v[156:159], v[194:197], v[48:51]
	v_mfma_f32_16x16x32_bf16 v[32:35], v[152:155], v[198:201], v[32:35]
	v_mfma_f32_16x16x32_bf16 v[32:35], v[156:159], v[202:205], v[32:35]
	v_mfma_f32_16x16x32_bf16 v[16:19], v[152:155], v[206:209], v[16:19]
	v_mfma_f32_16x16x32_bf16 v[16:19], v[156:159], v[210:213], v[16:19]
	s_setprio 0
	s_setprio 1
	v_mfma_f32_16x16x32_bf16 v[44:47], v[160:163], v[182:185], v[44:47]
	v_mfma_f32_16x16x32_bf16 v[44:47], v[164:167], v[186:189], v[44:47]
	v_mfma_f32_16x16x32_bf16 v[28:31], v[160:163], v[190:193], v[28:31]
	v_mfma_f32_16x16x32_bf16 v[28:31], v[164:167], v[194:197], v[28:31]
	v_mfma_f32_16x16x32_bf16 v[12:15], v[160:163], v[198:201], v[12:15]
	v_mfma_f32_16x16x32_bf16 v[12:15], v[164:167], v[202:205], v[12:15]
	v_mfma_f32_16x16x32_bf16 v[4:7], v[160:163], v[206:209], v[4:7]
	v_mfma_f32_16x16x32_bf16 v[4:7], v[164:167], v[210:213], v[4:7]
	v_mfma_f32_16x16x32_bf16 v[40:43], v[170:173], v[182:185], v[40:43]
	v_mfma_f32_16x16x32_bf16 v[40:43], v[178:181], v[186:189], v[40:43]
	v_mfma_f32_16x16x32_bf16 v[24:27], v[170:173], v[190:193], v[24:27]
	v_mfma_f32_16x16x32_bf16 v[24:27], v[178:181], v[194:197], v[24:27]
	v_mfma_f32_16x16x32_bf16 v[8:11], v[170:173], v[198:201], v[8:11]
	v_mfma_f32_16x16x32_bf16 v[8:11], v[178:181], v[202:205], v[8:11]
	v_mfma_f32_16x16x32_bf16 v[0:3], v[170:173], v[206:209], v[0:3]
	v_mfma_f32_16x16x32_bf16 v[0:3], v[178:181], v[210:213], v[0:3]
	s_setprio 0
	s_barrier
	s_add_i32 s2, s2, 2
	s_add_u32 s86, s86, 0x100
	s_addc_u32 s87, s87, 0
	s_add_u32 s42, s42, 0x100
	s_addc_u32 s43, s43, 0
	s_cmp_gt_u32 s2, 29
	s_cbranch_scc0 .LBB0_514
	s_and_b64 vcc, exec, s[74:75]
	s_cbranch_vccz .LBB0_517
	s_barrier

; #define PG8_STAGE(bufoff, gbase, voff) do { _Pragma("unroll") for (int _i = 0; _i < 2; ++_i) \
;         __builtin_amdgcn_global_load_lds((const unsigned*)((const char*)(gbase) + (voff)[_i]), (PG8_LAS unsigned*)(lds + (bufoff) + ldsw + _i * 8192), 16, 0, 0); } while (0)
; #define PG8_LDA(dst, b, h) do { _Pragma("unroll") for (int m = 0; m < 4; ++m) _Pragma("unroll") for (int k = 0; k < 2; ++k) dst[m][k] = *(const PG8_LAS bf16x8*)(lds + PG8_SA(b, h) + aoff + m * 2048 + k * 1024); } while (0)
; #define PG8_LDB(dst, b, h) do { _Pragma("unroll") for (int n = 0; n < 2; ++n) _Pragma("unroll") for (int k = 0; k < 2; ++k) dst[n][k] = *(const PG8_LAS bf16x8*)(lds + PG8_SB(b, h) + boff + n * 2048 + k * 1024); } while (0)
; #define PG8_MMA(ai, bj, At, Bt) do { __builtin_amdgcn_s_setprio(1); _Pragma("unroll") for (int m = 0; m < 4; ++m) _Pragma("unroll") for (int n = 0; n < 2; ++n) _Pragma("unroll") for (int k = 0; k < 2; ++k) \
;         acc[ai][bj][m][n] = __builtin_amdgcn_mfma_f32_16x16x32_bf16(Bt[n][k], At[m][k], acc[ai][bj][m][n], 0, 0, 0); __builtin_amdgcn_s_setprio(0); } while (0)
; #define PG8_WAIT_V(n) asm volatile("s_waitcnt vmcnt(" #n ")" ::: "memory")
; #define PG8_WAIT_L(n) asm volatile("s_waitcnt lgkmcnt(" #n ")" ::: "memory")
; #define PG8_BAR __builtin_amdgcn_s_barrier()
; #define PG8_SCHED __builtin_amdgcn_sched_barrier(0)
;     ...
;             const bool last = (t == nt - 2);
;             const char* a1 = PG8_KADV(cA, (size_t)(t + 1) * kstep);
;             const char* a2 = last ? nA : PG8_KADV(cA, (size_t)(t + 2) * kstep); const char* b2 = last ? nB : PG8_KADV(cB, (size_t)(t + 2) * kstep);
;             const char* a3 = PG8_KADV(a2, kstep); const char* b3 = PG8_KADV(b2, kstep);
;             if (last && has_next) S.a_ready(nxt);
;             if constexpr (SP2) {
;             PG8_LDB(B0, 0, 0); PG8_LDB(B1, 0, 1); PG8_SCHED; PG8_LDA(At, 0, 0); PG8_STAGE(PG8_SA(1, 1), a1 + hstep, voffA);
;             PG8_WAIT_V(8); PG8_WAIT_L(0); PG8_BAR; PG8_MMA(0, 0, At, B0); PG8_MMA(0, 1, At, B1); PG8_BAR; PG8_SCHED;
;             PG8_LDA(At, 0, 1); PG8_STAGE(PG8_SB(0, 0), b2, voffB); PG8_STAGE(PG8_SB(0, 1), b2 + hstep, voffB); PG8_STAGE(PG8_SA(0, 0), a2, voffA);
;             PG8_WAIT_V(8); PG8_WAIT_L(0); PG8_BAR; PG8_MMA(1, 0, At, B0); PG8_MMA(1, 1, At, B1); PG8_BAR; PG8_SCHED;
.LBB0_541:
	s_add_u32 s3, s88, 0xfff80080
	s_addc_u32 s12, s89, -1
	s_add_i32 s13, 0, 0x10000
	s_cmp_eq_u32 s2, 28
	s_cselect_b32 s93, s15, s12
	s_cselect_b32 s92, s30, s3
	v_add_u32_e32 v140, s13, v142
	s_cselect_b32 s91, s33, s43
	s_cselect_b32 s90, s40, s42
	s_add_i32 s3, 0, 0x14000
	ds_read_b128 v[146:149], v140
	ds_read_b128 v[150:153], v140 offset:1024
	ds_read_b128 v[154:157], v140 offset:2048
	ds_read_b128 v[158:161], v140 offset:3072
	v_add_u32_e32 v140, s3, v142
	ds_read_b128 v[162:165], v140
	ds_read_b128 v[170:173], v140 offset:1024
	ds_read_b128 v[178:181], v140 offset:2048
	ds_read_b128 v[182:185], v140 offset:3072
	s_add_i32 m0, s21, 0xc000
	ds_read_b128 v[186:189], v145
	ds_read_b128 v[190:193], v145 offset:1024
	ds_read_b128 v[194:197], v145 offset:2048
	ds_read_b128 v[198:201], v145 offset:3072
	ds_read_b128 v[202:205], v145 offset:4096
	ds_read_b128 v[206:209], v145 offset:5120
	ds_read_b128 v[210:213], v145 offset:6144
	ds_read_b128 v[214:217], v145 offset:7168
	global_load_lds_dwordx4 v136, s[88:89]
	s_add_i32 m0, s21, 0xe000
	s_nop 0
	global_load_lds_dwordx4 v138, s[88:89]
	s_waitcnt vmcnt(8)
	s_waitcnt lgkmcnt(0)
	s_barrier
	s_setprio 1
	s_waitcnt lgkmcnt(0)
	v_mfma_f32_16x16x32_bf16 v[124:127], v[146:149], v[186:189], v[124:127]
	v_mfma_f32_16x16x32_bf16 v[124:127], v[150:153], v[190:193], v[124:127]
	v_mfma_f32_16x16x32_bf16 v[116:119], v[146:149], v[194:197], v[116:119]
	v_mfma_f32_16x16x32_bf16 v[116:119], v[150:153], v[198:201], v[116:119]
	v_mfma_f32_16x16x32_bf16 v[100:103], v[146:149], v[202:205], v[100:103]
	v_mfma_f32_16x16x32_bf16 v[100:103], v[150:153], v[206:209], v[100:103]
	v_mfma_f32_16x16x32_bf16 v[84:87], v[146:149], v[210:213], v[84:87]
	v_mfma_f32_16x16x32_bf16 v[84:87], v[150:153], v[214:217], v[84:87]
	v_mfma_f32_16x16x32_bf16 v[120:123], v[154:157], v[186:189], v[120:123]
	v_mfma_f32_16x16x32_bf16 v[120:123], v[158:161], v[190:193], v[120:123]
	v_mfma_f32_16x16x32_bf16 v[112:115], v[154:157], v[194:197], v[112:115]
	v_mfma_f32_16x16x32_bf16 v[112:115], v[158:161], v[198:201], v[112:115]
	v_mfma_f32_16x16x32_bf16 v[96:99], v[154:157], v[202:205], v[96:99]
	v_mfma_f32_16x16x32_bf16 v[96:99], v[158:161], v[206:209], v[96:99]
	v_mfma_f32_16x16x32_bf16 v[80:83], v[154:157], v[210:213], v[80:83]
	v_mfma_f32_16x16x32_bf16 v[80:83], v[158:161], v[214:217], v[80:83]
	s_setprio 0
	s_setprio 1
	v_mfma_f32_16x16x32_bf16 v[108:111], v[162:165], v[186:189], v[108:111]
	v_mfma_f32_16x16x32_bf16 v[108:111], v[170:173], v[190:193], v[108:111]
	v_mfma_f32_16x16x32_bf16 v[92:95], v[162:165], v[194:197], v[92:95]
	v_mfma_f32_16x16x32_bf16 v[92:95], v[170:173], v[198:201], v[92:95]
	v_mfma_f32_16x16x32_bf16 v[76:79], v[162:165], v[202:205], v[76:79]
	v_mfma_f32_16x16x32_bf16 v[76:79], v[170:173], v[206:209], v[76:79]
	v_mfma_f32_16x16x32_bf16 v[68:71], v[162:165], v[210:213], v[68:71]
	v_mfma_f32_16x16x32_bf16 v[68:71], v[170:173], v[214:217], v[68:71]
	v_mfma_f32_16x16x32_bf16 v[104:107], v[178:181], v[186:189], v[104:107]
	v_mfma_f32_16x16x32_bf16 v[104:107], v[182:185], v[190:193], v[104:107]
	v_mfma_f32_16x16x32_bf16 v[88:91], v[178:181], v[194:197], v[88:91]
	v_mfma_f32_16x16x32_bf16 v[88:91], v[182:185], v[198:201], v[88:91]
	v_mfma_f32_16x16x32_bf16 v[72:75], v[178:181], v[202:205], v[72:75]
	v_mfma_f32_16x16x32_bf16 v[72:75], v[182:185], v[206:209], v[72:75]
	v_mfma_f32_16x16x32_bf16 v[64:67], v[178:181], v[210:213], v[64:67]
	v_mfma_f32_16x16x32_bf16 v[64:67], v[182:185], v[214:217], v[64:67]
	s_setprio 0
	s_barrier
	s_add_i32 s12, s13, s20
	s_mov_b32 m0, s12
	ds_read_b128 v[186:189], v145 offset:16384
	ds_read_b128 v[190:193], v145 offset:17408
	ds_read_b128 v[194:197], v145 offset:18432
	ds_read_b128 v[198:201], v145 offset:19456
	ds_read_b128 v[202:205], v145 offset:20480
	ds_read_b128 v[206:209], v145 offset:21504
	ds_read_b128 v[210:213], v145 offset:22528
	ds_read_b128 v[214:217], v145 offset:23552
	global_load_lds_dwordx4 v132, s[90:91]
	s_add_i32 m0, s12, 0x2000
	s_add_u32 vcc_lo, s90, 0x80000
	v_lshl_add_u64 v[218:219], s[90:91], 0, v[128:129]
	s_addc_u32 vcc_hi, s91, 0
	s_add_i32 s3, s3, s20
	global_load_lds_dwordx4 v128, s[90:91]
	s_mov_b32 m0, s3
	v_lshl_add_u64 v[222:223], s[92:93], 0, v[130:131]
	global_load_lds_dwordx4 v132, vcc
	s_add_i32 m0, s3, 0x2000
	s_nop 0
	global_load_lds_dwordx4 v128, vcc
	v_lshl_add_u64 v[220:221], s[92:93], 0, v[134:135]
	s_mov_b32 m0, s21
	s_nop 0
	global_load_lds_dwordx4 v134, s[92:93]
	s_mov_b32 m0, s22
	s_nop 0
	global_load_lds_dwordx4 v130, s[92:93]
	s_waitcnt vmcnt(8)
	s_waitcnt lgkmcnt(0)
	s_barrier
; #define PG8_STAGE(bufoff, gbase, voff) do { _Pragma("unroll") for (int _i = 0; _i < 2; ++_i) \
;         __builtin_amdgcn_global_load_lds((const unsigned*)((const char*)(gbase) + (voff)[_i]), (PG8_LAS unsigned*)(lds + (bufoff) + ldsw + _i * 8192), 16, 0, 0); } while (0)
; #define PG8_LDA(dst, b, h) do { _Pragma("unroll") for (int m = 0; m < 4; ++m) _Pragma("unroll") for (int k = 0; k < 2; ++k) dst[m][k] = *(const PG8_LAS bf16x8*)(lds + PG8_SA(b, h) + aoff + m * 2048 + k * 1024); } while (0)
; #define PG8_LDB(dst, b, h) do { _Pragma("unroll") for (int n = 0; n < 2; ++n) _Pragma("unroll") for (int k = 0; k < 2; ++k) dst[n][k] = *(const PG8_LAS bf16x8*)(lds + PG8_SB(b, h) + boff + n * 2048 + k * 1024); } while (0)
; #define PG8_MMA(ai, bj, At, Bt) do { __builtin_amdgcn_s_setprio(1); _Pragma("unroll") for (int m = 0; m < 4; ++m) _Pragma("unroll") for (int n = 0; n < 2; ++n) _Pragma("unroll") for (int k = 0; k < 2; ++k) \
;         acc[ai][bj][m][n] = __builtin_amdgcn_mfma_f32_16x16x32_bf16(Bt[n][k], At[m][k], acc[ai][bj][m][n], 0, 0, 0); __builtin_amdgcn_s_setprio(0); } while (0)
; #define PG8_WAIT_V(n) asm volatile("s_waitcnt vmcnt(" #n ")" ::: "memory")
; #define PG8_WAIT_L(n) asm volatile("s_waitcnt lgkmcnt(" #n ")" ::: "memory")
; #define PG8_BAR __builtin_amdgcn_s_barrier()
; #define PG8_SCHED __builtin_amdgcn_sched_barrier(0)
;     ...
;             PG8_WAIT_V(8); PG8_WAIT_L(0); PG8_BAR; PG8_MMA(1, 0, At, B0); PG8_MMA(1, 1, At, B1); PG8_BAR; PG8_SCHED;
;             PG8_LDB(B0, 1, 0); PG8_LDB(B1, 1, 1); PG8_SCHED; PG8_LDA(At, 1, 0); PG8_STAGE(PG8_SA(0, 1), a2 + hstep, voffA);
;             PG8_WAIT_V(8); PG8_WAIT_L(0); PG8_BAR; PG8_MMA(0, 0, At, B0); PG8_MMA(0, 1, At, B1); PG8_BAR; PG8_SCHED;
	s_setprio 1
	s_waitcnt lgkmcnt(0)
	v_mfma_f32_16x16x32_bf16 v[60:63], v[146:149], v[186:189], v[60:63]
	v_mfma_f32_16x16x32_bf16 v[60:63], v[150:153], v[190:193], v[60:63]
	v_mfma_f32_16x16x32_bf16 v[52:55], v[146:149], v[194:197], v[52:55]
	v_mfma_f32_16x16x32_bf16 v[52:55], v[150:153], v[198:201], v[52:55]
	v_mfma_f32_16x16x32_bf16 v[36:39], v[146:149], v[202:205], v[36:39]
	v_mfma_f32_16x16x32_bf16 v[36:39], v[150:153], v[206:209], v[36:39]
	v_mfma_f32_16x16x32_bf16 v[20:23], v[146:149], v[210:213], v[20:23]
	v_mfma_f32_16x16x32_bf16 v[20:23], v[150:153], v[214:217], v[20:23]
	v_mfma_f32_16x16x32_bf16 v[56:59], v[154:157], v[186:189], v[56:59]
	v_mfma_f32_16x16x32_bf16 v[56:59], v[158:161], v[190:193], v[56:59]
	v_mfma_f32_16x16x32_bf16 v[48:51], v[154:157], v[194:197], v[48:51]
	v_mfma_f32_16x16x32_bf16 v[48:51], v[158:161], v[198:201], v[48:51]
	v_mfma_f32_16x16x32_bf16 v[32:35], v[154:157], v[202:205], v[32:35]
	v_mfma_f32_16x16x32_bf16 v[32:35], v[158:161], v[206:209], v[32:35]
	v_mfma_f32_16x16x32_bf16 v[16:19], v[154:157], v[210:213], v[16:19]
	v_mfma_f32_16x16x32_bf16 v[16:19], v[158:161], v[214:217], v[16:19]
	s_setprio 0
	s_setprio 1
	v_mfma_f32_16x16x32_bf16 v[44:47], v[162:165], v[186:189], v[44:47]
	v_mfma_f32_16x16x32_bf16 v[44:47], v[170:173], v[190:193], v[44:47]
	v_mfma_f32_16x16x32_bf16 v[28:31], v[162:165], v[194:197], v[28:31]
	v_mfma_f32_16x16x32_bf16 v[28:31], v[170:173], v[198:201], v[28:31]
	v_mfma_f32_16x16x32_bf16 v[12:15], v[162:165], v[202:205], v[12:15]
	v_mfma_f32_16x16x32_bf16 v[12:15], v[170:173], v[206:209], v[12:15]
	v_mfma_f32_16x16x32_bf16 v[4:7], v[162:165], v[210:213], v[4:7]
	v_mfma_f32_16x16x32_bf16 v[4:7], v[170:173], v[214:217], v[4:7]
	v_mfma_f32_16x16x32_bf16 v[40:43], v[178:181], v[186:189], v[40:43]
	v_mfma_f32_16x16x32_bf16 v[40:43], v[182:185], v[190:193], v[40:43]
	v_mfma_f32_16x16x32_bf16 v[24:27], v[178:181], v[194:197], v[24:27]
	v_mfma_f32_16x16x32_bf16 v[24:27], v[182:185], v[198:201], v[24:27]
	v_mfma_f32_16x16x32_bf16 v[8:11], v[178:181], v[202:205], v[8:11]
	v_mfma_f32_16x16x32_bf16 v[8:11], v[182:185], v[206:209], v[8:11]
	v_mfma_f32_16x16x32_bf16 v[0:3], v[178:181], v[210:213], v[0:3]
	v_mfma_f32_16x16x32_bf16 v[0:3], v[182:185], v[214:217], v[0:3]
	s_setprio 0
	s_barrier
	s_add_i32 s3, 0, 0x18000
	v_add_u32_e32 v140, s3, v142
	s_add_i32 s12, 0, 0x1c000
	ds_read_b128 v[146:149], v140
	ds_read_b128 v[150:153], v140 offset:1024
	ds_read_b128 v[154:157], v140 offset:2048
	ds_read_b128 v[158:161], v140 offset:3072
	v_add_u32_e32 v140, s12, v142
	ds_read_b128 v[162:165], v140
	ds_read_b128 v[170:173], v140 offset:1024
	ds_read_b128 v[178:181], v140 offset:2048
	ds_read_b128 v[182:185], v140 offset:3072
	s_add_u32 s92, s92, 0x80000
	s_addc_u32 s93, s93, 0
	s_mov_b32 m0, s23
	ds_read_b128 v[186:189], v145 offset:32768
	ds_read_b128 v[190:193], v145 offset:33792
	ds_read_b128 v[194:197], v145 offset:34816
	ds_read_b128 v[198:201], v145 offset:35840
	ds_read_b128 v[202:205], v145 offset:36864
	ds_read_b128 v[206:209], v145 offset:37888
	ds_read_b128 v[210:213], v145 offset:38912
	ds_read_b128 v[214:217], v145 offset:39936
	global_load_lds_dwordx4 v134, s[92:93]
	s_mov_b32 m0, s57
	s_nop 0
	global_load_lds_dwordx4 v130, s[92:93]
	s_waitcnt vmcnt(8)
	s_waitcnt lgkmcnt(0)
	s_barrier
	s_setprio 1
	s_waitcnt lgkmcnt(0)
	v_mfma_f32_16x16x32_bf16 v[124:127], v[146:149], v[186:189], v[124:127]
	v_mfma_f32_16x16x32_bf16 v[124:127], v[150:153], v[190:193], v[124:127]
	v_mfma_f32_16x16x32_bf16 v[116:119], v[146:149], v[194:197], v[116:119]
	v_mfma_f32_16x16x32_bf16 v[116:119], v[150:153], v[198:201], v[116:119]
	v_mfma_f32_16x16x32_bf16 v[100:103], v[146:149], v[202:205], v[100:103]
	v_mfma_f32_16x16x32_bf16 v[100:103], v[150:153], v[206:209], v[100:103]
	v_mfma_f32_16x16x32_bf16 v[84:87], v[146:149], v[210:213], v[84:87]
	v_mfma_f32_16x16x32_bf16 v[84:87], v[150:153], v[214:217], v[84:87]
	v_mfma_f32_16x16x32_bf16 v[120:123], v[154:157], v[186:189], v[120:123]
	v_mfma_f32_16x16x32_bf16 v[120:123], v[158:161], v[190:193], v[120:123]
	v_mfma_f32_16x16x32_bf16 v[112:115], v[154:157], v[194:197], v[112:115]
	v_mfma_f32_16x16x32_bf16 v[112:115], v[158:161], v[198:201], v[112:115]
	v_mfma_f32_16x16x32_bf16 v[96:99], v[154:157], v[202:205], v[96:99]
	v_mfma_f32_16x16x32_bf16 v[96:99], v[158:161], v[206:209], v[96:99]
	v_mfma_f32_16x16x32_bf16 v[80:83], v[154:157], v[210:213], v[80:83]
	v_mfma_f32_16x16x32_bf16 v[80:83], v[158:161], v[214:217], v[80:83]
	s_setprio 0
	s_setprio 1
	v_mfma_f32_16x16x32_bf16 v[108:111], v[162:165], v[186:189], v[108:111]
	v_mfma_f32_16x16x32_bf16 v[108:111], v[170:173], v[190:193], v[108:111]
	v_mfma_f32_16x16x32_bf16 v[92:95], v[162:165], v[194:197], v[92:95]
	v_mfma_f32_16x16x32_bf16 v[92:95], v[170:173], v[198:201], v[92:95]
	v_mfma_f32_16x16x32_bf16 v[76:79], v[162:165], v[202:205], v[76:79]
	v_mfma_f32_16x16x32_bf16 v[76:79], v[170:173], v[206:209], v[76:79]
	v_mfma_f32_16x16x32_bf16 v[68:71], v[162:165], v[210:213], v[68:71]
	v_mfma_f32_16x16x32_bf16 v[68:71], v[170:173], v[214:217], v[68:71]
	v_mfma_f32_16x16x32_bf16 v[104:107], v[178:181], v[186:189], v[104:107]
	v_mfma_f32_16x16x32_bf16 v[104:107], v[182:185], v[190:193], v[104:107]
	v_mfma_f32_16x16x32_bf16 v[88:91], v[178:181], v[194:197], v[88:91]
	v_mfma_f32_16x16x32_bf16 v[88:91], v[182:185], v[198:201], v[88:91]
	v_mfma_f32_16x16x32_bf16 v[72:75], v[178:181], v[202:205], v[72:75]
	v_mfma_f32_16x16x32_bf16 v[72:75], v[182:185], v[206:209], v[72:75]
	v_mfma_f32_16x16x32_bf16 v[64:67], v[178:181], v[210:213], v[64:67]
	v_mfma_f32_16x16x32_bf16 v[64:67], v[182:185], v[214:217], v[64:67]
	s_setprio 0
	s_barrier
; #define PG8_STAGE(bufoff, gbase, voff) do { _Pragma("unroll") for (int _i = 0; _i < 2; ++_i) \
;         __builtin_amdgcn_global_load_lds((const unsigned*)((const char*)(gbase) + (voff)[_i]), (PG8_LAS unsigned*)(lds + (bufoff) + ldsw + _i * 8192), 16, 0, 0); } while (0)
; #define PG8_LDA(dst, b, h) do { _Pragma("unroll") for (int m = 0; m < 4; ++m) _Pragma("unroll") for (int k = 0; k < 2; ++k) dst[m][k] = *(const PG8_LAS bf16x8*)(lds + PG8_SA(b, h) + aoff + m * 2048 + k * 1024); } while (0)
; #define PG8_MMA(ai, bj, At, Bt) do { __builtin_amdgcn_s_setprio(1); _Pragma("unroll") for (int m = 0; m < 4; ++m) _Pragma("unroll") for (int n = 0; n < 2; ++n) _Pragma("unroll") for (int k = 0; k < 2; ++k) \
;         acc[ai][bj][m][n] = __builtin_amdgcn_mfma_f32_16x16x32_bf16(Bt[n][k], At[m][k], acc[ai][bj][m][n], 0, 0, 0); __builtin_amdgcn_s_setprio(0); } while (0)
; #define PG8_WAIT_V(n) asm volatile("s_waitcnt vmcnt(" #n ")" ::: "memory")
; #define PG8_WAIT_L(n) asm volatile("s_waitcnt lgkmcnt(" #n ")" ::: "memory")
; #define PG8_BAR __builtin_amdgcn_s_barrier()
; #define PG8_SCHED __builtin_amdgcn_sched_barrier(0)
;     ...
;             PG8_LDA(At, 1, 1); PG8_STAGE(PG8_SB(1, 0), b3, voffB); PG8_STAGE(PG8_SB(1, 1), b3 + hstep, voffB); PG8_STAGE(PG8_SA(1, 0), a3, voffA);
;             PG8_WAIT_V(8); PG8_WAIT_L(0); PG8_BAR; PG8_MMA(1, 0, At, B0); PG8_MMA(1, 1, At, B1); PG8_BAR; PG8_SCHED;
	s_add_i32 s3, s3, s20
	s_mov_b32 m0, s3
	ds_read_b128 v[186:189], v145 offset:49152
	ds_read_b128 v[190:193], v145 offset:50176
	ds_read_b128 v[194:197], v145 offset:51200
	ds_read_b128 v[198:201], v145 offset:52224
	ds_read_b128 v[202:205], v145 offset:53248
	ds_read_b128 v[206:209], v145 offset:54272
	ds_read_b128 v[210:213], v145 offset:55296
	ds_read_b128 v[214:217], v145 offset:56320
	s_add_u32 s100, s90, s16
	s_addc_u32 s101, s91, s17
	global_load_lds_dwordx4 v132, s[100:101]
	s_add_i32 m0, s3, 0x2000
	s_add_u32 s90, s90, 0x80080
	v_lshl_add_u64 v[166:167], v[218:219], 0, s[16:17]
	s_addc_u32 s91, s91, 0
	s_add_i32 s3, s12, s20
	global_load_lds_dwordx4 v[166:167], off
	s_mov_b32 m0, s3
	s_nop 0
	global_load_lds_dwordx4 v132, s[90:91]
	s_add_i32 m0, s3, 0x2000
	s_nop 0
	global_load_lds_dwordx4 v128, s[90:91]
	v_lshl_add_u64 v[166:167], v[220:221], 0, s[16:17]
	s_mov_b32 m0, s59
	s_nop 0
	global_load_lds_dwordx4 v[166:167], off
	v_lshl_add_u64 v[166:167], v[222:223], 0, s[16:17]
	s_mov_b32 m0, s8
	s_nop 0
	global_load_lds_dwordx4 v[166:167], off
	s_waitcnt vmcnt(8)
	s_waitcnt lgkmcnt(0)
	s_barrier
	s_setprio 1
	s_waitcnt lgkmcnt(0)
	v_mfma_f32_16x16x32_bf16 v[60:63], v[146:149], v[186:189], v[60:63]
	v_mfma_f32_16x16x32_bf16 v[60:63], v[150:153], v[190:193], v[60:63]
	v_mfma_f32_16x16x32_bf16 v[52:55], v[146:149], v[194:197], v[52:55]
	v_mfma_f32_16x16x32_bf16 v[52:55], v[150:153], v[198:201], v[52:55]
	v_mfma_f32_16x16x32_bf16 v[36:39], v[146:149], v[202:205], v[36:39]
	v_mfma_f32_16x16x32_bf16 v[36:39], v[150:153], v[206:209], v[36:39]
	v_mfma_f32_16x16x32_bf16 v[20:23], v[146:149], v[210:213], v[20:23]
	v_mfma_f32_16x16x32_bf16 v[20:23], v[150:153], v[214:217], v[20:23]
	v_mfma_f32_16x16x32_bf16 v[56:59], v[154:157], v[186:189], v[56:59]
	v_mfma_f32_16x16x32_bf16 v[56:59], v[158:161], v[190:193], v[56:59]
	v_mfma_f32_16x16x32_bf16 v[48:51], v[154:157], v[194:197], v[48:51]
	v_mfma_f32_16x16x32_bf16 v[48:51], v[158:161], v[198:201], v[48:51]
	v_mfma_f32_16x16x32_bf16 v[32:35], v[154:157], v[202:205], v[32:35]
	v_mfma_f32_16x16x32_bf16 v[32:35], v[158:161], v[206:209], v[32:35]
	v_mfma_f32_16x16x32_bf16 v[16:19], v[154:157], v[210:213], v[16:19]
	v_mfma_f32_16x16x32_bf16 v[16:19], v[158:161], v[214:217], v[16:19]
	s_setprio 0
	s_setprio 1
	v_mfma_f32_16x16x32_bf16 v[44:47], v[162:165], v[186:189], v[44:47]
	v_mfma_f32_16x16x32_bf16 v[44:47], v[170:173], v[190:193], v[44:47]
	v_mfma_f32_16x16x32_bf16 v[28:31], v[162:165], v[194:197], v[28:31]
	v_mfma_f32_16x16x32_bf16 v[28:31], v[170:173], v[198:201], v[28:31]
	v_mfma_f32_16x16x32_bf16 v[12:15], v[162:165], v[202:205], v[12:15]
	v_mfma_f32_16x16x32_bf16 v[12:15], v[170:173], v[206:209], v[12:15]
	v_mfma_f32_16x16x32_bf16 v[4:7], v[162:165], v[210:213], v[4:7]
	v_mfma_f32_16x16x32_bf16 v[4:7], v[170:173], v[214:217], v[4:7]
	v_mfma_f32_16x16x32_bf16 v[40:43], v[178:181], v[186:189], v[40:43]
	v_mfma_f32_16x16x32_bf16 v[40:43], v[182:185], v[190:193], v[40:43]
	v_mfma_f32_16x16x32_bf16 v[24:27], v[178:181], v[194:197], v[24:27]
	v_mfma_f32_16x16x32_bf16 v[24:27], v[182:185], v[198:201], v[24:27]
	v_mfma_f32_16x16x32_bf16 v[8:11], v[178:181], v[202:205], v[8:11]
	v_mfma_f32_16x16x32_bf16 v[8:11], v[182:185], v[206:209], v[8:11]
	v_mfma_f32_16x16x32_bf16 v[0:3], v[178:181], v[210:213], v[0:3]
	v_mfma_f32_16x16x32_bf16 v[0:3], v[182:185], v[214:217], v[0:3]
	s_setprio 0
	s_barrier
	s_add_i32 s2, s2, 2
	s_add_u32 s88, s88, 0x100
	s_addc_u32 s89, s89, 0
	s_add_u32 s42, s42, 0x100
	s_addc_u32 s43, s43, 0
	s_cmp_gt_u32 s2, 29
	s_cbranch_scc0 .LBB0_541
	s_and_b64 vcc, exec, s[76:77]
	s_cbranch_vccz .LBB0_544
	s_barrier

; #define PG8_STAGE(bufoff, gbase, voff) do { _Pragma("unroll") for (int _i = 0; _i < 2; ++_i) \
;         __builtin_amdgcn_global_load_lds((const unsigned*)((const char*)(gbase) + (voff)[_i]), (PG8_LAS unsigned*)(lds + (bufoff) + ldsw + _i * 8192), 16, 0, 0); } while (0)
; #define PG8_LDA(dst, b, h) do { _Pragma("unroll") for (int m = 0; m < 4; ++m) _Pragma("unroll") for (int k = 0; k < 2; ++k) dst[m][k] = *(const PG8_LAS bf16x8*)(lds + PG8_SA(b, h) + aoff + m * 2048 + k * 1024); } while (0)
; #define PG8_LDB(dst, b, h) do { _Pragma("unroll") for (int n = 0; n < 2; ++n) _Pragma("unroll") for (int k = 0; k < 2; ++k) dst[n][k] = *(const PG8_LAS bf16x8*)(lds + PG8_SB(b, h) + boff + n * 2048 + k * 1024); } while (0)
; #define PG8_MMA(ai, bj, At, Bt) do { __builtin_amdgcn_s_setprio(1); _Pragma("unroll") for (int m = 0; m < 4; ++m) _Pragma("unroll") for (int n = 0; n < 2; ++n) _Pragma("unroll") for (int k = 0; k < 2; ++k) \
;         acc[ai][bj][m][n] = __builtin_amdgcn_mfma_f32_16x16x32_bf16(Bt[n][k], At[m][k], acc[ai][bj][m][n], 0, 0, 0); __builtin_amdgcn_s_setprio(0); } while (0)
; #define PG8_WAIT_V(n) asm volatile("s_waitcnt vmcnt(" #n ")" ::: "memory")
; #define PG8_WAIT_L(n) asm volatile("s_waitcnt lgkmcnt(" #n ")" ::: "memory")
; #define PG8_BAR __builtin_amdgcn_s_barrier()
; #define PG8_SCHED __builtin_amdgcn_sched_barrier(0)
;     ...
;             const bool last = (t == nt - 2);
;             const char* a1 = PG8_KADV(cA, (size_t)(t + 1) * kstep);
;             const char* a2 = last ? nA : PG8_KADV(cA, (size_t)(t + 2) * kstep); const char* b2 = last ? nB : PG8_KADV(cB, (size_t)(t + 2) * kstep);
;             const char* a3 = PG8_KADV(a2, kstep); const char* b3 = PG8_KADV(b2, kstep);
;             if (last && has_next) S.a_ready(nxt);
;             if constexpr (SP2) {
;             PG8_LDB(B0, 0, 0); PG8_LDB(B1, 0, 1); PG8_SCHED; PG8_LDA(At, 0, 0); PG8_STAGE(PG8_SA(1, 1), a1 + hstep, voffA);
;             PG8_WAIT_V(8); PG8_WAIT_L(0); PG8_BAR; PG8_MMA(0, 0, At, B0); PG8_MMA(0, 1, At, B1); PG8_BAR; PG8_SCHED;
;             PG8_LDA(At, 0, 1); PG8_STAGE(PG8_SB(0, 0), b2, voffB); PG8_STAGE(PG8_SB(0, 1), b2 + hstep, voffB); PG8_STAGE(PG8_SA(0, 0), a2, voffA);
;             PG8_WAIT_V(8); PG8_WAIT_L(0); PG8_BAR; PG8_MMA(1, 0, At, B0); PG8_MMA(1, 1, At, B1); PG8_BAR; PG8_SCHED;
.LBB0_626:
	s_add_u32 s12, s86, 0xfffc0080
	s_addc_u32 s13, s87, -1
	s_add_i32 s96, 0, 0x10000
	s_cmp_eq_u32 s3, 12
	s_cselect_b32 s91, s75, s13
	s_cselect_b32 s90, s81, s12
	v_add_u32_e32 v143, s96, v140
	s_cselect_b32 s89, s79, s2
	s_cselect_b32 s88, vcc_lo, vcc_hi
	s_add_i32 s31, 0, 0x14000
	ds_read_b128 v[144:147], v143
	ds_read_b128 v[148:151], v143 offset:1024
	ds_read_b128 v[152:155], v143 offset:2048
	ds_read_b128 v[156:159], v143 offset:3072
	v_add_u32_e32 v143, s31, v140
	ds_read_b128 v[160:163], v143
	ds_read_b128 v[164:167], v143 offset:1024
	ds_read_b128 v[170:173], v143 offset:2048
	ds_read_b128 v[178:181], v143 offset:3072
	s_add_i32 m0, s97, 0xc000
	ds_read_b128 v[182:185], v142
	ds_read_b128 v[186:189], v142 offset:1024
	ds_read_b128 v[190:193], v142 offset:2048
	ds_read_b128 v[194:197], v142 offset:3072
	ds_read_b128 v[198:201], v142 offset:4096
	ds_read_b128 v[202:205], v142 offset:5120
	ds_read_b128 v[206:209], v142 offset:6144
	ds_read_b128 v[210:213], v142 offset:7168
	global_load_lds_dwordx4 v136, s[86:87]
	s_add_i32 m0, s97, 0xe000
	s_nop 0
	global_load_lds_dwordx4 v138, s[86:87]
	s_waitcnt vmcnt(8)
	s_waitcnt lgkmcnt(0)
	s_barrier
	s_setprio 1
	s_waitcnt lgkmcnt(0)
	v_mfma_f32_16x16x32_bf16 v[124:127], v[144:147], v[182:185], v[124:127]
	v_mfma_f32_16x16x32_bf16 v[124:127], v[148:151], v[186:189], v[124:127]
	v_mfma_f32_16x16x32_bf16 v[116:119], v[144:147], v[190:193], v[116:119]
	v_mfma_f32_16x16x32_bf16 v[116:119], v[148:151], v[194:197], v[116:119]
	v_mfma_f32_16x16x32_bf16 v[100:103], v[144:147], v[198:201], v[100:103]
	v_mfma_f32_16x16x32_bf16 v[100:103], v[148:151], v[202:205], v[100:103]
	v_mfma_f32_16x16x32_bf16 v[84:87], v[144:147], v[206:209], v[84:87]
	v_mfma_f32_16x16x32_bf16 v[84:87], v[148:151], v[210:213], v[84:87]
	v_mfma_f32_16x16x32_bf16 v[120:123], v[152:155], v[182:185], v[120:123]
	v_mfma_f32_16x16x32_bf16 v[120:123], v[156:159], v[186:189], v[120:123]
	v_mfma_f32_16x16x32_bf16 v[112:115], v[152:155], v[190:193], v[112:115]
	v_mfma_f32_16x16x32_bf16 v[112:115], v[156:159], v[194:197], v[112:115]
	v_mfma_f32_16x16x32_bf16 v[96:99], v[152:155], v[198:201], v[96:99]
	v_mfma_f32_16x16x32_bf16 v[96:99], v[156:159], v[202:205], v[96:99]
	v_mfma_f32_16x16x32_bf16 v[80:83], v[152:155], v[206:209], v[80:83]
	v_mfma_f32_16x16x32_bf16 v[80:83], v[156:159], v[210:213], v[80:83]
	s_setprio 0
	s_setprio 1
	v_mfma_f32_16x16x32_bf16 v[108:111], v[160:163], v[182:185], v[108:111]
	v_mfma_f32_16x16x32_bf16 v[108:111], v[164:167], v[186:189], v[108:111]
	v_mfma_f32_16x16x32_bf16 v[92:95], v[160:163], v[190:193], v[92:95]
	v_mfma_f32_16x16x32_bf16 v[92:95], v[164:167], v[194:197], v[92:95]
	v_mfma_f32_16x16x32_bf16 v[76:79], v[160:163], v[198:201], v[76:79]
	v_mfma_f32_16x16x32_bf16 v[76:79], v[164:167], v[202:205], v[76:79]
	v_mfma_f32_16x16x32_bf16 v[68:71], v[160:163], v[206:209], v[68:71]
	v_mfma_f32_16x16x32_bf16 v[68:71], v[164:167], v[210:213], v[68:71]
	v_mfma_f32_16x16x32_bf16 v[104:107], v[170:173], v[182:185], v[104:107]
	v_mfma_f32_16x16x32_bf16 v[104:107], v[178:181], v[186:189], v[104:107]
	v_mfma_f32_16x16x32_bf16 v[88:91], v[170:173], v[190:193], v[88:91]
	v_mfma_f32_16x16x32_bf16 v[88:91], v[178:181], v[194:197], v[88:91]
	v_mfma_f32_16x16x32_bf16 v[72:75], v[170:173], v[198:201], v[72:75]
	v_mfma_f32_16x16x32_bf16 v[72:75], v[178:181], v[202:205], v[72:75]
	v_mfma_f32_16x16x32_bf16 v[64:67], v[170:173], v[206:209], v[64:67]
	v_mfma_f32_16x16x32_bf16 v[64:67], v[178:181], v[210:213], v[64:67]
	s_setprio 0
	s_barrier
	s_add_i32 s12, s96, s93
	s_mov_b32 m0, s12
	ds_read_b128 v[182:185], v142 offset:16384
	ds_read_b128 v[186:189], v142 offset:17408
	ds_read_b128 v[190:193], v142 offset:18432
	ds_read_b128 v[194:197], v142 offset:19456
	ds_read_b128 v[198:201], v142 offset:20480
	ds_read_b128 v[202:205], v142 offset:21504
	ds_read_b128 v[206:209], v142 offset:22528
	ds_read_b128 v[210:213], v142 offset:23552
	global_load_lds_dwordx4 v130, s[88:89]
	s_add_i32 m0, s12, 0x2000
	s_add_u32 s12, s88, 0x40000
	s_addc_u32 s13, s89, 0
	s_add_i32 s31, s31, s93
	global_load_lds_dwordx4 v134, s[88:89]
	s_mov_b32 m0, s31
	s_nop 0
	global_load_lds_dwordx4 v130, s[12:13]
	s_add_i32 m0, s31, 0x2000
	s_nop 0
	global_load_lds_dwordx4 v134, s[12:13]
	s_mov_b32 m0, s97
	s_nop 0
	global_load_lds_dwordx4 v128, s[90:91]
	s_mov_b32 m0, s40
	s_nop 0
	global_load_lds_dwordx4 v132, s[90:91]
	s_waitcnt vmcnt(8)
	s_waitcnt lgkmcnt(0)
	s_barrier
	s_setprio 1
	s_waitcnt lgkmcnt(0)
	v_mfma_f32_16x16x32_bf16 v[60:63], v[144:147], v[182:185], v[60:63]
	v_mfma_f32_16x16x32_bf16 v[60:63], v[148:151], v[186:189], v[60:63]
	v_mfma_f32_16x16x32_bf16 v[52:55], v[144:147], v[190:193], v[52:55]
	v_mfma_f32_16x16x32_bf16 v[52:55], v[148:151], v[194:197], v[52:55]
	v_mfma_f32_16x16x32_bf16 v[36:39], v[144:147], v[198:201], v[36:39]
	v_mfma_f32_16x16x32_bf16 v[36:39], v[148:151], v[202:205], v[36:39]
	v_mfma_f32_16x16x32_bf16 v[20:23], v[144:147], v[206:209], v[20:23]
	v_mfma_f32_16x16x32_bf16 v[20:23], v[148:151], v[210:213], v[20:23]
	v_mfma_f32_16x16x32_bf16 v[56:59], v[152:155], v[182:185], v[56:59]
	v_mfma_f32_16x16x32_bf16 v[56:59], v[156:159], v[186:189], v[56:59]
	v_mfma_f32_16x16x32_bf16 v[48:51], v[152:155], v[190:193], v[48:51]
	v_mfma_f32_16x16x32_bf16 v[48:51], v[156:159], v[194:197], v[48:51]
	v_mfma_f32_16x16x32_bf16 v[32:35], v[152:155], v[198:201], v[32:35]
	v_mfma_f32_16x16x32_bf16 v[32:35], v[156:159], v[202:205], v[32:35]
	v_mfma_f32_16x16x32_bf16 v[16:19], v[152:155], v[206:209], v[16:19]
	v_mfma_f32_16x16x32_bf16 v[16:19], v[156:159], v[210:213], v[16:19]
	s_setprio 0
	s_setprio 1
	v_mfma_f32_16x16x32_bf16 v[44:47], v[160:163], v[182:185], v[44:47]
	v_mfma_f32_16x16x32_bf16 v[44:47], v[164:167], v[186:189], v[44:47]
	v_mfma_f32_16x16x32_bf16 v[28:31], v[160:163], v[190:193], v[28:31]
	v_mfma_f32_16x16x32_bf16 v[28:31], v[164:167], v[194:197], v[28:31]
	v_mfma_f32_16x16x32_bf16 v[12:15], v[160:163], v[198:201], v[12:15]
	v_mfma_f32_16x16x32_bf16 v[12:15], v[164:167], v[202:205], v[12:15]
	v_mfma_f32_16x16x32_bf16 v[4:7], v[160:163], v[206:209], v[4:7]
	v_mfma_f32_16x16x32_bf16 v[4:7], v[164:167], v[210:213], v[4:7]
	v_mfma_f32_16x16x32_bf16 v[40:43], v[170:173], v[182:185], v[40:43]
	v_mfma_f32_16x16x32_bf16 v[40:43], v[178:181], v[186:189], v[40:43]
	v_mfma_f32_16x16x32_bf16 v[24:27], v[170:173], v[190:193], v[24:27]
	v_mfma_f32_16x16x32_bf16 v[24:27], v[178:181], v[194:197], v[24:27]
	v_mfma_f32_16x16x32_bf16 v[8:11], v[170:173], v[198:201], v[8:11]
	v_mfma_f32_16x16x32_bf16 v[8:11], v[178:181], v[202:205], v[8:11]
	v_mfma_f32_16x16x32_bf16 v[0:3], v[170:173], v[206:209], v[0:3]
	v_mfma_f32_16x16x32_bf16 v[0:3], v[178:181], v[210:213], v[0:3]
	s_setprio 0
	s_barrier
; #define PG8_STAGE(bufoff, gbase, voff) do { _Pragma("unroll") for (int _i = 0; _i < 2; ++_i) \
;         __builtin_amdgcn_global_load_lds((const unsigned*)((const char*)(gbase) + (voff)[_i]), (PG8_LAS unsigned*)(lds + (bufoff) + ldsw + _i * 8192), 16, 0, 0); } while (0)
; #define PG8_LDA(dst, b, h) do { _Pragma("unroll") for (int m = 0; m < 4; ++m) _Pragma("unroll") for (int k = 0; k < 2; ++k) dst[m][k] = *(const PG8_LAS bf16x8*)(lds + PG8_SA(b, h) + aoff + m * 2048 + k * 1024); } while (0)
; #define PG8_LDB(dst, b, h) do { _Pragma("unroll") for (int n = 0; n < 2; ++n) _Pragma("unroll") for (int k = 0; k < 2; ++k) dst[n][k] = *(const PG8_LAS bf16x8*)(lds + PG8_SB(b, h) + boff + n * 2048 + k * 1024); } while (0)
; #define PG8_MMA(ai, bj, At, Bt) do { __builtin_amdgcn_s_setprio(1); _Pragma("unroll") for (int m = 0; m < 4; ++m) _Pragma("unroll") for (int n = 0; n < 2; ++n) _Pragma("unroll") for (int k = 0; k < 2; ++k) \
;         acc[ai][bj][m][n] = __builtin_amdgcn_mfma_f32_16x16x32_bf16(Bt[n][k], At[m][k], acc[ai][bj][m][n], 0, 0, 0); __builtin_amdgcn_s_setprio(0); } while (0)
; #define PG8_WAIT_V(n) asm volatile("s_waitcnt vmcnt(" #n ")" ::: "memory")
; #define PG8_WAIT_L(n) asm volatile("s_waitcnt lgkmcnt(" #n ")" ::: "memory")
; #define PG8_BAR __builtin_amdgcn_s_barrier()
; #define PG8_SCHED __builtin_amdgcn_sched_barrier(0)
;     ...
;             PG8_LDB(B0, 1, 0); PG8_LDB(B1, 1, 1); PG8_SCHED; PG8_LDA(At, 1, 0); PG8_STAGE(PG8_SA(0, 1), a2 + hstep, voffA);
;             PG8_WAIT_V(8); PG8_WAIT_L(0); PG8_BAR; PG8_MMA(0, 0, At, B0); PG8_MMA(0, 1, At, B1); PG8_BAR; PG8_SCHED;
;             PG8_LDA(At, 1, 1); PG8_STAGE(PG8_SB(1, 0), b3, voffB); PG8_STAGE(PG8_SB(1, 1), b3 + hstep, voffB); PG8_STAGE(PG8_SA(1, 0), a3, voffA);
;             PG8_WAIT_V(8); PG8_WAIT_L(0); PG8_BAR; PG8_MMA(1, 0, At, B0); PG8_MMA(1, 1, At, B1); PG8_BAR; PG8_SCHED;
	s_add_i32 s31, 0, 0x18000
	v_add_u32_e32 v143, s31, v140
	s_add_i32 s96, 0, 0x1c000
	ds_read_b128 v[144:147], v143
	ds_read_b128 v[148:151], v143 offset:1024
	ds_read_b128 v[152:155], v143 offset:2048
	ds_read_b128 v[156:159], v143 offset:3072
	v_add_u32_e32 v143, s96, v140
	ds_read_b128 v[160:163], v143
	ds_read_b128 v[164:167], v143 offset:1024
	ds_read_b128 v[170:173], v143 offset:2048
	ds_read_b128 v[178:181], v143 offset:3072
	s_add_u32 s12, s90, 0x40000
	s_addc_u32 s13, s91, 0
	s_mov_b32 m0, s33
	ds_read_b128 v[182:185], v142 offset:32768
	ds_read_b128 v[186:189], v142 offset:33792
	ds_read_b128 v[190:193], v142 offset:34816
	ds_read_b128 v[194:197], v142 offset:35840
	ds_read_b128 v[198:201], v142 offset:36864
	ds_read_b128 v[202:205], v142 offset:37888
	ds_read_b128 v[206:209], v142 offset:38912
	ds_read_b128 v[210:213], v142 offset:39936
	global_load_lds_dwordx4 v128, s[12:13]
	s_mov_b32 m0, s30
	s_nop 0
	global_load_lds_dwordx4 v132, s[12:13]
	s_waitcnt vmcnt(8)
	s_waitcnt lgkmcnt(0)
	s_barrier
	s_setprio 1
	s_waitcnt lgkmcnt(0)
	v_mfma_f32_16x16x32_bf16 v[124:127], v[144:147], v[182:185], v[124:127]
	v_mfma_f32_16x16x32_bf16 v[124:127], v[148:151], v[186:189], v[124:127]
	v_mfma_f32_16x16x32_bf16 v[116:119], v[144:147], v[190:193], v[116:119]
	v_mfma_f32_16x16x32_bf16 v[116:119], v[148:151], v[194:197], v[116:119]
	v_mfma_f32_16x16x32_bf16 v[100:103], v[144:147], v[198:201], v[100:103]
	v_mfma_f32_16x16x32_bf16 v[100:103], v[148:151], v[202:205], v[100:103]
	v_mfma_f32_16x16x32_bf16 v[84:87], v[144:147], v[206:209], v[84:87]
	v_mfma_f32_16x16x32_bf16 v[84:87], v[148:151], v[210:213], v[84:87]
	v_mfma_f32_16x16x32_bf16 v[120:123], v[152:155], v[182:185], v[120:123]
	v_mfma_f32_16x16x32_bf16 v[120:123], v[156:159], v[186:189], v[120:123]
	v_mfma_f32_16x16x32_bf16 v[112:115], v[152:155], v[190:193], v[112:115]
	v_mfma_f32_16x16x32_bf16 v[112:115], v[156:159], v[194:197], v[112:115]
	v_mfma_f32_16x16x32_bf16 v[96:99], v[152:155], v[198:201], v[96:99]
	v_mfma_f32_16x16x32_bf16 v[96:99], v[156:159], v[202:205], v[96:99]
	v_mfma_f32_16x16x32_bf16 v[80:83], v[152:155], v[206:209], v[80:83]
	v_mfma_f32_16x16x32_bf16 v[80:83], v[156:159], v[210:213], v[80:83]
	s_setprio 0
	s_setprio 1
	v_mfma_f32_16x16x32_bf16 v[108:111], v[160:163], v[182:185], v[108:111]
	v_mfma_f32_16x16x32_bf16 v[108:111], v[164:167], v[186:189], v[108:111]
	v_mfma_f32_16x16x32_bf16 v[92:95], v[160:163], v[190:193], v[92:95]
	v_mfma_f32_16x16x32_bf16 v[92:95], v[164:167], v[194:197], v[92:95]
	v_mfma_f32_16x16x32_bf16 v[76:79], v[160:163], v[198:201], v[76:79]
	v_mfma_f32_16x16x32_bf16 v[76:79], v[164:167], v[202:205], v[76:79]
	v_mfma_f32_16x16x32_bf16 v[68:71], v[160:163], v[206:209], v[68:71]
	v_mfma_f32_16x16x32_bf16 v[68:71], v[164:167], v[210:213], v[68:71]
	v_mfma_f32_16x16x32_bf16 v[104:107], v[170:173], v[182:185], v[104:107]
	v_mfma_f32_16x16x32_bf16 v[104:107], v[178:181], v[186:189], v[104:107]
	v_mfma_f32_16x16x32_bf16 v[88:91], v[170:173], v[190:193], v[88:91]
	v_mfma_f32_16x16x32_bf16 v[88:91], v[178:181], v[194:197], v[88:91]
	v_mfma_f32_16x16x32_bf16 v[72:75], v[170:173], v[198:201], v[72:75]
	v_mfma_f32_16x16x32_bf16 v[72:75], v[178:181], v[202:205], v[72:75]
	v_mfma_f32_16x16x32_bf16 v[64:67], v[170:173], v[206:209], v[64:67]
	v_mfma_f32_16x16x32_bf16 v[64:67], v[178:181], v[210:213], v[64:67]
	s_setprio 0
	s_barrier
	s_add_i32 s12, s31, s93
	s_mov_b32 m0, s12
	ds_read_b128 v[182:185], v142 offset:49152
	ds_read_b128 v[186:189], v142 offset:50176
	ds_read_b128 v[190:193], v142 offset:51200
	ds_read_b128 v[194:197], v142 offset:52224
	ds_read_b128 v[198:201], v142 offset:53248
	ds_read_b128 v[202:205], v142 offset:54272
	ds_read_b128 v[206:209], v142 offset:55296
	ds_read_b128 v[210:213], v142 offset:56320
	s_add_u32 s100, s88, s16
	s_addc_u32 s101, s89, s17
	global_load_lds_dwordx4 v130, s[100:101]
	s_add_i32 m0, s12, 0x2000
	s_add_u32 s12, s88, 0x40080
	s_addc_u32 s13, s89, 0
	s_add_i32 s31, s96, s93
	global_load_lds_dwordx4 v134, s[100:101]
	s_mov_b32 m0, s31
	s_nop 0
	global_load_lds_dwordx4 v130, s[12:13]
	s_add_i32 m0, s31, 0x2000
	s_nop 0
	global_load_lds_dwordx4 v134, s[12:13]
	s_mov_b32 m0, s14
	s_nop 0
	s_add_u32 s100, s90, s16
	s_addc_u32 s101, s91, s17
	global_load_lds_dwordx4 v128, s[100:101]
	s_mov_b32 m0, s15
	s_nop 0
	global_load_lds_dwordx4 v132, s[100:101]
	s_waitcnt vmcnt(8)
	s_waitcnt lgkmcnt(0)
	s_barrier
	s_setprio 1
	s_waitcnt lgkmcnt(0)
	v_mfma_f32_16x16x32_bf16 v[60:63], v[144:147], v[182:185], v[60:63]
	v_mfma_f32_16x16x32_bf16 v[60:63], v[148:151], v[186:189], v[60:63]
	v_mfma_f32_16x16x32_bf16 v[52:55], v[144:147], v[190:193], v[52:55]
	v_mfma_f32_16x16x32_bf16 v[52:55], v[148:151], v[194:197], v[52:55]
	v_mfma_f32_16x16x32_bf16 v[36:39], v[144:147], v[198:201], v[36:39]
	v_mfma_f32_16x16x32_bf16 v[36:39], v[148:151], v[202:205], v[36:39]
	v_mfma_f32_16x16x32_bf16 v[20:23], v[144:147], v[206:209], v[20:23]
	v_mfma_f32_16x16x32_bf16 v[20:23], v[148:151], v[210:213], v[20:23]
	v_mfma_f32_16x16x32_bf16 v[56:59], v[152:155], v[182:185], v[56:59]
	v_mfma_f32_16x16x32_bf16 v[56:59], v[156:159], v[186:189], v[56:59]
	v_mfma_f32_16x16x32_bf16 v[48:51], v[152:155], v[190:193], v[48:51]
	v_mfma_f32_16x16x32_bf16 v[48:51], v[156:159], v[194:197], v[48:51]
	v_mfma_f32_16x16x32_bf16 v[32:35], v[152:155], v[198:201], v[32:35]
	v_mfma_f32_16x16x32_bf16 v[32:35], v[156:159], v[202:205], v[32:35]
	v_mfma_f32_16x16x32_bf16 v[16:19], v[152:155], v[206:209], v[16:19]
	v_mfma_f32_16x16x32_bf16 v[16:19], v[156:159], v[210:213], v[16:19]
	s_setprio 0
	s_setprio 1
	v_mfma_f32_16x16x32_bf16 v[44:47], v[160:163], v[182:185], v[44:47]
	v_mfma_f32_16x16x32_bf16 v[44:47], v[164:167], v[186:189], v[44:47]
	v_mfma_f32_16x16x32_bf16 v[28:31], v[160:163], v[190:193], v[28:31]
	v_mfma_f32_16x16x32_bf16 v[28:31], v[164:167], v[194:197], v[28:31]
	v_mfma_f32_16x16x32_bf16 v[12:15], v[160:163], v[198:201], v[12:15]
	v_mfma_f32_16x16x32_bf16 v[12:15], v[164:167], v[202:205], v[12:15]
	v_mfma_f32_16x16x32_bf16 v[4:7], v[160:163], v[206:209], v[4:7]
	v_mfma_f32_16x16x32_bf16 v[4:7], v[164:167], v[210:213], v[4:7]
	v_mfma_f32_16x16x32_bf16 v[40:43], v[170:173], v[182:185], v[40:43]
	v_mfma_f32_16x16x32_bf16 v[40:43], v[178:181], v[186:189], v[40:43]
	v_mfma_f32_16x16x32_bf16 v[24:27], v[170:173], v[190:193], v[24:27]
	v_mfma_f32_16x16x32_bf16 v[24:27], v[178:181], v[194:197], v[24:27]
	v_mfma_f32_16x16x32_bf16 v[8:11], v[170:173], v[198:201], v[8:11]
	v_mfma_f32_16x16x32_bf16 v[8:11], v[178:181], v[202:205], v[8:11]
	v_mfma_f32_16x16x32_bf16 v[0:3], v[170:173], v[206:209], v[0:3]
	v_mfma_f32_16x16x32_bf16 v[0:3], v[178:181], v[210:213], v[0:3]
	s_setprio 0
	s_barrier
	s_add_i32 s3, s3, 2
	s_add_u32 s86, s86, 0x100
	s_addc_u32 s87, s87, 0
	s_add_u32 vcc_hi, vcc_hi, 0x100
	s_addc_u32 s2, s2, 0
	s_cmp_gt_u32 s3, 13
	s_cbranch_scc0 .LBB0_626
	s_and_b64 vcc, exec, s[72:73]
	s_cbranch_vccz .LBB0_629
	s_barrier

; #define PG8_STAGE(bufoff, gbase, voff) do { _Pragma("unroll") for (int _i = 0; _i < 2; ++_i) \
;         __builtin_amdgcn_global_load_lds((const unsigned*)((const char*)(gbase) + (voff)[_i]), (PG8_LAS unsigned*)(lds + (bufoff) + ldsw + _i * 8192), 16, 0, 0); } while (0)
; #define PG8_LDA(dst, b, h) do { _Pragma("unroll") for (int m = 0; m < 4; ++m) _Pragma("unroll") for (int k = 0; k < 2; ++k) dst[m][k] = *(const PG8_LAS bf16x8*)(lds + PG8_SA(b, h) + aoff + m * 2048 + k * 1024); } while (0)
; #define PG8_LDB(dst, b, h) do { _Pragma("unroll") for (int n = 0; n < 2; ++n) _Pragma("unroll") for (int k = 0; k < 2; ++k) dst[n][k] = *(const PG8_LAS bf16x8*)(lds + PG8_SB(b, h) + boff + n * 2048 + k * 1024); } while (0)
; #define PG8_MMA(ai, bj, At, Bt) do { __builtin_amdgcn_s_setprio(1); _Pragma("unroll") for (int m = 0; m < 4; ++m) _Pragma("unroll") for (int n = 0; n < 2; ++n) _Pragma("unroll") for (int k = 0; k < 2; ++k) \
;         acc[ai][bj][m][n] = __builtin_amdgcn_mfma_f32_16x16x32_bf16(Bt[n][k], At[m][k], acc[ai][bj][m][n], 0, 0, 0); __builtin_amdgcn_s_setprio(0); } while (0)
; #define PG8_WAIT_V(n) asm volatile("s_waitcnt vmcnt(" #n ")" ::: "memory")
; #define PG8_WAIT_L(n) asm volatile("s_waitcnt lgkmcnt(" #n ")" ::: "memory")
; #define PG8_BAR __builtin_amdgcn_s_barrier()
; #define PG8_SCHED __builtin_amdgcn_sched_barrier(0)
;     ...
;             const bool last = (t == nt - 2);
;             const char* a1 = PG8_KADV(cA, (size_t)(t + 1) * kstep);
;             const char* a2 = last ? nA : PG8_KADV(cA, (size_t)(t + 2) * kstep); const char* b2 = last ? nB : PG8_KADV(cB, (size_t)(t + 2) * kstep);
;             const char* a3 = PG8_KADV(a2, kstep); const char* b3 = PG8_KADV(b2, kstep);
;             if (last && has_next) S.a_ready(nxt);
;             if constexpr (SP2) {
;             PG8_LDB(B0, 0, 0); PG8_LDB(B1, 0, 1); PG8_SCHED; PG8_LDA(At, 0, 0); PG8_STAGE(PG8_SA(1, 1), a1 + hstep, voffA);
;             PG8_WAIT_V(8); PG8_WAIT_L(0); PG8_BAR; PG8_MMA(0, 0, At, B0); PG8_MMA(0, 1, At, B1); PG8_BAR; PG8_SCHED;
;             PG8_LDA(At, 0, 1); PG8_STAGE(PG8_SB(0, 0), b2, voffB); PG8_STAGE(PG8_SB(0, 1), b2 + hstep, voffB); PG8_STAGE(PG8_SA(0, 0), a2, voffA);
;             PG8_WAIT_V(8); PG8_WAIT_L(0); PG8_BAR; PG8_MMA(1, 0, At, B0); PG8_MMA(1, 1, At, B1); PG8_BAR; PG8_SCHED;
.LBB0_856:
	s_add_u32 s12, s82, 0xfff80080
	s_addc_u32 s13, s83, -1
	s_add_i32 s31, 0, 0x10000
	s_cmp_eq_u32 s3, 28
	s_cselect_b32 s87, s15, s13
	s_cselect_b32 s86, s23, s12
	s_cselect_b32 s85, s25, s2
	s_cselect_b32 s84, s28, s30
	s_add_i32 s33, 0, 0x14000
	v_add_u32_e32 v140, s31, v166
	v_add_u32_e32 v164, s33, v166
	ds_read_b128 v[128:131], v140
	ds_read_b128 v[132:135], v140 offset:1024
	ds_read_b128 v[136:139], v140 offset:2048
	ds_read_b128 v[140:143], v140 offset:3072
	ds_read_b128 v[144:147], v164
	ds_read_b128 v[148:151], v164 offset:1024
	ds_read_b128 v[170:173], v164 offset:2048
	ds_read_b128 v[178:181], v164 offset:3072
	s_add_i32 m0, s9, 0xc000
	ds_read_b128 v[184:187], v183
	ds_read_b128 v[188:191], v183 offset:1024
	ds_read_b128 v[192:195], v183 offset:2048
	ds_read_b128 v[196:199], v183 offset:3072
	ds_read_b128 v[200:203], v183 offset:4096
	ds_read_b128 v[204:207], v183 offset:5120
	ds_read_b128 v[208:211], v183 offset:6144
	ds_read_b128 v[212:215], v183 offset:7168
	global_load_lds_dwordx4 v160, s[82:83]
	s_add_i32 m0, s9, 0xe000
	s_nop 0
	global_load_lds_dwordx4 v162, s[82:83]
	s_waitcnt vmcnt(8)
	s_waitcnt lgkmcnt(0)
	s_barrier
	s_setprio 1
	s_waitcnt lgkmcnt(0)
	v_mfma_f32_16x16x32_bf16 v[124:127], v[128:131], v[184:187], v[124:127]
	v_mfma_f32_16x16x32_bf16 v[124:127], v[132:135], v[188:191], v[124:127]
	v_mfma_f32_16x16x32_bf16 v[112:115], v[128:131], v[192:195], v[112:115]
	v_mfma_f32_16x16x32_bf16 v[112:115], v[132:135], v[196:199], v[112:115]
	v_mfma_f32_16x16x32_bf16 v[92:95], v[128:131], v[200:203], v[92:95]
	v_mfma_f32_16x16x32_bf16 v[92:95], v[132:135], v[204:207], v[92:95]
	v_mfma_f32_16x16x32_bf16 v[80:83], v[128:131], v[208:211], v[80:83]
	v_mfma_f32_16x16x32_bf16 v[80:83], v[132:135], v[212:215], v[80:83]
	v_mfma_f32_16x16x32_bf16 v[120:123], v[136:139], v[184:187], v[120:123]
	v_mfma_f32_16x16x32_bf16 v[120:123], v[140:143], v[188:191], v[120:123]
	v_mfma_f32_16x16x32_bf16 v[104:107], v[136:139], v[192:195], v[104:107]
	v_mfma_f32_16x16x32_bf16 v[104:107], v[140:143], v[196:199], v[104:107]
	v_mfma_f32_16x16x32_bf16 v[88:91], v[136:139], v[200:203], v[88:91]
	v_mfma_f32_16x16x32_bf16 v[88:91], v[140:143], v[204:207], v[88:91]
	v_mfma_f32_16x16x32_bf16 v[72:75], v[136:139], v[208:211], v[72:75]
	v_mfma_f32_16x16x32_bf16 v[72:75], v[140:143], v[212:215], v[72:75]
	s_setprio 0
	s_setprio 1
	v_mfma_f32_16x16x32_bf16 v[116:119], v[144:147], v[184:187], v[116:119]
	v_mfma_f32_16x16x32_bf16 v[116:119], v[148:151], v[188:191], v[116:119]
	v_mfma_f32_16x16x32_bf16 v[100:103], v[144:147], v[192:195], v[100:103]
	v_mfma_f32_16x16x32_bf16 v[100:103], v[148:151], v[196:199], v[100:103]
	v_mfma_f32_16x16x32_bf16 v[84:87], v[144:147], v[200:203], v[84:87]
	v_mfma_f32_16x16x32_bf16 v[84:87], v[148:151], v[204:207], v[84:87]
	v_mfma_f32_16x16x32_bf16 v[68:71], v[144:147], v[208:211], v[68:71]
	v_mfma_f32_16x16x32_bf16 v[68:71], v[148:151], v[212:215], v[68:71]
	v_mfma_f32_16x16x32_bf16 v[108:111], v[170:173], v[184:187], v[108:111]
	v_mfma_f32_16x16x32_bf16 v[108:111], v[178:181], v[188:191], v[108:111]
	v_mfma_f32_16x16x32_bf16 v[96:99], v[170:173], v[192:195], v[96:99]
	v_mfma_f32_16x16x32_bf16 v[96:99], v[178:181], v[196:199], v[96:99]
	v_mfma_f32_16x16x32_bf16 v[76:79], v[170:173], v[200:203], v[76:79]
	v_mfma_f32_16x16x32_bf16 v[76:79], v[178:181], v[204:207], v[76:79]
	v_mfma_f32_16x16x32_bf16 v[64:67], v[170:173], v[208:211], v[64:67]
	v_mfma_f32_16x16x32_bf16 v[64:67], v[178:181], v[212:215], v[64:67]
	s_setprio 0
	s_barrier
	s_add_i32 s12, s31, s8
	s_mov_b32 m0, s12
	ds_read_b128 v[184:187], v183 offset:16384
	ds_read_b128 v[188:191], v183 offset:17408
	ds_read_b128 v[192:195], v183 offset:18432
	ds_read_b128 v[196:199], v183 offset:19456
	ds_read_b128 v[200:203], v183 offset:20480
	ds_read_b128 v[204:207], v183 offset:21504
	ds_read_b128 v[208:211], v183 offset:22528
	ds_read_b128 v[212:215], v183 offset:23552
	global_load_lds_dwordx4 v154, s[84:85]
	s_add_i32 m0, s12, 0x2000
	s_add_u32 s12, s84, 0x80000
	s_addc_u32 s13, s85, 0
	s_add_i32 s31, s33, s8
	global_load_lds_dwordx4 v158, s[84:85]
	s_mov_b32 m0, s31
	s_nop 0
	global_load_lds_dwordx4 v154, s[12:13]
	s_add_i32 m0, s31, 0x2000
	s_nop 0
	global_load_lds_dwordx4 v158, s[12:13]
	s_mov_b32 m0, s9
	s_nop 0
	global_load_lds_dwordx4 v152, s[86:87]
	s_mov_b32 m0, s10
	s_nop 0
	global_load_lds_dwordx4 v156, s[86:87]
	s_waitcnt vmcnt(8)
	s_waitcnt lgkmcnt(0)
	s_barrier
	s_setprio 1
	s_waitcnt lgkmcnt(0)
	v_mfma_f32_16x16x32_bf16 v[60:63], v[128:131], v[184:187], v[60:63]
	v_mfma_f32_16x16x32_bf16 v[60:63], v[132:135], v[188:191], v[60:63]
	v_mfma_f32_16x16x32_bf16 v[48:51], v[128:131], v[192:195], v[48:51]
	v_mfma_f32_16x16x32_bf16 v[48:51], v[132:135], v[196:199], v[48:51]
	v_mfma_f32_16x16x32_bf16 v[28:31], v[128:131], v[200:203], v[28:31]
	v_mfma_f32_16x16x32_bf16 v[28:31], v[132:135], v[204:207], v[28:31]
	v_mfma_f32_16x16x32_bf16 v[16:19], v[128:131], v[208:211], v[16:19]
	v_mfma_f32_16x16x32_bf16 v[16:19], v[132:135], v[212:215], v[16:19]
	v_mfma_f32_16x16x32_bf16 v[56:59], v[136:139], v[184:187], v[56:59]
	v_mfma_f32_16x16x32_bf16 v[56:59], v[140:143], v[188:191], v[56:59]
	v_mfma_f32_16x16x32_bf16 v[40:43], v[136:139], v[192:195], v[40:43]
	v_mfma_f32_16x16x32_bf16 v[40:43], v[140:143], v[196:199], v[40:43]
	v_mfma_f32_16x16x32_bf16 v[24:27], v[136:139], v[200:203], v[24:27]
	v_mfma_f32_16x16x32_bf16 v[24:27], v[140:143], v[204:207], v[24:27]
	v_mfma_f32_16x16x32_bf16 v[8:11], v[136:139], v[208:211], v[8:11]
	v_mfma_f32_16x16x32_bf16 v[8:11], v[140:143], v[212:215], v[8:11]
	s_setprio 0
	s_setprio 1
	v_mfma_f32_16x16x32_bf16 v[52:55], v[144:147], v[184:187], v[52:55]
	v_mfma_f32_16x16x32_bf16 v[52:55], v[148:151], v[188:191], v[52:55]
	v_mfma_f32_16x16x32_bf16 v[36:39], v[144:147], v[192:195], v[36:39]
	v_mfma_f32_16x16x32_bf16 v[36:39], v[148:151], v[196:199], v[36:39]
	v_mfma_f32_16x16x32_bf16 v[20:23], v[144:147], v[200:203], v[20:23]
	v_mfma_f32_16x16x32_bf16 v[20:23], v[148:151], v[204:207], v[20:23]
	v_mfma_f32_16x16x32_bf16 v[4:7], v[144:147], v[208:211], v[4:7]
	v_mfma_f32_16x16x32_bf16 v[4:7], v[148:151], v[212:215], v[4:7]
	v_mfma_f32_16x16x32_bf16 v[44:47], v[170:173], v[184:187], v[44:47]
	v_mfma_f32_16x16x32_bf16 v[44:47], v[178:181], v[188:191], v[44:47]
	v_mfma_f32_16x16x32_bf16 v[32:35], v[170:173], v[192:195], v[32:35]
	v_mfma_f32_16x16x32_bf16 v[32:35], v[178:181], v[196:199], v[32:35]
	v_mfma_f32_16x16x32_bf16 v[12:15], v[170:173], v[200:203], v[12:15]
	v_mfma_f32_16x16x32_bf16 v[12:15], v[178:181], v[204:207], v[12:15]
	v_mfma_f32_16x16x32_bf16 v[0:3], v[170:173], v[208:211], v[0:3]
	v_mfma_f32_16x16x32_bf16 v[0:3], v[178:181], v[212:215], v[0:3]
	s_setprio 0
	s_barrier
; #define PG8_STAGE(bufoff, gbase, voff) do { _Pragma("unroll") for (int _i = 0; _i < 2; ++_i) \
;         __builtin_amdgcn_global_load_lds((const unsigned*)((const char*)(gbase) + (voff)[_i]), (PG8_LAS unsigned*)(lds + (bufoff) + ldsw + _i * 8192), 16, 0, 0); } while (0)
; #define PG8_LDA(dst, b, h) do { _Pragma("unroll") for (int m = 0; m < 4; ++m) _Pragma("unroll") for (int k = 0; k < 2; ++k) dst[m][k] = *(const PG8_LAS bf16x8*)(lds + PG8_SA(b, h) + aoff + m * 2048 + k * 1024); } while (0)
; #define PG8_LDB(dst, b, h) do { _Pragma("unroll") for (int n = 0; n < 2; ++n) _Pragma("unroll") for (int k = 0; k < 2; ++k) dst[n][k] = *(const PG8_LAS bf16x8*)(lds + PG8_SB(b, h) + boff + n * 2048 + k * 1024); } while (0)
; #define PG8_MMA(ai, bj, At, Bt) do { __builtin_amdgcn_s_setprio(1); _Pragma("unroll") for (int m = 0; m < 4; ++m) _Pragma("unroll") for (int n = 0; n < 2; ++n) _Pragma("unroll") for (int k = 0; k < 2; ++k) \
;         acc[ai][bj][m][n] = __builtin_amdgcn_mfma_f32_16x16x32_bf16(Bt[n][k], At[m][k], acc[ai][bj][m][n], 0, 0, 0); __builtin_amdgcn_s_setprio(0); } while (0)
; #define PG8_WAIT_V(n) asm volatile("s_waitcnt vmcnt(" #n ")" ::: "memory")
; #define PG8_WAIT_L(n) asm volatile("s_waitcnt lgkmcnt(" #n ")" ::: "memory")
; #define PG8_BAR __builtin_amdgcn_s_barrier()
; #define PG8_SCHED __builtin_amdgcn_sched_barrier(0)
;     ...
;             PG8_LDB(B0, 1, 0); PG8_LDB(B1, 1, 1); PG8_SCHED; PG8_LDA(At, 1, 0); PG8_STAGE(PG8_SA(0, 1), a2 + hstep, voffA);
;             PG8_WAIT_V(8); PG8_WAIT_L(0); PG8_BAR; PG8_MMA(0, 0, At, B0); PG8_MMA(0, 1, At, B1); PG8_BAR; PG8_SCHED;
;             PG8_LDA(At, 1, 1); PG8_STAGE(PG8_SB(1, 0), b3, voffB); PG8_STAGE(PG8_SB(1, 1), b3 + hstep, voffB); PG8_STAGE(PG8_SA(1, 0), a3, voffA);
;             PG8_WAIT_V(8); PG8_WAIT_L(0); PG8_BAR; PG8_MMA(1, 0, At, B0); PG8_MMA(1, 1, At, B1); PG8_BAR; PG8_SCHED;
	s_add_i32 s31, 0, 0x18000
	s_add_i32 s33, 0, 0x1c000
	v_add_u32_e32 v140, s31, v166
	v_add_u32_e32 v168, s33, v166
	ds_read_b128 v[128:131], v140
	ds_read_b128 v[132:135], v140 offset:1024
	ds_read_b128 v[136:139], v140 offset:2048
	ds_read_b128 v[140:143], v140 offset:3072
	ds_read_b128 v[144:147], v168
	ds_read_b128 v[148:151], v168 offset:1024
	ds_read_b128 v[170:173], v168 offset:2048
	ds_read_b128 v[178:181], v168 offset:3072
	s_add_u32 s12, s86, 0x80000
	s_addc_u32 s13, s87, 0
	s_mov_b32 m0, s18
	ds_read_b128 v[184:187], v183 offset:32768
	ds_read_b128 v[188:191], v183 offset:33792
	ds_read_b128 v[192:195], v183 offset:34816
	ds_read_b128 v[196:199], v183 offset:35840
	ds_read_b128 v[200:203], v183 offset:36864
	ds_read_b128 v[204:207], v183 offset:37888
	ds_read_b128 v[208:211], v183 offset:38912
	ds_read_b128 v[212:215], v183 offset:39936
	global_load_lds_dwordx4 v152, s[12:13]
	s_mov_b32 m0, s19
	s_nop 0
	global_load_lds_dwordx4 v156, s[12:13]
	s_waitcnt vmcnt(8)
	s_waitcnt lgkmcnt(0)
	s_barrier
	s_setprio 1
	s_waitcnt lgkmcnt(0)
	v_mfma_f32_16x16x32_bf16 v[124:127], v[128:131], v[184:187], v[124:127]
	v_mfma_f32_16x16x32_bf16 v[124:127], v[132:135], v[188:191], v[124:127]
	v_mfma_f32_16x16x32_bf16 v[112:115], v[128:131], v[192:195], v[112:115]
	v_mfma_f32_16x16x32_bf16 v[112:115], v[132:135], v[196:199], v[112:115]
	v_mfma_f32_16x16x32_bf16 v[92:95], v[128:131], v[200:203], v[92:95]
	v_mfma_f32_16x16x32_bf16 v[92:95], v[132:135], v[204:207], v[92:95]
	v_mfma_f32_16x16x32_bf16 v[80:83], v[128:131], v[208:211], v[80:83]
	v_mfma_f32_16x16x32_bf16 v[80:83], v[132:135], v[212:215], v[80:83]
	v_mfma_f32_16x16x32_bf16 v[120:123], v[136:139], v[184:187], v[120:123]
	v_mfma_f32_16x16x32_bf16 v[120:123], v[140:143], v[188:191], v[120:123]
	v_mfma_f32_16x16x32_bf16 v[104:107], v[136:139], v[192:195], v[104:107]
	v_mfma_f32_16x16x32_bf16 v[104:107], v[140:143], v[196:199], v[104:107]
	v_mfma_f32_16x16x32_bf16 v[88:91], v[136:139], v[200:203], v[88:91]
	v_mfma_f32_16x16x32_bf16 v[88:91], v[140:143], v[204:207], v[88:91]
	v_mfma_f32_16x16x32_bf16 v[72:75], v[136:139], v[208:211], v[72:75]
	v_mfma_f32_16x16x32_bf16 v[72:75], v[140:143], v[212:215], v[72:75]
	s_setprio 0
	s_setprio 1
	v_mfma_f32_16x16x32_bf16 v[116:119], v[144:147], v[184:187], v[116:119]
	v_mfma_f32_16x16x32_bf16 v[116:119], v[148:151], v[188:191], v[116:119]
	v_mfma_f32_16x16x32_bf16 v[100:103], v[144:147], v[192:195], v[100:103]
	v_mfma_f32_16x16x32_bf16 v[100:103], v[148:151], v[196:199], v[100:103]
	v_mfma_f32_16x16x32_bf16 v[84:87], v[144:147], v[200:203], v[84:87]
	v_mfma_f32_16x16x32_bf16 v[84:87], v[148:151], v[204:207], v[84:87]
	v_mfma_f32_16x16x32_bf16 v[68:71], v[144:147], v[208:211], v[68:71]
	v_mfma_f32_16x16x32_bf16 v[68:71], v[148:151], v[212:215], v[68:71]
	v_mfma_f32_16x16x32_bf16 v[108:111], v[170:173], v[184:187], v[108:111]
	v_mfma_f32_16x16x32_bf16 v[108:111], v[178:181], v[188:191], v[108:111]
	v_mfma_f32_16x16x32_bf16 v[96:99], v[170:173], v[192:195], v[96:99]
	v_mfma_f32_16x16x32_bf16 v[96:99], v[178:181], v[196:199], v[96:99]
	v_mfma_f32_16x16x32_bf16 v[76:79], v[170:173], v[200:203], v[76:79]
	v_mfma_f32_16x16x32_bf16 v[76:79], v[178:181], v[204:207], v[76:79]
	v_mfma_f32_16x16x32_bf16 v[64:67], v[170:173], v[208:211], v[64:67]
	v_mfma_f32_16x16x32_bf16 v[64:67], v[178:181], v[212:215], v[64:67]
	s_setprio 0
	s_barrier
	s_add_i32 s12, s31, s8
	s_mov_b32 m0, s12
	ds_read_b128 v[184:187], v183 offset:49152
	ds_read_b128 v[188:191], v183 offset:50176
	ds_read_b128 v[192:195], v183 offset:51200
	ds_read_b128 v[196:199], v183 offset:52224
	ds_read_b128 v[200:203], v183 offset:53248
	ds_read_b128 v[204:207], v183 offset:54272
	ds_read_b128 v[208:211], v183 offset:55296
	ds_read_b128 v[212:215], v183 offset:56320
	s_add_u32 s100, s84, s16
	s_addc_u32 s101, s85, s17
	global_load_lds_dwordx4 v154, s[100:101]
	s_add_i32 m0, s12, 0x2000
	s_add_u32 s12, s84, 0x80080
	s_addc_u32 s13, s85, 0
	s_add_i32 s31, s33, s8
	global_load_lds_dwordx4 v158, s[100:101]
	s_mov_b32 m0, s31
	s_nop 0
	global_load_lds_dwordx4 v154, s[12:13]
	s_add_i32 m0, s31, 0x2000
	s_nop 0
	global_load_lds_dwordx4 v158, s[12:13]
	s_mov_b32 m0, s20
	s_nop 0
	s_add_u32 s100, s86, s16
	s_addc_u32 s101, s87, s17
	global_load_lds_dwordx4 v152, s[100:101]
	s_mov_b32 m0, s21
	s_nop 0
	global_load_lds_dwordx4 v156, s[100:101]
	s_waitcnt vmcnt(8)
	s_waitcnt lgkmcnt(0)
	s_barrier
	s_setprio 1
	s_waitcnt lgkmcnt(0)
	v_mfma_f32_16x16x32_bf16 v[60:63], v[128:131], v[184:187], v[60:63]
	v_mfma_f32_16x16x32_bf16 v[60:63], v[132:135], v[188:191], v[60:63]
	v_mfma_f32_16x16x32_bf16 v[48:51], v[128:131], v[192:195], v[48:51]
	v_mfma_f32_16x16x32_bf16 v[48:51], v[132:135], v[196:199], v[48:51]
	v_mfma_f32_16x16x32_bf16 v[28:31], v[128:131], v[200:203], v[28:31]
	v_mfma_f32_16x16x32_bf16 v[28:31], v[132:135], v[204:207], v[28:31]
	v_mfma_f32_16x16x32_bf16 v[16:19], v[128:131], v[208:211], v[16:19]
	v_mfma_f32_16x16x32_bf16 v[16:19], v[132:135], v[212:215], v[16:19]
	v_mfma_f32_16x16x32_bf16 v[56:59], v[136:139], v[184:187], v[56:59]
	v_mfma_f32_16x16x32_bf16 v[56:59], v[140:143], v[188:191], v[56:59]
	v_mfma_f32_16x16x32_bf16 v[40:43], v[136:139], v[192:195], v[40:43]
	v_mfma_f32_16x16x32_bf16 v[40:43], v[140:143], v[196:199], v[40:43]
	v_mfma_f32_16x16x32_bf16 v[24:27], v[136:139], v[200:203], v[24:27]
	v_mfma_f32_16x16x32_bf16 v[24:27], v[140:143], v[204:207], v[24:27]
	v_mfma_f32_16x16x32_bf16 v[8:11], v[136:139], v[208:211], v[8:11]
	v_mfma_f32_16x16x32_bf16 v[8:11], v[140:143], v[212:215], v[8:11]
	s_setprio 0
	s_setprio 1
	v_mfma_f32_16x16x32_bf16 v[52:55], v[144:147], v[184:187], v[52:55]
	v_mfma_f32_16x16x32_bf16 v[52:55], v[148:151], v[188:191], v[52:55]
	v_mfma_f32_16x16x32_bf16 v[36:39], v[144:147], v[192:195], v[36:39]
	v_mfma_f32_16x16x32_bf16 v[36:39], v[148:151], v[196:199], v[36:39]
	v_mfma_f32_16x16x32_bf16 v[20:23], v[144:147], v[200:203], v[20:23]
	v_mfma_f32_16x16x32_bf16 v[20:23], v[148:151], v[204:207], v[20:23]
	v_mfma_f32_16x16x32_bf16 v[4:7], v[144:147], v[208:211], v[4:7]
	v_mfma_f32_16x16x32_bf16 v[4:7], v[148:151], v[212:215], v[4:7]
	v_mfma_f32_16x16x32_bf16 v[44:47], v[170:173], v[184:187], v[44:47]
	v_mfma_f32_16x16x32_bf16 v[44:47], v[178:181], v[188:191], v[44:47]
	v_mfma_f32_16x16x32_bf16 v[32:35], v[170:173], v[192:195], v[32:35]
	v_mfma_f32_16x16x32_bf16 v[32:35], v[178:181], v[196:199], v[32:35]
	v_mfma_f32_16x16x32_bf16 v[12:15], v[170:173], v[200:203], v[12:15]
	v_mfma_f32_16x16x32_bf16 v[12:15], v[178:181], v[204:207], v[12:15]
	v_mfma_f32_16x16x32_bf16 v[0:3], v[170:173], v[208:211], v[0:3]
	v_mfma_f32_16x16x32_bf16 v[0:3], v[178:181], v[212:215], v[0:3]
	s_setprio 0
	s_barrier
	s_add_i32 s3, s3, 2
	s_add_u32 s82, s82, 0x100
	s_addc_u32 s83, s83, 0
	s_add_u32 s30, s30, 0x100
	s_addc_u32 s2, s2, 0
	s_cmp_gt_u32 s3, 29
	s_cbranch_scc0 .LBB0_856
	s_and_b64 vcc, exec, s[70:71]
	s_cbranch_vccz .LBB0_859
	s_barrier

; #define PG8_STAGE(bufoff, gbase, voff) do { _Pragma("unroll") for (int _i = 0; _i < 2; ++_i) \
;         __builtin_amdgcn_global_load_lds((const unsigned*)((const char*)(gbase) + (voff)[_i]), (PG8_LAS unsigned*)(lds + (bufoff) + ldsw + _i * 8192), 16, 0, 0); } while (0)
; #define PG8_LDA(dst, b, h) do { _Pragma("unroll") for (int m = 0; m < 4; ++m) _Pragma("unroll") for (int k = 0; k < 2; ++k) dst[m][k] = *(const PG8_LAS bf16x8*)(lds + PG8_SA(b, h) + aoff + m * 2048 + k * 1024); } while (0)
; #define PG8_LDB(dst, b, h) do { _Pragma("unroll") for (int n = 0; n < 2; ++n) _Pragma("unroll") for (int k = 0; k < 2; ++k) dst[n][k] = *(const PG8_LAS bf16x8*)(lds + PG8_SB(b, h) + boff + n * 2048 + k * 1024); } while (0)
; #define PG8_MMA(ai, bj, At, Bt) do { __builtin_amdgcn_s_setprio(1); _Pragma("unroll") for (int m = 0; m < 4; ++m) _Pragma("unroll") for (int n = 0; n < 2; ++n) _Pragma("unroll") for (int k = 0; k < 2; ++k) \
;         acc[ai][bj][m][n] = __builtin_amdgcn_mfma_f32_16x16x32_bf16(Bt[n][k], At[m][k], acc[ai][bj][m][n], 0, 0, 0); __builtin_amdgcn_s_setprio(0); } while (0)
; #define PG8_WAIT_V(n) asm volatile("s_waitcnt vmcnt(" #n ")" ::: "memory")
; #define PG8_WAIT_L(n) asm volatile("s_waitcnt lgkmcnt(" #n ")" ::: "memory")
; #define PG8_BAR __builtin_amdgcn_s_barrier()
; #define PG8_SCHED __builtin_amdgcn_sched_barrier(0)
;     ...
;             const bool last = (t == nt - 2);
;             const char* a1 = PG8_KADV(cA, (size_t)(t + 1) * kstep);
;             const char* a2 = last ? nA : PG8_KADV(cA, (size_t)(t + 2) * kstep); const char* b2 = last ? nB : PG8_KADV(cB, (size_t)(t + 2) * kstep);
;             const char* a3 = PG8_KADV(a2, kstep); const char* b3 = PG8_KADV(b2, kstep);
;             if (last && has_next) S.a_ready(nxt);
;             if constexpr (SP2) {
;             PG8_LDB(B0, 0, 0); PG8_LDB(B1, 0, 1); PG8_SCHED; PG8_LDA(At, 0, 0); PG8_STAGE(PG8_SA(1, 1), a1 + hstep, voffA);
;             PG8_WAIT_V(8); PG8_WAIT_L(0); PG8_BAR; PG8_MMA(0, 0, At, B0); PG8_MMA(0, 1, At, B1); PG8_BAR; PG8_SCHED;
;             PG8_LDA(At, 0, 1); PG8_STAGE(PG8_SB(0, 0), b2, voffB); PG8_STAGE(PG8_SB(0, 1), b2 + hstep, voffB); PG8_STAGE(PG8_SA(0, 0), a2, voffA);
;             PG8_WAIT_V(8); PG8_WAIT_L(0); PG8_BAR; PG8_MMA(1, 0, At, B0); PG8_MMA(1, 1, At, B1); PG8_BAR; PG8_SCHED;
.LBB0_983:
	s_add_u32 s12, s70, 0xfff80080
	s_addc_u32 s13, s71, -1
	s_add_i32 s31, 0, 0x10000
	s_cmp_eq_u32 s3, 28
	s_cselect_b32 s75, s15, s13
	s_cselect_b32 s74, s28, s12
	s_cselect_b32 s73, s30, s2
	s_cselect_b32 s72, s33, s40
	s_add_i32 s42, 0, 0x14000
	v_add_u32_e32 v156, s31, v141
	v_add_u32_e32 v168, s42, v141
	ds_read_b128 v[144:147], v156
	ds_read_b128 v[148:151], v156 offset:1024
	ds_read_b128 v[152:155], v156 offset:2048
	ds_read_b128 v[156:159], v156 offset:3072
	ds_read_b128 v[160:163], v168
	ds_read_b128 v[164:167], v168 offset:1024
	ds_read_b128 v[170:173], v168 offset:2048
	ds_read_b128 v[178:181], v168 offset:3072
	s_add_i32 m0, s18, 0xc000
	ds_read_b128 v[182:185], v143
	ds_read_b128 v[186:189], v143 offset:1024
	ds_read_b128 v[190:193], v143 offset:2048
	ds_read_b128 v[194:197], v143 offset:3072
	ds_read_b128 v[198:201], v143 offset:4096
	ds_read_b128 v[202:205], v143 offset:5120
	ds_read_b128 v[206:209], v143 offset:6144
	ds_read_b128 v[210:213], v143 offset:7168
	global_load_lds_dwordx4 v136, s[70:71]
	s_add_i32 m0, s18, 0xe000
	s_nop 0
	global_load_lds_dwordx4 v138, s[70:71]
	s_waitcnt vmcnt(8)
	s_waitcnt lgkmcnt(0)
	s_barrier
	s_setprio 1
	s_waitcnt lgkmcnt(0)
	v_mfma_f32_16x16x32_bf16 v[124:127], v[144:147], v[182:185], v[124:127]
	v_mfma_f32_16x16x32_bf16 v[124:127], v[148:151], v[186:189], v[124:127]
	v_mfma_f32_16x16x32_bf16 v[108:111], v[144:147], v[190:193], v[108:111]
	v_mfma_f32_16x16x32_bf16 v[108:111], v[148:151], v[194:197], v[108:111]
	v_mfma_f32_16x16x32_bf16 v[92:95], v[144:147], v[198:201], v[92:95]
	v_mfma_f32_16x16x32_bf16 v[92:95], v[148:151], v[202:205], v[92:95]
	v_mfma_f32_16x16x32_bf16 v[76:79], v[144:147], v[206:209], v[76:79]
	v_mfma_f32_16x16x32_bf16 v[76:79], v[148:151], v[210:213], v[76:79]
	v_mfma_f32_16x16x32_bf16 v[120:123], v[152:155], v[182:185], v[120:123]
	v_mfma_f32_16x16x32_bf16 v[120:123], v[156:159], v[186:189], v[120:123]
	v_mfma_f32_16x16x32_bf16 v[104:107], v[152:155], v[190:193], v[104:107]
	v_mfma_f32_16x16x32_bf16 v[104:107], v[156:159], v[194:197], v[104:107]
	v_mfma_f32_16x16x32_bf16 v[88:91], v[152:155], v[198:201], v[88:91]
	v_mfma_f32_16x16x32_bf16 v[88:91], v[156:159], v[202:205], v[88:91]
	v_mfma_f32_16x16x32_bf16 v[72:75], v[152:155], v[206:209], v[72:75]
	v_mfma_f32_16x16x32_bf16 v[72:75], v[156:159], v[210:213], v[72:75]
	s_setprio 0
	s_setprio 1
	v_mfma_f32_16x16x32_bf16 v[116:119], v[160:163], v[182:185], v[116:119]
	v_mfma_f32_16x16x32_bf16 v[116:119], v[164:167], v[186:189], v[116:119]
	v_mfma_f32_16x16x32_bf16 v[100:103], v[160:163], v[190:193], v[100:103]
	v_mfma_f32_16x16x32_bf16 v[100:103], v[164:167], v[194:197], v[100:103]
	v_mfma_f32_16x16x32_bf16 v[84:87], v[160:163], v[198:201], v[84:87]
	v_mfma_f32_16x16x32_bf16 v[84:87], v[164:167], v[202:205], v[84:87]
	v_mfma_f32_16x16x32_bf16 v[68:71], v[160:163], v[206:209], v[68:71]
	v_mfma_f32_16x16x32_bf16 v[68:71], v[164:167], v[210:213], v[68:71]
	v_mfma_f32_16x16x32_bf16 v[112:115], v[170:173], v[182:185], v[112:115]
	v_mfma_f32_16x16x32_bf16 v[112:115], v[178:181], v[186:189], v[112:115]
	v_mfma_f32_16x16x32_bf16 v[96:99], v[170:173], v[190:193], v[96:99]
	v_mfma_f32_16x16x32_bf16 v[96:99], v[178:181], v[194:197], v[96:99]
	v_mfma_f32_16x16x32_bf16 v[80:83], v[170:173], v[198:201], v[80:83]
	v_mfma_f32_16x16x32_bf16 v[80:83], v[178:181], v[202:205], v[80:83]
	v_mfma_f32_16x16x32_bf16 v[64:67], v[170:173], v[206:209], v[64:67]
	v_mfma_f32_16x16x32_bf16 v[64:67], v[178:181], v[210:213], v[64:67]
	s_setprio 0
	s_barrier
	s_add_i32 s12, s31, s10
	s_mov_b32 m0, s12
	ds_read_b128 v[182:185], v143 offset:16384
	ds_read_b128 v[186:189], v143 offset:17408
	ds_read_b128 v[190:193], v143 offset:18432
	ds_read_b128 v[194:197], v143 offset:19456
	ds_read_b128 v[198:201], v143 offset:20480
	ds_read_b128 v[202:205], v143 offset:21504
	ds_read_b128 v[206:209], v143 offset:22528
	ds_read_b128 v[210:213], v143 offset:23552
	global_load_lds_dwordx4 v132, s[72:73]
	s_add_i32 m0, s12, 0x2000
	s_add_u32 s12, s72, 0x80000
	s_addc_u32 s13, s73, 0
	s_add_i32 s31, s42, s10
	global_load_lds_dwordx4 v128, s[72:73]
	s_mov_b32 m0, s31
	s_nop 0
	global_load_lds_dwordx4 v132, s[12:13]
	s_add_i32 m0, s31, 0x2000
	s_nop 0
	global_load_lds_dwordx4 v128, s[12:13]
	s_mov_b32 m0, s18
	s_nop 0
	global_load_lds_dwordx4 v134, s[74:75]
	s_mov_b32 m0, s19
	s_nop 0
	global_load_lds_dwordx4 v130, s[74:75]
	s_waitcnt vmcnt(8)
	s_waitcnt lgkmcnt(0)
	s_barrier
	s_setprio 1
	s_waitcnt lgkmcnt(0)
	v_mfma_f32_16x16x32_bf16 v[60:63], v[144:147], v[182:185], v[60:63]
	v_mfma_f32_16x16x32_bf16 v[60:63], v[148:151], v[186:189], v[60:63]
	v_mfma_f32_16x16x32_bf16 v[44:47], v[144:147], v[190:193], v[44:47]
	v_mfma_f32_16x16x32_bf16 v[44:47], v[148:151], v[194:197], v[44:47]
	v_mfma_f32_16x16x32_bf16 v[28:31], v[144:147], v[198:201], v[28:31]
	v_mfma_f32_16x16x32_bf16 v[28:31], v[148:151], v[202:205], v[28:31]
	v_mfma_f32_16x16x32_bf16 v[12:15], v[144:147], v[206:209], v[12:15]
	v_mfma_f32_16x16x32_bf16 v[12:15], v[148:151], v[210:213], v[12:15]
	v_mfma_f32_16x16x32_bf16 v[56:59], v[152:155], v[182:185], v[56:59]
	v_mfma_f32_16x16x32_bf16 v[56:59], v[156:159], v[186:189], v[56:59]
	v_mfma_f32_16x16x32_bf16 v[40:43], v[152:155], v[190:193], v[40:43]
	v_mfma_f32_16x16x32_bf16 v[40:43], v[156:159], v[194:197], v[40:43]
	v_mfma_f32_16x16x32_bf16 v[24:27], v[152:155], v[198:201], v[24:27]
	v_mfma_f32_16x16x32_bf16 v[24:27], v[156:159], v[202:205], v[24:27]
	v_mfma_f32_16x16x32_bf16 v[8:11], v[152:155], v[206:209], v[8:11]
	v_mfma_f32_16x16x32_bf16 v[8:11], v[156:159], v[210:213], v[8:11]
	s_setprio 0
	s_setprio 1
	v_mfma_f32_16x16x32_bf16 v[52:55], v[160:163], v[182:185], v[52:55]
	v_mfma_f32_16x16x32_bf16 v[52:55], v[164:167], v[186:189], v[52:55]
	v_mfma_f32_16x16x32_bf16 v[36:39], v[160:163], v[190:193], v[36:39]
	v_mfma_f32_16x16x32_bf16 v[36:39], v[164:167], v[194:197], v[36:39]
	v_mfma_f32_16x16x32_bf16 v[20:23], v[160:163], v[198:201], v[20:23]
	v_mfma_f32_16x16x32_bf16 v[20:23], v[164:167], v[202:205], v[20:23]
	v_mfma_f32_16x16x32_bf16 v[4:7], v[160:163], v[206:209], v[4:7]
	v_mfma_f32_16x16x32_bf16 v[4:7], v[164:167], v[210:213], v[4:7]
	v_mfma_f32_16x16x32_bf16 v[48:51], v[170:173], v[182:185], v[48:51]
	v_mfma_f32_16x16x32_bf16 v[48:51], v[178:181], v[186:189], v[48:51]
	v_mfma_f32_16x16x32_bf16 v[32:35], v[170:173], v[190:193], v[32:35]
	v_mfma_f32_16x16x32_bf16 v[32:35], v[178:181], v[194:197], v[32:35]
	v_mfma_f32_16x16x32_bf16 v[16:19], v[170:173], v[198:201], v[16:19]
	v_mfma_f32_16x16x32_bf16 v[16:19], v[178:181], v[202:205], v[16:19]
	v_mfma_f32_16x16x32_bf16 v[0:3], v[170:173], v[206:209], v[0:3]
	v_mfma_f32_16x16x32_bf16 v[0:3], v[178:181], v[210:213], v[0:3]
	s_setprio 0
	s_barrier
; #define PG8_STAGE(bufoff, gbase, voff) do { _Pragma("unroll") for (int _i = 0; _i < 2; ++_i) \
;         __builtin_amdgcn_global_load_lds((const unsigned*)((const char*)(gbase) + (voff)[_i]), (PG8_LAS unsigned*)(lds + (bufoff) + ldsw + _i * 8192), 16, 0, 0); } while (0)
; #define PG8_LDA(dst, b, h) do { _Pragma("unroll") for (int m = 0; m < 4; ++m) _Pragma("unroll") for (int k = 0; k < 2; ++k) dst[m][k] = *(const PG8_LAS bf16x8*)(lds + PG8_SA(b, h) + aoff + m * 2048 + k * 1024); } while (0)
; #define PG8_LDB(dst, b, h) do { _Pragma("unroll") for (int n = 0; n < 2; ++n) _Pragma("unroll") for (int k = 0; k < 2; ++k) dst[n][k] = *(const PG8_LAS bf16x8*)(lds + PG8_SB(b, h) + boff + n * 2048 + k * 1024); } while (0)
; #define PG8_MMA(ai, bj, At, Bt) do { __builtin_amdgcn_s_setprio(1); _Pragma("unroll") for (int m = 0; m < 4; ++m) _Pragma("unroll") for (int n = 0; n < 2; ++n) _Pragma("unroll") for (int k = 0; k < 2; ++k) \
;         acc[ai][bj][m][n] = __builtin_amdgcn_mfma_f32_16x16x32_bf16(Bt[n][k], At[m][k], acc[ai][bj][m][n], 0, 0, 0); __builtin_amdgcn_s_setprio(0); } while (0)
; #define PG8_WAIT_V(n) asm volatile("s_waitcnt vmcnt(" #n ")" ::: "memory")
; #define PG8_WAIT_L(n) asm volatile("s_waitcnt lgkmcnt(" #n ")" ::: "memory")
; #define PG8_BAR __builtin_amdgcn_s_barrier()
; #define PG8_SCHED __builtin_amdgcn_sched_barrier(0)
;     ...
;             PG8_LDB(B0, 1, 0); PG8_LDB(B1, 1, 1); PG8_SCHED; PG8_LDA(At, 1, 0); PG8_STAGE(PG8_SA(0, 1), a2 + hstep, voffA);
;             PG8_WAIT_V(8); PG8_WAIT_L(0); PG8_BAR; PG8_MMA(0, 0, At, B0); PG8_MMA(0, 1, At, B1); PG8_BAR; PG8_SCHED;
;             PG8_LDA(At, 1, 1); PG8_STAGE(PG8_SB(1, 0), b3, voffB); PG8_STAGE(PG8_SB(1, 1), b3 + hstep, voffB); PG8_STAGE(PG8_SA(1, 0), a3, voffA);
;             PG8_WAIT_V(8); PG8_WAIT_L(0); PG8_BAR; PG8_MMA(1, 0, At, B0); PG8_MMA(1, 1, At, B1); PG8_BAR; PG8_SCHED;
	s_add_i32 s31, 0, 0x18000
	s_add_i32 s42, 0, 0x1c000
	v_add_u32_e32 v156, s31, v141
	v_add_u32_e32 v168, s42, v141
	ds_read_b128 v[144:147], v156
	ds_read_b128 v[148:151], v156 offset:1024
	ds_read_b128 v[152:155], v156 offset:2048
	ds_read_b128 v[156:159], v156 offset:3072
	ds_read_b128 v[160:163], v168
	ds_read_b128 v[164:167], v168 offset:1024
	ds_read_b128 v[170:173], v168 offset:2048
	ds_read_b128 v[178:181], v168 offset:3072
	s_add_u32 s12, s74, 0x80000
	s_addc_u32 s13, s75, 0
	s_mov_b32 m0, s20
	ds_read_b128 v[182:185], v143 offset:32768
	ds_read_b128 v[186:189], v143 offset:33792
	ds_read_b128 v[190:193], v143 offset:34816
	ds_read_b128 v[194:197], v143 offset:35840
	ds_read_b128 v[198:201], v143 offset:36864
	ds_read_b128 v[202:205], v143 offset:37888
	ds_read_b128 v[206:209], v143 offset:38912
	ds_read_b128 v[210:213], v143 offset:39936
	global_load_lds_dwordx4 v134, s[12:13]
	s_mov_b32 m0, s21
	s_nop 0
	global_load_lds_dwordx4 v130, s[12:13]
	s_waitcnt vmcnt(8)
	s_waitcnt lgkmcnt(0)
	s_barrier
	s_setprio 1
	s_waitcnt lgkmcnt(0)
	v_mfma_f32_16x16x32_bf16 v[124:127], v[144:147], v[182:185], v[124:127]
	v_mfma_f32_16x16x32_bf16 v[124:127], v[148:151], v[186:189], v[124:127]
	v_mfma_f32_16x16x32_bf16 v[108:111], v[144:147], v[190:193], v[108:111]
	v_mfma_f32_16x16x32_bf16 v[108:111], v[148:151], v[194:197], v[108:111]
	v_mfma_f32_16x16x32_bf16 v[92:95], v[144:147], v[198:201], v[92:95]
	v_mfma_f32_16x16x32_bf16 v[92:95], v[148:151], v[202:205], v[92:95]
	v_mfma_f32_16x16x32_bf16 v[76:79], v[144:147], v[206:209], v[76:79]
	v_mfma_f32_16x16x32_bf16 v[76:79], v[148:151], v[210:213], v[76:79]
	v_mfma_f32_16x16x32_bf16 v[120:123], v[152:155], v[182:185], v[120:123]
	v_mfma_f32_16x16x32_bf16 v[120:123], v[156:159], v[186:189], v[120:123]
	v_mfma_f32_16x16x32_bf16 v[104:107], v[152:155], v[190:193], v[104:107]
	v_mfma_f32_16x16x32_bf16 v[104:107], v[156:159], v[194:197], v[104:107]
	v_mfma_f32_16x16x32_bf16 v[88:91], v[152:155], v[198:201], v[88:91]
	v_mfma_f32_16x16x32_bf16 v[88:91], v[156:159], v[202:205], v[88:91]
	v_mfma_f32_16x16x32_bf16 v[72:75], v[152:155], v[206:209], v[72:75]
	v_mfma_f32_16x16x32_bf16 v[72:75], v[156:159], v[210:213], v[72:75]
	s_setprio 0
	s_setprio 1
	v_mfma_f32_16x16x32_bf16 v[116:119], v[160:163], v[182:185], v[116:119]
	v_mfma_f32_16x16x32_bf16 v[116:119], v[164:167], v[186:189], v[116:119]
	v_mfma_f32_16x16x32_bf16 v[100:103], v[160:163], v[190:193], v[100:103]
	v_mfma_f32_16x16x32_bf16 v[100:103], v[164:167], v[194:197], v[100:103]
	v_mfma_f32_16x16x32_bf16 v[84:87], v[160:163], v[198:201], v[84:87]
	v_mfma_f32_16x16x32_bf16 v[84:87], v[164:167], v[202:205], v[84:87]
	v_mfma_f32_16x16x32_bf16 v[68:71], v[160:163], v[206:209], v[68:71]
	v_mfma_f32_16x16x32_bf16 v[68:71], v[164:167], v[210:213], v[68:71]
	v_mfma_f32_16x16x32_bf16 v[112:115], v[170:173], v[182:185], v[112:115]
	v_mfma_f32_16x16x32_bf16 v[112:115], v[178:181], v[186:189], v[112:115]
	v_mfma_f32_16x16x32_bf16 v[96:99], v[170:173], v[190:193], v[96:99]
	v_mfma_f32_16x16x32_bf16 v[96:99], v[178:181], v[194:197], v[96:99]
	v_mfma_f32_16x16x32_bf16 v[80:83], v[170:173], v[198:201], v[80:83]
	v_mfma_f32_16x16x32_bf16 v[80:83], v[178:181], v[202:205], v[80:83]
	v_mfma_f32_16x16x32_bf16 v[64:67], v[170:173], v[206:209], v[64:67]
	v_mfma_f32_16x16x32_bf16 v[64:67], v[178:181], v[210:213], v[64:67]
	s_setprio 0
	s_barrier
	s_add_i32 s12, s31, s10
	s_mov_b32 m0, s12
	ds_read_b128 v[182:185], v143 offset:49152
	ds_read_b128 v[186:189], v143 offset:50176
	ds_read_b128 v[190:193], v143 offset:51200
	ds_read_b128 v[194:197], v143 offset:52224
	ds_read_b128 v[198:201], v143 offset:53248
	ds_read_b128 v[202:205], v143 offset:54272
	ds_read_b128 v[206:209], v143 offset:55296
	ds_read_b128 v[210:213], v143 offset:56320
	s_add_u32 s100, s72, s16
	s_addc_u32 s101, s73, s17
	global_load_lds_dwordx4 v132, s[100:101]
	s_add_i32 m0, s12, 0x2000
	s_add_u32 s12, s72, 0x80080
	s_addc_u32 s13, s73, 0
	s_add_i32 s31, s42, s10
	global_load_lds_dwordx4 v128, s[100:101]
	s_mov_b32 m0, s31
	s_nop 0
	global_load_lds_dwordx4 v132, s[12:13]
	s_add_i32 m0, s31, 0x2000
	s_nop 0
	global_load_lds_dwordx4 v128, s[12:13]
	s_mov_b32 m0, s22
	s_nop 0
	s_add_u32 s100, s74, s16
	s_addc_u32 s101, s75, s17
	global_load_lds_dwordx4 v134, s[100:101]
	s_mov_b32 m0, s23
	s_nop 0
	global_load_lds_dwordx4 v130, s[100:101]
	s_waitcnt vmcnt(8)
	s_waitcnt lgkmcnt(0)
	s_barrier
	s_setprio 1
	s_waitcnt lgkmcnt(0)
	v_mfma_f32_16x16x32_bf16 v[60:63], v[144:147], v[182:185], v[60:63]
	v_mfma_f32_16x16x32_bf16 v[60:63], v[148:151], v[186:189], v[60:63]
	v_mfma_f32_16x16x32_bf16 v[44:47], v[144:147], v[190:193], v[44:47]
	v_mfma_f32_16x16x32_bf16 v[44:47], v[148:151], v[194:197], v[44:47]
	v_mfma_f32_16x16x32_bf16 v[28:31], v[144:147], v[198:201], v[28:31]
	v_mfma_f32_16x16x32_bf16 v[28:31], v[148:151], v[202:205], v[28:31]
	v_mfma_f32_16x16x32_bf16 v[12:15], v[144:147], v[206:209], v[12:15]
	v_mfma_f32_16x16x32_bf16 v[12:15], v[148:151], v[210:213], v[12:15]
	v_mfma_f32_16x16x32_bf16 v[56:59], v[152:155], v[182:185], v[56:59]
	v_mfma_f32_16x16x32_bf16 v[56:59], v[156:159], v[186:189], v[56:59]
	v_mfma_f32_16x16x32_bf16 v[40:43], v[152:155], v[190:193], v[40:43]
	v_mfma_f32_16x16x32_bf16 v[40:43], v[156:159], v[194:197], v[40:43]
	v_mfma_f32_16x16x32_bf16 v[24:27], v[152:155], v[198:201], v[24:27]
	v_mfma_f32_16x16x32_bf16 v[24:27], v[156:159], v[202:205], v[24:27]
	v_mfma_f32_16x16x32_bf16 v[8:11], v[152:155], v[206:209], v[8:11]
	v_mfma_f32_16x16x32_bf16 v[8:11], v[156:159], v[210:213], v[8:11]
	s_setprio 0
	s_setprio 1
	v_mfma_f32_16x16x32_bf16 v[52:55], v[160:163], v[182:185], v[52:55]
	v_mfma_f32_16x16x32_bf16 v[52:55], v[164:167], v[186:189], v[52:55]
	v_mfma_f32_16x16x32_bf16 v[36:39], v[160:163], v[190:193], v[36:39]
	v_mfma_f32_16x16x32_bf16 v[36:39], v[164:167], v[194:197], v[36:39]
	v_mfma_f32_16x16x32_bf16 v[20:23], v[160:163], v[198:201], v[20:23]
	v_mfma_f32_16x16x32_bf16 v[20:23], v[164:167], v[202:205], v[20:23]
	v_mfma_f32_16x16x32_bf16 v[4:7], v[160:163], v[206:209], v[4:7]
	v_mfma_f32_16x16x32_bf16 v[4:7], v[164:167], v[210:213], v[4:7]
	v_mfma_f32_16x16x32_bf16 v[48:51], v[170:173], v[182:185], v[48:51]
	v_mfma_f32_16x16x32_bf16 v[48:51], v[178:181], v[186:189], v[48:51]
	v_mfma_f32_16x16x32_bf16 v[32:35], v[170:173], v[190:193], v[32:35]
	v_mfma_f32_16x16x32_bf16 v[32:35], v[178:181], v[194:197], v[32:35]
	v_mfma_f32_16x16x32_bf16 v[16:19], v[170:173], v[198:201], v[16:19]
	v_mfma_f32_16x16x32_bf16 v[16:19], v[178:181], v[202:205], v[16:19]
	v_mfma_f32_16x16x32_bf16 v[0:3], v[170:173], v[206:209], v[0:3]
	v_mfma_f32_16x16x32_bf16 v[0:3], v[178:181], v[210:213], v[0:3]
	s_setprio 0
	s_barrier
	s_add_i32 s3, s3, 2
	s_add_u32 s70, s70, 0x100
	s_addc_u32 s71, s71, 0
	s_add_u32 s40, s40, 0x100
	s_addc_u32 s2, s2, 0
	s_cmp_gt_u32 s3, 29
	s_cbranch_scc0 .LBB0_983
	s_and_b64 vcc, exec, s[56:57]
	s_cbranch_vccz .LBB0_986
	s_barrier

; #define PG8_STAGE(bufoff, gbase, voff) do { _Pragma("unroll") for (int _i = 0; _i < 2; ++_i) \
;         __builtin_amdgcn_global_load_lds((const unsigned*)((const char*)(gbase) + (voff)[_i]), (PG8_LAS unsigned*)(lds + (bufoff) + ldsw + _i * 8192), 16, 0, 0); } while (0)
; #define PG8_LDA(dst, b, h) do { _Pragma("unroll") for (int m = 0; m < 4; ++m) _Pragma("unroll") for (int k = 0; k < 2; ++k) dst[m][k] = *(const PG8_LAS bf16x8*)(lds + PG8_SA(b, h) + aoff + m * 2048 + k * 1024); } while (0)
; #define PG8_LDB(dst, b, h) do { _Pragma("unroll") for (int n = 0; n < 2; ++n) _Pragma("unroll") for (int k = 0; k < 2; ++k) dst[n][k] = *(const PG8_LAS bf16x8*)(lds + PG8_SB(b, h) + boff + n * 2048 + k * 1024); } while (0)
; #define PG8_MMA(ai, bj, At, Bt) do { __builtin_amdgcn_s_setprio(1); _Pragma("unroll") for (int m = 0; m < 4; ++m) _Pragma("unroll") for (int n = 0; n < 2; ++n) _Pragma("unroll") for (int k = 0; k < 2; ++k) \
;         acc[ai][bj][m][n] = __builtin_amdgcn_mfma_f32_16x16x32_bf16(Bt[n][k], At[m][k], acc[ai][bj][m][n], 0, 0, 0); __builtin_amdgcn_s_setprio(0); } while (0)
; #define PG8_WAIT_V(n) asm volatile("s_waitcnt vmcnt(" #n ")" ::: "memory")
; #define PG8_WAIT_L(n) asm volatile("s_waitcnt lgkmcnt(" #n ")" ::: "memory")
; #define PG8_BAR __builtin_amdgcn_s_barrier()
; #define PG8_SCHED __builtin_amdgcn_sched_barrier(0)
;     ...
;             const bool last = (t == nt - 2);
;             const char* a1 = PG8_KADV(cA, (size_t)(t + 1) * kstep);
;             const char* a2 = last ? nA : PG8_KADV(cA, (size_t)(t + 2) * kstep); const char* b2 = last ? nB : PG8_KADV(cB, (size_t)(t + 2) * kstep);
;             const char* a3 = PG8_KADV(a2, kstep); const char* b3 = PG8_KADV(b2, kstep);
;             if (last && has_next) S.a_ready(nxt);
;             if constexpr (SP2) {
;             PG8_LDB(B0, 0, 0); PG8_LDB(B1, 0, 1); PG8_SCHED; PG8_LDA(At, 0, 0); PG8_STAGE(PG8_SA(1, 1), a1 + hstep, voffA);
;             PG8_WAIT_V(8); PG8_WAIT_L(0); PG8_BAR; PG8_MMA(0, 0, At, B0); PG8_MMA(0, 1, At, B1); PG8_BAR; PG8_SCHED;
;             PG8_LDA(At, 0, 1); PG8_STAGE(PG8_SB(0, 0), b2, voffB); PG8_STAGE(PG8_SB(0, 1), b2 + hstep, voffB); PG8_STAGE(PG8_SA(0, 0), a2, voffA);
;             PG8_WAIT_V(8); PG8_WAIT_L(0); PG8_BAR; PG8_MMA(1, 0, At, B0); PG8_MMA(1, 1, At, B1); PG8_BAR; PG8_SCHED;
.LBB0_1066:
	s_add_u32 s62, s60, 0xffffff00
	s_addc_u32 s63, s61, -1
	s_add_i32 s26, 0, 0x10000
	s_cmpk_eq_i32 s3, 0x54
	s_cselect_b32 s67, s5, s63
	s_cselect_b32 s66, s4, s62
	s_cselect_b32 s65, s59, s25
	s_cselect_b32 s64, s58, s2
	s_add_i32 s28, 0, 0x14000
	v_add_u32_e32 v152, s26, v166
	v_add_u32_e32 v164, s28, v166
	ds_read_b128 v[128:131], v152
	ds_read_b128 v[132:135], v152 offset:1024
	ds_read_b128 v[148:151], v152 offset:2048
	ds_read_b128 v[152:155], v152 offset:3072
	ds_read_b128 v[156:159], v164
	ds_read_b128 v[160:163], v164 offset:1024
	ds_read_b128 v[170:173], v164 offset:2048
	ds_read_b128 v[178:181], v164 offset:3072
	s_add_i32 m0, s13, 0xc000
	ds_read_b128 v[184:187], v183
	ds_read_b128 v[188:191], v183 offset:1024
	ds_read_b128 v[192:195], v183 offset:2048
	ds_read_b128 v[196:199], v183 offset:3072
	ds_read_b128 v[200:203], v183 offset:4096
	ds_read_b128 v[204:207], v183 offset:5120
	ds_read_b128 v[208:211], v183 offset:6144
	ds_read_b128 v[212:215], v183 offset:7168
	global_load_lds_dwordx4 v144, s[60:61]
	s_add_i32 m0, s13, 0xe000
	s_nop 0
	global_load_lds_dwordx4 v146, s[60:61]
	s_waitcnt vmcnt(8)
	s_waitcnt lgkmcnt(0)
	s_barrier
	s_setprio 1
	s_waitcnt lgkmcnt(0)
	v_mfma_f32_16x16x32_bf16 v[124:127], v[128:131], v[184:187], v[124:127]
	v_mfma_f32_16x16x32_bf16 v[124:127], v[132:135], v[188:191], v[124:127]
	v_mfma_f32_16x16x32_bf16 v[112:115], v[128:131], v[192:195], v[112:115]
	v_mfma_f32_16x16x32_bf16 v[112:115], v[132:135], v[196:199], v[112:115]
	v_mfma_f32_16x16x32_bf16 v[92:95], v[128:131], v[200:203], v[92:95]
	v_mfma_f32_16x16x32_bf16 v[92:95], v[132:135], v[204:207], v[92:95]
	v_mfma_f32_16x16x32_bf16 v[80:83], v[128:131], v[208:211], v[80:83]
	v_mfma_f32_16x16x32_bf16 v[80:83], v[132:135], v[212:215], v[80:83]
	v_mfma_f32_16x16x32_bf16 v[120:123], v[148:151], v[184:187], v[120:123]
	v_mfma_f32_16x16x32_bf16 v[120:123], v[152:155], v[188:191], v[120:123]
	v_mfma_f32_16x16x32_bf16 v[104:107], v[148:151], v[192:195], v[104:107]
	v_mfma_f32_16x16x32_bf16 v[104:107], v[152:155], v[196:199], v[104:107]
	v_mfma_f32_16x16x32_bf16 v[88:91], v[148:151], v[200:203], v[88:91]
	v_mfma_f32_16x16x32_bf16 v[88:91], v[152:155], v[204:207], v[88:91]
	v_mfma_f32_16x16x32_bf16 v[72:75], v[148:151], v[208:211], v[72:75]
	v_mfma_f32_16x16x32_bf16 v[72:75], v[152:155], v[212:215], v[72:75]
	s_setprio 0
	s_setprio 1
	v_mfma_f32_16x16x32_bf16 v[116:119], v[156:159], v[184:187], v[116:119]
	v_mfma_f32_16x16x32_bf16 v[116:119], v[160:163], v[188:191], v[116:119]
	v_mfma_f32_16x16x32_bf16 v[100:103], v[156:159], v[192:195], v[100:103]
	v_mfma_f32_16x16x32_bf16 v[100:103], v[160:163], v[196:199], v[100:103]
	v_mfma_f32_16x16x32_bf16 v[84:87], v[156:159], v[200:203], v[84:87]
	v_mfma_f32_16x16x32_bf16 v[84:87], v[160:163], v[204:207], v[84:87]
	v_mfma_f32_16x16x32_bf16 v[68:71], v[156:159], v[208:211], v[68:71]
	v_mfma_f32_16x16x32_bf16 v[68:71], v[160:163], v[212:215], v[68:71]
	v_mfma_f32_16x16x32_bf16 v[108:111], v[170:173], v[184:187], v[108:111]
	v_mfma_f32_16x16x32_bf16 v[108:111], v[178:181], v[188:191], v[108:111]
	v_mfma_f32_16x16x32_bf16 v[96:99], v[170:173], v[192:195], v[96:99]
	v_mfma_f32_16x16x32_bf16 v[96:99], v[178:181], v[196:199], v[96:99]
	v_mfma_f32_16x16x32_bf16 v[76:79], v[170:173], v[200:203], v[76:79]
	v_mfma_f32_16x16x32_bf16 v[76:79], v[178:181], v[204:207], v[76:79]
	v_mfma_f32_16x16x32_bf16 v[64:67], v[170:173], v[208:211], v[64:67]
	v_mfma_f32_16x16x32_bf16 v[64:67], v[178:181], v[212:215], v[64:67]
	s_setprio 0
	s_barrier
	s_add_i32 s26, s26, s10
	s_mov_b32 m0, s26
	ds_read_b128 v[184:187], v183 offset:16384
	ds_read_b128 v[188:191], v183 offset:17408
	ds_read_b128 v[192:195], v183 offset:18432
	ds_read_b128 v[196:199], v183 offset:19456
	ds_read_b128 v[200:203], v183 offset:20480
	ds_read_b128 v[204:207], v183 offset:21504
	ds_read_b128 v[208:211], v183 offset:22528
	ds_read_b128 v[212:215], v183 offset:23552
	global_load_lds_dwordx4 v138, s[64:65]
	s_add_i32 m0, s26, 0x2000
	s_add_u32 s42, s64, 0x160000
	s_addc_u32 s43, s65, 0
	s_add_i32 s26, s28, s10
	global_load_lds_dwordx4 v142, s[64:65]
	s_mov_b32 m0, s26
	s_nop 0
	global_load_lds_dwordx4 v138, s[42:43]
	s_add_i32 m0, s26, 0x2000
	s_nop 0
	global_load_lds_dwordx4 v142, s[42:43]
	s_mov_b32 m0, s13
	s_nop 0
	global_load_lds_dwordx4 v136, s[66:67]
	s_mov_b32 m0, s18
	s_nop 0
	global_load_lds_dwordx4 v140, s[66:67]
	s_waitcnt vmcnt(8)
	s_waitcnt lgkmcnt(0)
	s_barrier
	s_setprio 1
	s_waitcnt lgkmcnt(0)
	v_mfma_f32_16x16x32_bf16 v[60:63], v[128:131], v[184:187], v[60:63]
	v_mfma_f32_16x16x32_bf16 v[60:63], v[132:135], v[188:191], v[60:63]
	v_mfma_f32_16x16x32_bf16 v[48:51], v[128:131], v[192:195], v[48:51]
	v_mfma_f32_16x16x32_bf16 v[48:51], v[132:135], v[196:199], v[48:51]
	v_mfma_f32_16x16x32_bf16 v[28:31], v[128:131], v[200:203], v[28:31]
	v_mfma_f32_16x16x32_bf16 v[28:31], v[132:135], v[204:207], v[28:31]
	v_mfma_f32_16x16x32_bf16 v[16:19], v[128:131], v[208:211], v[16:19]
	v_mfma_f32_16x16x32_bf16 v[16:19], v[132:135], v[212:215], v[16:19]
	v_mfma_f32_16x16x32_bf16 v[56:59], v[148:151], v[184:187], v[56:59]
	v_mfma_f32_16x16x32_bf16 v[56:59], v[152:155], v[188:191], v[56:59]
	v_mfma_f32_16x16x32_bf16 v[40:43], v[148:151], v[192:195], v[40:43]
	v_mfma_f32_16x16x32_bf16 v[40:43], v[152:155], v[196:199], v[40:43]
	v_mfma_f32_16x16x32_bf16 v[24:27], v[148:151], v[200:203], v[24:27]
	v_mfma_f32_16x16x32_bf16 v[24:27], v[152:155], v[204:207], v[24:27]
	v_mfma_f32_16x16x32_bf16 v[8:11], v[148:151], v[208:211], v[8:11]
	v_mfma_f32_16x16x32_bf16 v[8:11], v[152:155], v[212:215], v[8:11]
	s_setprio 0
	s_setprio 1
	v_mfma_f32_16x16x32_bf16 v[52:55], v[156:159], v[184:187], v[52:55]
	v_mfma_f32_16x16x32_bf16 v[52:55], v[160:163], v[188:191], v[52:55]
	v_mfma_f32_16x16x32_bf16 v[36:39], v[156:159], v[192:195], v[36:39]
	v_mfma_f32_16x16x32_bf16 v[36:39], v[160:163], v[196:199], v[36:39]
	v_mfma_f32_16x16x32_bf16 v[20:23], v[156:159], v[200:203], v[20:23]
	v_mfma_f32_16x16x32_bf16 v[20:23], v[160:163], v[204:207], v[20:23]
	v_mfma_f32_16x16x32_bf16 v[4:7], v[156:159], v[208:211], v[4:7]
	v_mfma_f32_16x16x32_bf16 v[4:7], v[160:163], v[212:215], v[4:7]
	v_mfma_f32_16x16x32_bf16 v[44:47], v[170:173], v[184:187], v[44:47]
	v_mfma_f32_16x16x32_bf16 v[44:47], v[178:181], v[188:191], v[44:47]
	v_mfma_f32_16x16x32_bf16 v[32:35], v[170:173], v[192:195], v[32:35]
	v_mfma_f32_16x16x32_bf16 v[32:35], v[178:181], v[196:199], v[32:35]
	v_mfma_f32_16x16x32_bf16 v[12:15], v[170:173], v[200:203], v[12:15]
	v_mfma_f32_16x16x32_bf16 v[12:15], v[178:181], v[204:207], v[12:15]
	v_mfma_f32_16x16x32_bf16 v[0:3], v[170:173], v[208:211], v[0:3]
	v_mfma_f32_16x16x32_bf16 v[0:3], v[178:181], v[212:215], v[0:3]
	s_setprio 0
	s_barrier
; #define PG8_STAGE(bufoff, gbase, voff) do { _Pragma("unroll") for (int _i = 0; _i < 2; ++_i) \
;         __builtin_amdgcn_global_load_lds((const unsigned*)((const char*)(gbase) + (voff)[_i]), (PG8_LAS unsigned*)(lds + (bufoff) + ldsw + _i * 8192), 16, 0, 0); } while (0)
; #define PG8_LDA(dst, b, h) do { _Pragma("unroll") for (int m = 0; m < 4; ++m) _Pragma("unroll") for (int k = 0; k < 2; ++k) dst[m][k] = *(const PG8_LAS bf16x8*)(lds + PG8_SA(b, h) + aoff + m * 2048 + k * 1024); } while (0)
; #define PG8_LDB(dst, b, h) do { _Pragma("unroll") for (int n = 0; n < 2; ++n) _Pragma("unroll") for (int k = 0; k < 2; ++k) dst[n][k] = *(const PG8_LAS bf16x8*)(lds + PG8_SB(b, h) + boff + n * 2048 + k * 1024); } while (0)
; #define PG8_MMA(ai, bj, At, Bt) do { __builtin_amdgcn_s_setprio(1); _Pragma("unroll") for (int m = 0; m < 4; ++m) _Pragma("unroll") for (int n = 0; n < 2; ++n) _Pragma("unroll") for (int k = 0; k < 2; ++k) \
;         acc[ai][bj][m][n] = __builtin_amdgcn_mfma_f32_16x16x32_bf16(Bt[n][k], At[m][k], acc[ai][bj][m][n], 0, 0, 0); __builtin_amdgcn_s_setprio(0); } while (0)
; #define PG8_WAIT_V(n) asm volatile("s_waitcnt vmcnt(" #n ")" ::: "memory")
; #define PG8_WAIT_L(n) asm volatile("s_waitcnt lgkmcnt(" #n ")" ::: "memory")
; #define PG8_BAR __builtin_amdgcn_s_barrier()
; #define PG8_SCHED __builtin_amdgcn_sched_barrier(0)
;     ...
;             PG8_LDB(B0, 1, 0); PG8_LDB(B1, 1, 1); PG8_SCHED; PG8_LDA(At, 1, 0); PG8_STAGE(PG8_SA(0, 1), a2 + hstep, voffA);
;             PG8_WAIT_V(8); PG8_WAIT_L(0); PG8_BAR; PG8_MMA(0, 0, At, B0); PG8_MMA(0, 1, At, B1); PG8_BAR; PG8_SCHED;
;             PG8_LDA(At, 1, 1); PG8_STAGE(PG8_SB(1, 0), b3, voffB); PG8_STAGE(PG8_SB(1, 1), b3 + hstep, voffB); PG8_STAGE(PG8_SA(1, 0), a3, voffA);
;             PG8_WAIT_V(8); PG8_WAIT_L(0); PG8_BAR; PG8_MMA(1, 0, At, B0); PG8_MMA(1, 1, At, B1); PG8_BAR; PG8_SCHED;
	s_add_i32 s26, 0, 0x18000
	s_add_i32 s28, 0, 0x1c000
	v_add_u32_e32 v152, s26, v166
	v_add_u32_e32 v168, s28, v166
	ds_read_b128 v[128:131], v152
	ds_read_b128 v[132:135], v152 offset:1024
	ds_read_b128 v[148:151], v152 offset:2048
	ds_read_b128 v[152:155], v152 offset:3072
	ds_read_b128 v[156:159], v168
	ds_read_b128 v[160:163], v168 offset:1024
	ds_read_b128 v[170:173], v168 offset:2048
	ds_read_b128 v[178:181], v168 offset:3072
	s_add_u32 s42, s66, 0x160000
	s_addc_u32 s43, s67, 0
	s_mov_b32 m0, s19
	ds_read_b128 v[184:187], v183 offset:32768
	ds_read_b128 v[188:191], v183 offset:33792
	ds_read_b128 v[192:195], v183 offset:34816
	ds_read_b128 v[196:199], v183 offset:35840
	ds_read_b128 v[200:203], v183 offset:36864
	ds_read_b128 v[204:207], v183 offset:37888
	ds_read_b128 v[208:211], v183 offset:38912
	ds_read_b128 v[212:215], v183 offset:39936
	global_load_lds_dwordx4 v136, s[42:43]
	s_mov_b32 m0, s20
	s_nop 0
	global_load_lds_dwordx4 v140, s[42:43]
	s_waitcnt vmcnt(8)
	s_waitcnt lgkmcnt(0)
	s_barrier
	s_setprio 1
	s_waitcnt lgkmcnt(0)
	v_mfma_f32_16x16x32_bf16 v[124:127], v[128:131], v[184:187], v[124:127]
	v_mfma_f32_16x16x32_bf16 v[124:127], v[132:135], v[188:191], v[124:127]
	v_mfma_f32_16x16x32_bf16 v[112:115], v[128:131], v[192:195], v[112:115]
	v_mfma_f32_16x16x32_bf16 v[112:115], v[132:135], v[196:199], v[112:115]
	v_mfma_f32_16x16x32_bf16 v[92:95], v[128:131], v[200:203], v[92:95]
	v_mfma_f32_16x16x32_bf16 v[92:95], v[132:135], v[204:207], v[92:95]
	v_mfma_f32_16x16x32_bf16 v[80:83], v[128:131], v[208:211], v[80:83]
	v_mfma_f32_16x16x32_bf16 v[80:83], v[132:135], v[212:215], v[80:83]
	v_mfma_f32_16x16x32_bf16 v[120:123], v[148:151], v[184:187], v[120:123]
	v_mfma_f32_16x16x32_bf16 v[120:123], v[152:155], v[188:191], v[120:123]
	v_mfma_f32_16x16x32_bf16 v[104:107], v[148:151], v[192:195], v[104:107]
	v_mfma_f32_16x16x32_bf16 v[104:107], v[152:155], v[196:199], v[104:107]
	v_mfma_f32_16x16x32_bf16 v[88:91], v[148:151], v[200:203], v[88:91]
	v_mfma_f32_16x16x32_bf16 v[88:91], v[152:155], v[204:207], v[88:91]
	v_mfma_f32_16x16x32_bf16 v[72:75], v[148:151], v[208:211], v[72:75]
	v_mfma_f32_16x16x32_bf16 v[72:75], v[152:155], v[212:215], v[72:75]
	s_setprio 0
	s_setprio 1
	v_mfma_f32_16x16x32_bf16 v[116:119], v[156:159], v[184:187], v[116:119]
	v_mfma_f32_16x16x32_bf16 v[116:119], v[160:163], v[188:191], v[116:119]
	v_mfma_f32_16x16x32_bf16 v[100:103], v[156:159], v[192:195], v[100:103]
	v_mfma_f32_16x16x32_bf16 v[100:103], v[160:163], v[196:199], v[100:103]
	v_mfma_f32_16x16x32_bf16 v[84:87], v[156:159], v[200:203], v[84:87]
	v_mfma_f32_16x16x32_bf16 v[84:87], v[160:163], v[204:207], v[84:87]
	v_mfma_f32_16x16x32_bf16 v[68:71], v[156:159], v[208:211], v[68:71]
	v_mfma_f32_16x16x32_bf16 v[68:71], v[160:163], v[212:215], v[68:71]
	v_mfma_f32_16x16x32_bf16 v[108:111], v[170:173], v[184:187], v[108:111]
	v_mfma_f32_16x16x32_bf16 v[108:111], v[178:181], v[188:191], v[108:111]
	v_mfma_f32_16x16x32_bf16 v[96:99], v[170:173], v[192:195], v[96:99]
	v_mfma_f32_16x16x32_bf16 v[96:99], v[178:181], v[196:199], v[96:99]
	v_mfma_f32_16x16x32_bf16 v[76:79], v[170:173], v[200:203], v[76:79]
	v_mfma_f32_16x16x32_bf16 v[76:79], v[178:181], v[204:207], v[76:79]
	v_mfma_f32_16x16x32_bf16 v[64:67], v[170:173], v[208:211], v[64:67]
	v_mfma_f32_16x16x32_bf16 v[64:67], v[178:181], v[212:215], v[64:67]
	s_setprio 0
	s_barrier
	s_add_i32 s26, s26, s10
	s_mov_b32 m0, s26
	ds_read_b128 v[184:187], v183 offset:49152
	ds_read_b128 v[188:191], v183 offset:50176
	ds_read_b128 v[192:195], v183 offset:51200
	ds_read_b128 v[196:199], v183 offset:52224
	ds_read_b128 v[200:203], v183 offset:53248
	ds_read_b128 v[204:207], v183 offset:54272
	ds_read_b128 v[208:211], v183 offset:55296
	ds_read_b128 v[212:215], v183 offset:56320
	s_add_u32 s100, s64, s38
	s_addc_u32 s101, s65, s39
	global_load_lds_dwordx4 v138, s[100:101]
	s_add_i32 m0, s26, 0x2000
	s_add_u32 s42, s64, 0x15ff80
	s_addc_u32 s43, s65, 0
	s_add_i32 s26, s28, s10
	global_load_lds_dwordx4 v142, s[100:101]
	s_mov_b32 m0, s26
	s_nop 0
	global_load_lds_dwordx4 v138, s[42:43]
	s_add_i32 m0, s26, 0x2000
	s_nop 0
	global_load_lds_dwordx4 v142, s[42:43]
	s_mov_b32 m0, s12
	s_nop 0
	s_add_u32 s100, s66, s38
	s_addc_u32 s101, s67, s39
	global_load_lds_dwordx4 v136, s[100:101]
	s_mov_b32 m0, s21
	s_nop 0
	global_load_lds_dwordx4 v140, s[100:101]
	s_waitcnt vmcnt(8)
	s_waitcnt lgkmcnt(0)
	s_barrier
	s_setprio 1
	s_waitcnt lgkmcnt(0)
	v_mfma_f32_16x16x32_bf16 v[60:63], v[128:131], v[184:187], v[60:63]
	v_mfma_f32_16x16x32_bf16 v[60:63], v[132:135], v[188:191], v[60:63]
	v_mfma_f32_16x16x32_bf16 v[48:51], v[128:131], v[192:195], v[48:51]
	v_mfma_f32_16x16x32_bf16 v[48:51], v[132:135], v[196:199], v[48:51]
	v_mfma_f32_16x16x32_bf16 v[28:31], v[128:131], v[200:203], v[28:31]
	v_mfma_f32_16x16x32_bf16 v[28:31], v[132:135], v[204:207], v[28:31]
	v_mfma_f32_16x16x32_bf16 v[16:19], v[128:131], v[208:211], v[16:19]
	v_mfma_f32_16x16x32_bf16 v[16:19], v[132:135], v[212:215], v[16:19]
	v_mfma_f32_16x16x32_bf16 v[56:59], v[148:151], v[184:187], v[56:59]
	v_mfma_f32_16x16x32_bf16 v[56:59], v[152:155], v[188:191], v[56:59]
	v_mfma_f32_16x16x32_bf16 v[40:43], v[148:151], v[192:195], v[40:43]
	v_mfma_f32_16x16x32_bf16 v[40:43], v[152:155], v[196:199], v[40:43]
	v_mfma_f32_16x16x32_bf16 v[24:27], v[148:151], v[200:203], v[24:27]
	v_mfma_f32_16x16x32_bf16 v[24:27], v[152:155], v[204:207], v[24:27]
	v_mfma_f32_16x16x32_bf16 v[8:11], v[148:151], v[208:211], v[8:11]
	v_mfma_f32_16x16x32_bf16 v[8:11], v[152:155], v[212:215], v[8:11]
	s_setprio 0
	s_setprio 1
	v_mfma_f32_16x16x32_bf16 v[52:55], v[156:159], v[184:187], v[52:55]
	v_mfma_f32_16x16x32_bf16 v[52:55], v[160:163], v[188:191], v[52:55]
	v_mfma_f32_16x16x32_bf16 v[36:39], v[156:159], v[192:195], v[36:39]
	v_mfma_f32_16x16x32_bf16 v[36:39], v[160:163], v[196:199], v[36:39]
	v_mfma_f32_16x16x32_bf16 v[20:23], v[156:159], v[200:203], v[20:23]
	v_mfma_f32_16x16x32_bf16 v[20:23], v[160:163], v[204:207], v[20:23]
	v_mfma_f32_16x16x32_bf16 v[4:7], v[156:159], v[208:211], v[4:7]
	v_mfma_f32_16x16x32_bf16 v[4:7], v[160:163], v[212:215], v[4:7]
	v_mfma_f32_16x16x32_bf16 v[44:47], v[170:173], v[184:187], v[44:47]
	v_mfma_f32_16x16x32_bf16 v[44:47], v[178:181], v[188:191], v[44:47]
	v_mfma_f32_16x16x32_bf16 v[32:35], v[170:173], v[192:195], v[32:35]
	v_mfma_f32_16x16x32_bf16 v[32:35], v[178:181], v[196:199], v[32:35]
	v_mfma_f32_16x16x32_bf16 v[12:15], v[170:173], v[200:203], v[12:15]
	v_mfma_f32_16x16x32_bf16 v[12:15], v[178:181], v[204:207], v[12:15]
	v_mfma_f32_16x16x32_bf16 v[0:3], v[170:173], v[208:211], v[0:3]
	v_mfma_f32_16x16x32_bf16 v[0:3], v[178:181], v[212:215], v[0:3]
	s_setprio 0
	s_barrier
	s_add_i32 s3, s3, 2
	s_add_u32 s2, s2, 0xffffff00
	s_addc_u32 s25, s25, -1
	s_cmpk_gt_u32 s3, 0x55
	s_mov_b64 s[60:61], s[62:63]
	s_cbranch_scc0 .LBB0_1066
	s_and_b64 vcc, exec, s[56:57]
	s_cbranch_vccz .LBB0_1069
	s_barrier
